# stack_i + first two LDS-DMA pieces issued ahead of the ds_read block in SP2-type load segments
# baseline (speedup 1.0000x reference)
;     __host__ __device__ bool next(int i, Unit& u) const { const int t = i / 3, b = i - 3 * t; Unit v; if (!StaticOrder::next(t, v)) return false; u.pm = v.pm; u.pn = 8 * b + v.pn; return true; }
; #define PG8_STAGE(bufoff, gbase, voff) do { const int so_ = (int)(unsigned)((const char*)(gbase) - base_##voff); _Pragma("unroll") for (int _i = 0; _i < 2; ++_i) \
;         __builtin_amdgcn_raw_ptr_buffer_load_lds(rs_##voff, (PG8_LAS unsigned*)(lds + (bufoff) + ldsw + _i * 8192), 16, (int)(voff)[_i], so_, 0, 0); } while (0)
; #define PG8_LDA(dst, b, h) do { _Pragma("unroll") for (int m = 0; m < 4; ++m) _Pragma("unroll") for (int k = 0; k < 2; ++k) dst[m][k] = *(const PG8_LAS bf16x8*)(lds + PG8_SA(b, h) + aoff + m * 2048 + k * 1024); } while (0)
; #define PG8_WAIT_V(n) asm volatile("s_waitcnt vmcnt(" #n ")" ::: "memory")
; #define PG8_WAIT_L(n) asm volatile("s_waitcnt lgkmcnt(" #n ")" ::: "memory")
; #define PG8_BAR __builtin_amdgcn_s_barrier()
; template <class Epi, class Sched, bool ALIGN_EPI = false, bool SP2 = false>
; __device__ __forceinline__ void gemm_phase(PG8_LAS unsigned char* lds, const Gemm g, const Sched& S, const Epi& E, int tid_in) {
;     ...
;         const bool has_next = S.next(ui + 1, nxt);
;         const char* nA = has_next ? (const char*)g.A + (size_t)nxt.pm * tstepA + (g.grp ? (size_t)(nxt.pn / g.grp) * g.agrp : (size_t)0) : cA; const char* nB = has_next ? (const char*)g.Bt + (size_t)nxt.pn * tstepB : cB;
;         for (int t = 0; t < nt; t += 2) {
;             const bool last = (t == nt - 2);
;             const char* a1 = cA + (size_t)(t + 1) * kstep;
;             const char* a2 = last ? nA : cA + (size_t)(t + 2) * kstep; const char* b2 = last ? nB : cB + (size_t)(t + 2) * kstep;
;             const char* a3 = a2 + kstep; const char* b3 = b2 + kstep;
;             if (last && has_next) S.a_ready(nxt);
;             if constexpr (SP2) {
;             PG8_LDB(B0, 0, 0); PG8_LDB(B1, 0, 1); PG8_SCHED; PG8_LDA(At, 0, 0); PG8_STAGE(PG8_SA(1, 1), a1 + hstepA, voffA);
;             PG8_WAIT_V(8); PG8_WAIT_L(0); PG8_BAR; PG8_MMA(0, 0, At, B0); PG8_MMA(0, 1, At, B1); PG8_BAR; PG8_SCHED;
;             PG8_LDA(At, 0, 1); PG8_STAGE(PG8_SB(0, 0), b2, voffB); PG8_STAGE(PG8_SB(0, 1), b2 + hstepB, voffB); PG8_STAGE(PG8_SA(0, 0), a2, voffA);
;             PG8_WAIT_V(8); PG8_WAIT_L(0); PG8_BAR; PG8_MMA(1, 0, At, B0); PG8_MMA(1, 1, At, B1); PG8_BAR; PG8_SCHED;
.LBB0_311:
	s_ashr_i32 s23, s22, 31
	s_lshl_b64 s[10:11], s[22:23], 20
	s_add_u32 s24, s4, s10
	s_addc_u32 s25, s26, s11
	s_and_b64 s[10:11], s[34:35], exec
	s_cselect_b32 s19, s24, s12
	s_ashr_i32 s15, s14, 31
	s_lshl_b64 s[10:11], s[14:15], 20
	s_add_u32 s10, s40, s10
	s_addc_u32 s11, s60, s11
	s_and_b64 s[20:21], s[34:35], exec
	s_cselect_b32 s15, s10, s16
	s_add_u32 s20, s16, 0x100
	v_mov_b32_e32 v2, 0
	s_addc_u32 s21, s17, 0
	s_mov_b32 s23, -2
	v_add_u32_e32 v0, 0x10000, v237
	ds_read_b128 v[130:133], v0
	ds_read_b128 v[134:137], v0 offset:1024
	ds_read_b128 v[138:141], v0 offset:2048
	ds_read_b128 v[142:145], v0 offset:3072
	v_add_u32_e32 v0, 0x14000, v237
	ds_read_b128 v[146:149], v0
	ds_read_b128 v[150:153], v0 offset:1024
	ds_read_b128 v[154:157], v0 offset:2048
	ds_read_b128 v[158:161], v0 offset:3072
	s_add_u32 s16, s12, 0x100
	s_addc_u32 s17, s13, 0
	s_sub_i32 s12, s12, s4
	s_add_i32 s12, s12, 0x80080
	s_sub_i32 s36, s12, 0x80000
	s_cmp_eq_u32 s23, 28
	s_cselect_b32 s13, s19, s16
	s_mov_b32 m0, s69
	ds_read_b128 v[162:165], v238
	ds_read_b128 v[166:169], v238 offset:1024
	ds_read_b128 v[170:173], v238 offset:2048
	ds_read_b128 v[174:177], v238 offset:3072
	ds_read_b128 v[178:181], v238 offset:4096
	ds_read_b128 v[182:185], v238 offset:5120
	ds_read_b128 v[186:189], v238 offset:6144
	ds_read_b128 v[190:193], v238 offset:7168
	s_mov_b32 m0, s78
	s_nop 0
	buffer_load_dwordx4 v211, s[4:7], s36 offen lds
	s_mov_b32 m0, s69
	s_nop 0
	buffer_load_dwordx4 v195, s[4:7], s12 offen lds
	s_mov_b32 m0, s67
	s_nop 0
	buffer_load_dwordx4 v211, s[4:7], s12 offen lds
	s_waitcnt vmcnt(8)
	s_waitcnt lgkmcnt(0)
	s_setprio 1
	s_barrier
	v_mfma_f32_16x16x32_bf16 v[126:129], v[130:133], v[162:165], 0
	v_mfma_f32_16x16x32_bf16 v[122:125], v[138:141], v[162:165], 0
	v_mfma_f32_16x16x32_bf16 v[106:109], v[138:141], v[170:173], 0
	v_mfma_f32_16x16x32_bf16 v[110:113], v[130:133], v[170:173], 0
	v_mfma_f32_16x16x32_bf16 v[94:97], v[130:133], v[178:181], 0
	v_mfma_f32_16x16x32_bf16 v[90:93], v[138:141], v[178:181], 0
	v_mfma_f32_16x16x32_bf16 v[74:77], v[138:141], v[186:189], 0
	v_mfma_f32_16x16x32_bf16 v[78:81], v[130:133], v[186:189], 0
	v_mfma_f32_16x16x32_bf16 v[126:129], v[134:137], v[166:169], v[126:129]
	v_mfma_f32_16x16x32_bf16 v[122:125], v[142:145], v[166:169], v[122:125]
	v_mfma_f32_16x16x32_bf16 v[106:109], v[142:145], v[174:177], v[106:109]
	v_mfma_f32_16x16x32_bf16 v[110:113], v[134:137], v[174:177], v[110:113]
	v_mfma_f32_16x16x32_bf16 v[94:97], v[134:137], v[182:185], v[94:97]
	v_mfma_f32_16x16x32_bf16 v[90:93], v[142:145], v[182:185], v[90:93]
	v_mfma_f32_16x16x32_bf16 v[74:77], v[142:145], v[190:193], v[74:77]
	v_mfma_f32_16x16x32_bf16 v[78:81], v[134:137], v[190:193], v[78:81]
	v_mfma_f32_16x16x32_bf16 v[118:121], v[146:149], v[162:165], 0
	v_mfma_f32_16x16x32_bf16 v[114:117], v[154:157], v[162:165], 0
	v_mfma_f32_16x16x32_bf16 v[98:101], v[154:157], v[170:173], 0
	v_mfma_f32_16x16x32_bf16 v[102:105], v[146:149], v[170:173], 0
	v_mfma_f32_16x16x32_bf16 v[86:89], v[146:149], v[178:181], 0
	v_mfma_f32_16x16x32_bf16 v[82:85], v[154:157], v[178:181], 0
	v_mfma_f32_16x16x32_bf16 v[66:69], v[154:157], v[186:189], 0
	v_mfma_f32_16x16x32_bf16 v[70:73], v[146:149], v[186:189], 0
	v_mfma_f32_16x16x32_bf16 v[118:121], v[150:153], v[166:169], v[118:121]
	v_mfma_f32_16x16x32_bf16 v[114:117], v[158:161], v[166:169], v[114:117]
	v_mfma_f32_16x16x32_bf16 v[98:101], v[158:161], v[174:177], v[98:101]
	v_mfma_f32_16x16x32_bf16 v[102:105], v[150:153], v[174:177], v[102:105]
	v_mfma_f32_16x16x32_bf16 v[86:89], v[150:153], v[182:185], v[86:89]
	v_mfma_f32_16x16x32_bf16 v[82:85], v[158:161], v[182:185], v[82:85]
	v_mfma_f32_16x16x32_bf16 v[66:69], v[158:161], v[190:193], v[66:69]
	v_mfma_f32_16x16x32_bf16 v[70:73], v[150:153], v[190:193], v[70:73]
	s_barrier
	s_setprio 0
	s_cselect_b32 s12, s15, s20
	s_mov_b32 m0, s61
	s_mov_b32 s42, s6
	s_mov_b32 s43, s7
	s_sub_i32 s12, s12, s40
	buffer_load_dwordx4 v207, s[40:43], s12 offen lds
	s_mov_b32 m0, s62
	s_add_i32 s36, s12, 0x80000
	buffer_load_dwordx4 v224, s[40:43], s12 offen lds
	ds_read_b128 v[162:165], v238 offset:16384
	ds_read_b128 v[166:169], v238 offset:17408
	ds_read_b128 v[170:173], v238 offset:18432
	ds_read_b128 v[174:177], v238 offset:19456
	ds_read_b128 v[178:181], v238 offset:20480
	ds_read_b128 v[182:185], v238 offset:21504
	ds_read_b128 v[186:189], v238 offset:22528
	ds_read_b128 v[190:193], v238 offset:23552
	s_mov_b32 m0, s63
	s_sub_i32 s13, s13, s4
	buffer_load_dwordx4 v207, s[40:43], s36 offen lds
	s_mov_b32 m0, s71
	s_nop 0
	buffer_load_dwordx4 v224, s[40:43], s36 offen lds
	s_mov_b32 m0, s53
	s_nop 0
	buffer_load_dwordx4 v195, s[4:7], s13 offen lds
	s_waitcnt vmcnt(7)
	s_waitcnt lgkmcnt(0)
	s_setprio 1
	s_barrier
; #define PG8_STAGE(bufoff, gbase, voff) do { const int so_ = (int)(unsigned)((const char*)(gbase) - base_##voff); _Pragma("unroll") for (int _i = 0; _i < 2; ++_i) \
;         __builtin_amdgcn_raw_ptr_buffer_load_lds(rs_##voff, (PG8_LAS unsigned*)(lds + (bufoff) + ldsw + _i * 8192), 16, (int)(voff)[_i], so_, 0, 0); } while (0)
; #define PG8_LDA(dst, b, h) do { _Pragma("unroll") for (int m = 0; m < 4; ++m) _Pragma("unroll") for (int k = 0; k < 2; ++k) dst[m][k] = *(const PG8_LAS bf16x8*)(lds + PG8_SA(b, h) + aoff + m * 2048 + k * 1024); } while (0)
; #define PG8_LDB(dst, b, h) do { _Pragma("unroll") for (int n = 0; n < 2; ++n) _Pragma("unroll") for (int k = 0; k < 2; ++k) dst[n][k] = *(const PG8_LAS bf16x8*)(lds + PG8_SB(b, h) + boff + n * 2048 + k * 1024); } while (0)
; #define PG8_MMA(ai, bj, At, Bt) do { __builtin_amdgcn_s_setprio(1); _Pragma("unroll") for (int m = 0; m < 4; ++m) _Pragma("unroll") for (int n = 0; n < 2; ++n) _Pragma("unroll") for (int k = 0; k < 2; ++k) \
;         acc[ai][bj][m][n] = __builtin_amdgcn_mfma_f32_16x16x32_bf16(Bt[n][k], At[m][k], acc[ai][bj][m][n], 0, 0, 0); __builtin_amdgcn_s_setprio(0); } while (0)
; #define PG8_WAIT_V(n) asm volatile("s_waitcnt vmcnt(" #n ")" ::: "memory")
; #define PG8_WAIT_L(n) asm volatile("s_waitcnt lgkmcnt(" #n ")" ::: "memory")
; #define PG8_BAR __builtin_amdgcn_s_barrier()
; #define PG8_SCHED __builtin_amdgcn_sched_barrier(0)
; template <class Epi, class Sched, bool ALIGN_EPI = false, bool SP2 = false>
; __device__ __forceinline__ void gemm_phase(PG8_LAS unsigned char* lds, const Gemm g, const Sched& S, const Epi& E, int tid_in) {
;     ...
;             PG8_WAIT_V(8); PG8_WAIT_L(0); PG8_BAR; PG8_MMA(0, 0, At, B0); PG8_MMA(0, 1, At, B1); PG8_BAR; PG8_SCHED;
;             PG8_LDA(At, 0, 1); PG8_STAGE(PG8_SB(0, 0), b2, voffB); PG8_STAGE(PG8_SB(0, 1), b2 + hstepB, voffB); PG8_STAGE(PG8_SA(0, 0), a2, voffA);
;             PG8_WAIT_V(8); PG8_WAIT_L(0); PG8_BAR; PG8_MMA(1, 0, At, B0); PG8_MMA(1, 1, At, B1); PG8_BAR; PG8_SCHED;
;             PG8_LDB(B0, 1, 0); PG8_LDB(B1, 1, 1); PG8_SCHED; PG8_LDA(At, 1, 0); PG8_STAGE(PG8_SA(0, 1), a2 + hstepA, voffA);
;             PG8_WAIT_V(8); PG8_WAIT_L(0); PG8_BAR; PG8_MMA(0, 0, At, B0); PG8_MMA(0, 1, At, B1); PG8_BAR; PG8_SCHED;
	v_mfma_f32_16x16x32_bf16 v[62:65], v[130:133], v[162:165], 0
	v_mfma_f32_16x16x32_bf16 v[58:61], v[138:141], v[162:165], 0
	v_mfma_f32_16x16x32_bf16 v[42:45], v[138:141], v[170:173], 0
	v_mfma_f32_16x16x32_bf16 v[46:49], v[130:133], v[170:173], 0
	v_mfma_f32_16x16x32_bf16 v[30:33], v[130:133], v[178:181], 0
	v_mfma_f32_16x16x32_bf16 v[26:29], v[138:141], v[178:181], 0
	v_mfma_f32_16x16x32_bf16 v[10:13], v[138:141], v[186:189], 0
	v_mfma_f32_16x16x32_bf16 v[14:17], v[130:133], v[186:189], 0
	v_mfma_f32_16x16x32_bf16 v[62:65], v[134:137], v[166:169], v[62:65]
	v_mfma_f32_16x16x32_bf16 v[58:61], v[142:145], v[166:169], v[58:61]
	v_mfma_f32_16x16x32_bf16 v[42:45], v[142:145], v[174:177], v[42:45]
	v_mfma_f32_16x16x32_bf16 v[46:49], v[134:137], v[174:177], v[46:49]
	v_mfma_f32_16x16x32_bf16 v[30:33], v[134:137], v[182:185], v[30:33]
	v_mfma_f32_16x16x32_bf16 v[26:29], v[142:145], v[182:185], v[26:29]
	v_mfma_f32_16x16x32_bf16 v[10:13], v[142:145], v[190:193], v[10:13]
	v_mfma_f32_16x16x32_bf16 v[14:17], v[134:137], v[190:193], v[14:17]
	v_mfma_f32_16x16x32_bf16 v[54:57], v[146:149], v[162:165], 0
	v_mfma_f32_16x16x32_bf16 v[50:53], v[154:157], v[162:165], 0
	v_mfma_f32_16x16x32_bf16 v[34:37], v[154:157], v[170:173], 0
	v_mfma_f32_16x16x32_bf16 v[38:41], v[146:149], v[170:173], 0
	v_mfma_f32_16x16x32_bf16 v[22:25], v[146:149], v[178:181], 0
	v_mfma_f32_16x16x32_bf16 v[18:21], v[154:157], v[178:181], 0
	v_mfma_f32_16x16x32_bf16 v[2:5], v[154:157], v[186:189], 0
	v_mfma_f32_16x16x32_bf16 v[6:9], v[146:149], v[186:189], 0
	v_mfma_f32_16x16x32_bf16 v[54:57], v[150:153], v[166:169], v[54:57]
	v_mfma_f32_16x16x32_bf16 v[50:53], v[158:161], v[166:169], v[50:53]
	v_mfma_f32_16x16x32_bf16 v[34:37], v[158:161], v[174:177], v[34:37]
	v_mfma_f32_16x16x32_bf16 v[38:41], v[150:153], v[174:177], v[38:41]
	v_mfma_f32_16x16x32_bf16 v[22:25], v[150:153], v[182:185], v[22:25]
	v_mfma_f32_16x16x32_bf16 v[18:21], v[158:161], v[182:185], v[18:21]
	v_mfma_f32_16x16x32_bf16 v[2:5], v[158:161], v[190:193], v[2:5]
	v_mfma_f32_16x16x32_bf16 v[6:9], v[150:153], v[190:193], v[6:9]
	s_barrier
	s_setprio 0
	v_add_u32_e32 v0, 0x18000, v237
	ds_read_b128 v[130:133], v0
	ds_read_b128 v[134:137], v0 offset:1024
	ds_read_b128 v[138:141], v0 offset:2048
	ds_read_b128 v[142:145], v0 offset:3072
	v_add_u32_e32 v0, 0x1c000, v237
	ds_read_b128 v[146:149], v0
	ds_read_b128 v[150:153], v0 offset:1024
	ds_read_b128 v[154:157], v0 offset:2048
	ds_read_b128 v[158:161], v0 offset:3072
	s_add_i32 s36, s13, 0x80000
	s_mov_b32 m0, s73
	ds_read_b128 v[162:165], v238 offset:32768
	ds_read_b128 v[166:169], v238 offset:33792
	ds_read_b128 v[170:173], v238 offset:34816
	ds_read_b128 v[174:177], v238 offset:35840
	ds_read_b128 v[178:181], v238 offset:36864
	ds_read_b128 v[182:185], v238 offset:37888
	ds_read_b128 v[186:189], v238 offset:38912
	ds_read_b128 v[190:193], v238 offset:39936
	s_mov_b32 m0, s72
	s_nop 0
	buffer_load_dwordx4 v211, s[4:7], s13 offen lds
	s_mov_b32 m0, s73
	s_nop 0
	buffer_load_dwordx4 v195, s[4:7], s36 offen lds
	s_mov_b32 m0, s74
	s_nop 0
	buffer_load_dwordx4 v211, s[4:7], s36 offen lds
	s_waitcnt vmcnt(8)
	s_waitcnt lgkmcnt(0)
	s_setprio 1
	s_barrier
	v_mfma_f32_16x16x32_bf16 v[126:129], v[130:133], v[162:165], v[126:129]
	v_mfma_f32_16x16x32_bf16 v[122:125], v[138:141], v[162:165], v[122:125]
	v_mfma_f32_16x16x32_bf16 v[106:109], v[138:141], v[170:173], v[106:109]
	v_mfma_f32_16x16x32_bf16 v[110:113], v[130:133], v[170:173], v[110:113]
	v_mfma_f32_16x16x32_bf16 v[94:97], v[130:133], v[178:181], v[94:97]
	v_mfma_f32_16x16x32_bf16 v[90:93], v[138:141], v[178:181], v[90:93]
	v_mfma_f32_16x16x32_bf16 v[74:77], v[138:141], v[186:189], v[74:77]
	v_mfma_f32_16x16x32_bf16 v[78:81], v[130:133], v[186:189], v[78:81]
	v_mfma_f32_16x16x32_bf16 v[126:129], v[134:137], v[166:169], v[126:129]
	v_mfma_f32_16x16x32_bf16 v[122:125], v[142:145], v[166:169], v[122:125]
	v_mfma_f32_16x16x32_bf16 v[106:109], v[142:145], v[174:177], v[106:109]
	v_mfma_f32_16x16x32_bf16 v[110:113], v[134:137], v[174:177], v[110:113]
	v_mfma_f32_16x16x32_bf16 v[94:97], v[134:137], v[182:185], v[94:97]
	v_mfma_f32_16x16x32_bf16 v[90:93], v[142:145], v[182:185], v[90:93]
	v_mfma_f32_16x16x32_bf16 v[74:77], v[142:145], v[190:193], v[74:77]
	v_mfma_f32_16x16x32_bf16 v[78:81], v[134:137], v[190:193], v[78:81]
	v_mfma_f32_16x16x32_bf16 v[118:121], v[146:149], v[162:165], v[118:121]
	v_mfma_f32_16x16x32_bf16 v[114:117], v[154:157], v[162:165], v[114:117]
	v_mfma_f32_16x16x32_bf16 v[98:101], v[154:157], v[170:173], v[98:101]
	v_mfma_f32_16x16x32_bf16 v[102:105], v[146:149], v[170:173], v[102:105]
	v_mfma_f32_16x16x32_bf16 v[86:89], v[146:149], v[178:181], v[86:89]
	v_mfma_f32_16x16x32_bf16 v[82:85], v[154:157], v[178:181], v[82:85]
	v_mfma_f32_16x16x32_bf16 v[66:69], v[154:157], v[186:189], v[66:69]
	v_mfma_f32_16x16x32_bf16 v[70:73], v[146:149], v[186:189], v[70:73]
	v_mfma_f32_16x16x32_bf16 v[118:121], v[150:153], v[166:169], v[118:121]
	v_mfma_f32_16x16x32_bf16 v[114:117], v[158:161], v[166:169], v[114:117]
	v_mfma_f32_16x16x32_bf16 v[98:101], v[158:161], v[174:177], v[98:101]
	v_mfma_f32_16x16x32_bf16 v[102:105], v[150:153], v[174:177], v[102:105]
	v_mfma_f32_16x16x32_bf16 v[86:89], v[150:153], v[182:185], v[86:89]
	v_mfma_f32_16x16x32_bf16 v[82:85], v[158:161], v[182:185], v[82:85]
	v_mfma_f32_16x16x32_bf16 v[66:69], v[158:161], v[190:193], v[66:69]
	v_mfma_f32_16x16x32_bf16 v[70:73], v[150:153], v[190:193], v[70:73]
	s_barrier
; #define PG8_STAGE(bufoff, gbase, voff) do { const int so_ = (int)(unsigned)((const char*)(gbase) - base_##voff); _Pragma("unroll") for (int _i = 0; _i < 2; ++_i) \
;         __builtin_amdgcn_raw_ptr_buffer_load_lds(rs_##voff, (PG8_LAS unsigned*)(lds + (bufoff) + ldsw + _i * 8192), 16, (int)(voff)[_i], so_, 0, 0); } while (0)
; #define PG8_LDA(dst, b, h) do { _Pragma("unroll") for (int m = 0; m < 4; ++m) _Pragma("unroll") for (int k = 0; k < 2; ++k) dst[m][k] = *(const PG8_LAS bf16x8*)(lds + PG8_SA(b, h) + aoff + m * 2048 + k * 1024); } while (0)
; #define PG8_LDB(dst, b, h) do { _Pragma("unroll") for (int n = 0; n < 2; ++n) _Pragma("unroll") for (int k = 0; k < 2; ++k) dst[n][k] = *(const PG8_LAS bf16x8*)(lds + PG8_SB(b, h) + boff + n * 2048 + k * 1024); } while (0)
; #define PG8_MMA(ai, bj, At, Bt) do { __builtin_amdgcn_s_setprio(1); _Pragma("unroll") for (int m = 0; m < 4; ++m) _Pragma("unroll") for (int n = 0; n < 2; ++n) _Pragma("unroll") for (int k = 0; k < 2; ++k) \
;         acc[ai][bj][m][n] = __builtin_amdgcn_mfma_f32_16x16x32_bf16(Bt[n][k], At[m][k], acc[ai][bj][m][n], 0, 0, 0); __builtin_amdgcn_s_setprio(0); } while (0)
; #define PG8_WAIT_V(n) asm volatile("s_waitcnt vmcnt(" #n ")" ::: "memory")
; #define PG8_WAIT_L(n) asm volatile("s_waitcnt lgkmcnt(" #n ")" ::: "memory")
; #define PG8_BAR __builtin_amdgcn_s_barrier()
; #define PG8_SCHED __builtin_amdgcn_sched_barrier(0)
; template <class Epi, class Sched, bool ALIGN_EPI = false, bool SP2 = false>
; __device__ __forceinline__ void gemm_phase(PG8_LAS unsigned char* lds, const Gemm g, const Sched& S, const Epi& E, int tid_in) {
;     ...
;             PG8_LDB(B0, 0, 0); PG8_LDB(B1, 0, 1); PG8_SCHED; PG8_LDA(At, 0, 0); PG8_STAGE(PG8_SA(1, 1), a1 + hstepA, voffA);
;             PG8_WAIT_V(8); PG8_WAIT_L(0); PG8_BAR; PG8_MMA(0, 0, At, B0); PG8_MMA(0, 1, At, B1); PG8_BAR; PG8_SCHED;
;     ...
;             PG8_LDA(At, 1, 1); PG8_STAGE(PG8_SB(1, 0), b3, voffB); PG8_STAGE(PG8_SB(1, 1), b3 + hstepB, voffB); PG8_STAGE(PG8_SA(1, 0), a3, voffA);
;             PG8_WAIT_V(8); PG8_WAIT_L(0); PG8_BAR; PG8_MMA(1, 0, At, B0); PG8_MMA(1, 1, At, B1); PG8_BAR; PG8_SCHED;
	s_setprio 0
	s_mov_b32 m0, s75
	s_add_i32 s36, s12, 0x80
	buffer_load_dwordx4 v207, s[40:43], s36 offen lds
	s_mov_b32 m0, s76
	s_add_i32 s12, s12, 0x80080
	buffer_load_dwordx4 v224, s[40:43], s36 offen lds
	ds_read_b128 v[162:165], v238 offset:49152
	ds_read_b128 v[166:169], v238 offset:50176
	ds_read_b128 v[170:173], v238 offset:51200
	ds_read_b128 v[174:177], v238 offset:52224
	ds_read_b128 v[178:181], v238 offset:53248
	ds_read_b128 v[182:185], v238 offset:54272
	ds_read_b128 v[186:189], v238 offset:55296
	ds_read_b128 v[190:193], v238 offset:56320
	s_mov_b32 m0, s79
	s_addk_i32 s13, 0x80
	buffer_load_dwordx4 v207, s[40:43], s12 offen lds
	s_mov_b32 m0, s68
	s_nop 0
	buffer_load_dwordx4 v224, s[40:43], s12 offen lds
	s_mov_b32 m0, s77
	s_nop 0
	buffer_load_dwordx4 v195, s[4:7], s13 offen lds
	s_waitcnt vmcnt(7)
	s_waitcnt lgkmcnt(0)
	s_setprio 1
	s_barrier
	v_mfma_f32_16x16x32_bf16 v[62:65], v[130:133], v[162:165], v[62:65]
	v_mfma_f32_16x16x32_bf16 v[58:61], v[138:141], v[162:165], v[58:61]
	v_mfma_f32_16x16x32_bf16 v[42:45], v[138:141], v[170:173], v[42:45]
	v_mfma_f32_16x16x32_bf16 v[46:49], v[130:133], v[170:173], v[46:49]
	v_mfma_f32_16x16x32_bf16 v[30:33], v[130:133], v[178:181], v[30:33]
	v_mfma_f32_16x16x32_bf16 v[26:29], v[138:141], v[178:181], v[26:29]
	v_mfma_f32_16x16x32_bf16 v[10:13], v[138:141], v[186:189], v[10:13]
	v_mfma_f32_16x16x32_bf16 v[14:17], v[130:133], v[186:189], v[14:17]
	v_mfma_f32_16x16x32_bf16 v[62:65], v[134:137], v[166:169], v[62:65]
	v_mfma_f32_16x16x32_bf16 v[58:61], v[142:145], v[166:169], v[58:61]
	v_mfma_f32_16x16x32_bf16 v[42:45], v[142:145], v[174:177], v[42:45]
	v_mfma_f32_16x16x32_bf16 v[46:49], v[134:137], v[174:177], v[46:49]
	v_mfma_f32_16x16x32_bf16 v[30:33], v[134:137], v[182:185], v[30:33]
	v_mfma_f32_16x16x32_bf16 v[26:29], v[142:145], v[182:185], v[26:29]
	v_mfma_f32_16x16x32_bf16 v[10:13], v[142:145], v[190:193], v[10:13]
	v_mfma_f32_16x16x32_bf16 v[14:17], v[134:137], v[190:193], v[14:17]
	v_mfma_f32_16x16x32_bf16 v[54:57], v[146:149], v[162:165], v[54:57]
	v_mfma_f32_16x16x32_bf16 v[50:53], v[154:157], v[162:165], v[50:53]
	v_mfma_f32_16x16x32_bf16 v[34:37], v[154:157], v[170:173], v[34:37]
	v_mfma_f32_16x16x32_bf16 v[38:41], v[146:149], v[170:173], v[38:41]
	v_mfma_f32_16x16x32_bf16 v[22:25], v[146:149], v[178:181], v[22:25]
	v_mfma_f32_16x16x32_bf16 v[18:21], v[154:157], v[178:181], v[18:21]
	v_mfma_f32_16x16x32_bf16 v[2:5], v[154:157], v[186:189], v[2:5]
	v_mfma_f32_16x16x32_bf16 v[6:9], v[146:149], v[186:189], v[6:9]
	v_mfma_f32_16x16x32_bf16 v[54:57], v[150:153], v[166:169], v[54:57]
	v_mfma_f32_16x16x32_bf16 v[50:53], v[158:161], v[166:169], v[50:53]
	v_mfma_f32_16x16x32_bf16 v[34:37], v[158:161], v[174:177], v[34:37]
	v_mfma_f32_16x16x32_bf16 v[38:41], v[150:153], v[174:177], v[38:41]
	v_mfma_f32_16x16x32_bf16 v[22:25], v[150:153], v[182:185], v[22:25]
	v_mfma_f32_16x16x32_bf16 v[18:21], v[158:161], v[182:185], v[18:21]
	v_mfma_f32_16x16x32_bf16 v[2:5], v[158:161], v[190:193], v[2:5]
	v_mfma_f32_16x16x32_bf16 v[6:9], v[150:153], v[190:193], v[6:9]
	s_barrier
	s_setprio 0
	s_add_i32 s23, s23, 2
	s_add_u32 s20, s20, 0x100
	s_addc_u32 s21, s21, 0
	s_cmp_gt_u32 s23, 29
	s_mov_b64 s[12:13], s[16:17]
.LBB0_312:
	v_add_u32_e32 v0, 0x10000, v237
	ds_read_b128 v[130:133], v0
	ds_read_b128 v[134:137], v0 offset:1024
	ds_read_b128 v[138:141], v0 offset:2048
	ds_read_b128 v[142:145], v0 offset:3072
	v_add_u32_e32 v0, 0x14000, v237
	ds_read_b128 v[146:149], v0
	ds_read_b128 v[150:153], v0 offset:1024
	ds_read_b128 v[154:157], v0 offset:2048
	ds_read_b128 v[158:161], v0 offset:3072
	s_add_u32 s16, s12, 0x100
	s_addc_u32 s17, s13, 0
	s_sub_i32 s12, s12, s4
	s_add_i32 s12, s12, 0x80080
	s_sub_i32 s36, s12, 0x80000
	s_cmp_eq_u32 s23, 28
	s_cselect_b32 s13, s19, s16
	s_mov_b32 m0, s69
	ds_read_b128 v[162:165], v238
	ds_read_b128 v[166:169], v238 offset:1024
	ds_read_b128 v[170:173], v238 offset:2048
	ds_read_b128 v[174:177], v238 offset:3072
	ds_read_b128 v[178:181], v238 offset:4096
	ds_read_b128 v[182:185], v238 offset:5120
	ds_read_b128 v[186:189], v238 offset:6144
	ds_read_b128 v[190:193], v238 offset:7168
	s_mov_b32 m0, s78
	s_nop 0
	buffer_load_dwordx4 v211, s[4:7], s36 offen lds
	s_mov_b32 m0, s69
	s_nop 0
	buffer_load_dwordx4 v195, s[4:7], s12 offen lds
	s_mov_b32 m0, s67
	s_nop 0
	buffer_load_dwordx4 v211, s[4:7], s12 offen lds
	s_waitcnt vmcnt(8)
	s_waitcnt lgkmcnt(0)
	s_setprio 1
	s_barrier
	v_mfma_f32_16x16x32_bf16 v[126:129], v[130:133], v[162:165], v[126:129]
	v_mfma_f32_16x16x32_bf16 v[122:125], v[138:141], v[162:165], v[122:125]
	v_mfma_f32_16x16x32_bf16 v[106:109], v[138:141], v[170:173], v[106:109]
	v_mfma_f32_16x16x32_bf16 v[110:113], v[130:133], v[170:173], v[110:113]
	v_mfma_f32_16x16x32_bf16 v[94:97], v[130:133], v[178:181], v[94:97]
	v_mfma_f32_16x16x32_bf16 v[90:93], v[138:141], v[178:181], v[90:93]
	v_mfma_f32_16x16x32_bf16 v[74:77], v[138:141], v[186:189], v[74:77]
	v_mfma_f32_16x16x32_bf16 v[78:81], v[130:133], v[186:189], v[78:81]
	v_mfma_f32_16x16x32_bf16 v[126:129], v[134:137], v[166:169], v[126:129]
	v_mfma_f32_16x16x32_bf16 v[122:125], v[142:145], v[166:169], v[122:125]
	v_mfma_f32_16x16x32_bf16 v[106:109], v[142:145], v[174:177], v[106:109]
	v_mfma_f32_16x16x32_bf16 v[110:113], v[134:137], v[174:177], v[110:113]
	v_mfma_f32_16x16x32_bf16 v[94:97], v[134:137], v[182:185], v[94:97]
	v_mfma_f32_16x16x32_bf16 v[90:93], v[142:145], v[182:185], v[90:93]
	v_mfma_f32_16x16x32_bf16 v[74:77], v[142:145], v[190:193], v[74:77]
	v_mfma_f32_16x16x32_bf16 v[78:81], v[134:137], v[190:193], v[78:81]
	v_mfma_f32_16x16x32_bf16 v[118:121], v[146:149], v[162:165], v[118:121]
	v_mfma_f32_16x16x32_bf16 v[114:117], v[154:157], v[162:165], v[114:117]
	v_mfma_f32_16x16x32_bf16 v[98:101], v[154:157], v[170:173], v[98:101]
	v_mfma_f32_16x16x32_bf16 v[102:105], v[146:149], v[170:173], v[102:105]
	v_mfma_f32_16x16x32_bf16 v[86:89], v[146:149], v[178:181], v[86:89]
	v_mfma_f32_16x16x32_bf16 v[82:85], v[154:157], v[178:181], v[82:85]
	v_mfma_f32_16x16x32_bf16 v[66:69], v[154:157], v[186:189], v[66:69]
	v_mfma_f32_16x16x32_bf16 v[70:73], v[146:149], v[186:189], v[70:73]
	v_mfma_f32_16x16x32_bf16 v[118:121], v[150:153], v[166:169], v[118:121]
	v_mfma_f32_16x16x32_bf16 v[114:117], v[158:161], v[166:169], v[114:117]
	v_mfma_f32_16x16x32_bf16 v[98:101], v[158:161], v[174:177], v[98:101]
	v_mfma_f32_16x16x32_bf16 v[102:105], v[150:153], v[174:177], v[102:105]
	v_mfma_f32_16x16x32_bf16 v[86:89], v[150:153], v[182:185], v[86:89]
	v_mfma_f32_16x16x32_bf16 v[82:85], v[158:161], v[182:185], v[82:85]
	v_mfma_f32_16x16x32_bf16 v[66:69], v[158:161], v[190:193], v[66:69]
	v_mfma_f32_16x16x32_bf16 v[70:73], v[150:153], v[190:193], v[70:73]
	s_barrier
; #define PG8_STAGE(bufoff, gbase, voff) do { const int so_ = (int)(unsigned)((const char*)(gbase) - base_##voff); _Pragma("unroll") for (int _i = 0; _i < 2; ++_i) \
;         __builtin_amdgcn_raw_ptr_buffer_load_lds(rs_##voff, (PG8_LAS unsigned*)(lds + (bufoff) + ldsw + _i * 8192), 16, (int)(voff)[_i], so_, 0, 0); } while (0)
; #define PG8_LDA(dst, b, h) do { _Pragma("unroll") for (int m = 0; m < 4; ++m) _Pragma("unroll") for (int k = 0; k < 2; ++k) dst[m][k] = *(const PG8_LAS bf16x8*)(lds + PG8_SA(b, h) + aoff + m * 2048 + k * 1024); } while (0)
; #define PG8_LDB(dst, b, h) do { _Pragma("unroll") for (int n = 0; n < 2; ++n) _Pragma("unroll") for (int k = 0; k < 2; ++k) dst[n][k] = *(const PG8_LAS bf16x8*)(lds + PG8_SB(b, h) + boff + n * 2048 + k * 1024); } while (0)
; #define PG8_MMA(ai, bj, At, Bt) do { __builtin_amdgcn_s_setprio(1); _Pragma("unroll") for (int m = 0; m < 4; ++m) _Pragma("unroll") for (int n = 0; n < 2; ++n) _Pragma("unroll") for (int k = 0; k < 2; ++k) \
;         acc[ai][bj][m][n] = __builtin_amdgcn_mfma_f32_16x16x32_bf16(Bt[n][k], At[m][k], acc[ai][bj][m][n], 0, 0, 0); __builtin_amdgcn_s_setprio(0); } while (0)
; #define PG8_WAIT_V(n) asm volatile("s_waitcnt vmcnt(" #n ")" ::: "memory")
; #define PG8_WAIT_L(n) asm volatile("s_waitcnt lgkmcnt(" #n ")" ::: "memory")
; #define PG8_BAR __builtin_amdgcn_s_barrier()
; #define PG8_SCHED __builtin_amdgcn_sched_barrier(0)
; template <class Epi, class Sched, bool ALIGN_EPI = false, bool SP2 = false>
; __device__ __forceinline__ void gemm_phase(PG8_LAS unsigned char* lds, const Gemm g, const Sched& S, const Epi& E, int tid_in) {
;     ...
;             PG8_LDA(At, 0, 1); PG8_STAGE(PG8_SB(0, 0), b2, voffB); PG8_STAGE(PG8_SB(0, 1), b2 + hstepB, voffB); PG8_STAGE(PG8_SA(0, 0), a2, voffA);
;             PG8_WAIT_V(8); PG8_WAIT_L(0); PG8_BAR; PG8_MMA(1, 0, At, B0); PG8_MMA(1, 1, At, B1); PG8_BAR; PG8_SCHED;
;             PG8_LDB(B0, 1, 0); PG8_LDB(B1, 1, 1); PG8_SCHED; PG8_LDA(At, 1, 0); PG8_STAGE(PG8_SA(0, 1), a2 + hstepA, voffA);
;             PG8_WAIT_V(8); PG8_WAIT_L(0); PG8_BAR; PG8_MMA(0, 0, At, B0); PG8_MMA(0, 1, At, B1); PG8_BAR; PG8_SCHED;
	s_setprio 0
	s_cselect_b32 s12, s15, s20
	s_mov_b32 m0, s61
	s_mov_b32 s42, s6
	s_mov_b32 s43, s7
	s_sub_i32 s12, s12, s40
	buffer_load_dwordx4 v207, s[40:43], s12 offen lds
	s_mov_b32 m0, s62
	s_add_i32 s36, s12, 0x80000
	buffer_load_dwordx4 v224, s[40:43], s12 offen lds
	ds_read_b128 v[162:165], v238 offset:16384
	ds_read_b128 v[166:169], v238 offset:17408
	ds_read_b128 v[170:173], v238 offset:18432
	ds_read_b128 v[174:177], v238 offset:19456
	ds_read_b128 v[178:181], v238 offset:20480
	ds_read_b128 v[182:185], v238 offset:21504
	ds_read_b128 v[186:189], v238 offset:22528
	ds_read_b128 v[190:193], v238 offset:23552
	s_mov_b32 m0, s63
	s_sub_i32 s13, s13, s4
	buffer_load_dwordx4 v207, s[40:43], s36 offen lds
	s_mov_b32 m0, s71
	s_nop 0
	buffer_load_dwordx4 v224, s[40:43], s36 offen lds
	s_mov_b32 m0, s53
	s_nop 0
	buffer_load_dwordx4 v195, s[4:7], s13 offen lds
	s_waitcnt vmcnt(7)
	s_waitcnt lgkmcnt(0)
	s_setprio 1
	s_barrier
	v_mfma_f32_16x16x32_bf16 v[62:65], v[130:133], v[162:165], v[62:65]
	v_mfma_f32_16x16x32_bf16 v[58:61], v[138:141], v[162:165], v[58:61]
	v_mfma_f32_16x16x32_bf16 v[42:45], v[138:141], v[170:173], v[42:45]
	v_mfma_f32_16x16x32_bf16 v[46:49], v[130:133], v[170:173], v[46:49]
	v_mfma_f32_16x16x32_bf16 v[30:33], v[130:133], v[178:181], v[30:33]
	v_mfma_f32_16x16x32_bf16 v[26:29], v[138:141], v[178:181], v[26:29]
	v_mfma_f32_16x16x32_bf16 v[10:13], v[138:141], v[186:189], v[10:13]
	v_mfma_f32_16x16x32_bf16 v[14:17], v[130:133], v[186:189], v[14:17]
	v_mfma_f32_16x16x32_bf16 v[62:65], v[134:137], v[166:169], v[62:65]
	v_mfma_f32_16x16x32_bf16 v[58:61], v[142:145], v[166:169], v[58:61]
	v_mfma_f32_16x16x32_bf16 v[42:45], v[142:145], v[174:177], v[42:45]
	v_mfma_f32_16x16x32_bf16 v[46:49], v[134:137], v[174:177], v[46:49]
	v_mfma_f32_16x16x32_bf16 v[30:33], v[134:137], v[182:185], v[30:33]
	v_mfma_f32_16x16x32_bf16 v[26:29], v[142:145], v[182:185], v[26:29]
	v_mfma_f32_16x16x32_bf16 v[10:13], v[142:145], v[190:193], v[10:13]
	v_mfma_f32_16x16x32_bf16 v[14:17], v[134:137], v[190:193], v[14:17]
	v_mfma_f32_16x16x32_bf16 v[54:57], v[146:149], v[162:165], v[54:57]
	v_mfma_f32_16x16x32_bf16 v[50:53], v[154:157], v[162:165], v[50:53]
	v_mfma_f32_16x16x32_bf16 v[34:37], v[154:157], v[170:173], v[34:37]
	v_mfma_f32_16x16x32_bf16 v[38:41], v[146:149], v[170:173], v[38:41]
	v_mfma_f32_16x16x32_bf16 v[22:25], v[146:149], v[178:181], v[22:25]
	v_mfma_f32_16x16x32_bf16 v[18:21], v[154:157], v[178:181], v[18:21]
	v_mfma_f32_16x16x32_bf16 v[2:5], v[154:157], v[186:189], v[2:5]
	v_mfma_f32_16x16x32_bf16 v[6:9], v[146:149], v[186:189], v[6:9]
	v_mfma_f32_16x16x32_bf16 v[54:57], v[150:153], v[166:169], v[54:57]
	v_mfma_f32_16x16x32_bf16 v[50:53], v[158:161], v[166:169], v[50:53]
	v_mfma_f32_16x16x32_bf16 v[34:37], v[158:161], v[174:177], v[34:37]
	v_mfma_f32_16x16x32_bf16 v[38:41], v[150:153], v[174:177], v[38:41]
	v_mfma_f32_16x16x32_bf16 v[22:25], v[150:153], v[182:185], v[22:25]
	v_mfma_f32_16x16x32_bf16 v[18:21], v[158:161], v[182:185], v[18:21]
	v_mfma_f32_16x16x32_bf16 v[2:5], v[158:161], v[190:193], v[2:5]
	v_mfma_f32_16x16x32_bf16 v[6:9], v[150:153], v[190:193], v[6:9]
	s_barrier
	s_setprio 0
	v_add_u32_e32 v0, 0x18000, v237
	ds_read_b128 v[130:133], v0
	ds_read_b128 v[134:137], v0 offset:1024
	ds_read_b128 v[138:141], v0 offset:2048
	ds_read_b128 v[142:145], v0 offset:3072
	v_add_u32_e32 v0, 0x1c000, v237
	ds_read_b128 v[146:149], v0
	ds_read_b128 v[150:153], v0 offset:1024
	ds_read_b128 v[154:157], v0 offset:2048
	ds_read_b128 v[158:161], v0 offset:3072
	s_add_i32 s36, s13, 0x80000
	s_mov_b32 m0, s73
	ds_read_b128 v[162:165], v238 offset:32768
	ds_read_b128 v[166:169], v238 offset:33792
	ds_read_b128 v[170:173], v238 offset:34816
	ds_read_b128 v[174:177], v238 offset:35840
	ds_read_b128 v[178:181], v238 offset:36864
	ds_read_b128 v[182:185], v238 offset:37888
	ds_read_b128 v[186:189], v238 offset:38912
	ds_read_b128 v[190:193], v238 offset:39936
	s_mov_b32 m0, s72
	s_nop 0
	buffer_load_dwordx4 v211, s[4:7], s13 offen lds
	s_mov_b32 m0, s73
	s_nop 0
	buffer_load_dwordx4 v195, s[4:7], s36 offen lds
	s_mov_b32 m0, s74
	s_nop 0
	buffer_load_dwordx4 v211, s[4:7], s36 offen lds
	s_waitcnt vmcnt(8)
	s_waitcnt lgkmcnt(0)
	s_setprio 1
	s_barrier
; #define PG8_STAGE(bufoff, gbase, voff) do { const int so_ = (int)(unsigned)((const char*)(gbase) - base_##voff); _Pragma("unroll") for (int _i = 0; _i < 2; ++_i) \
;         __builtin_amdgcn_raw_ptr_buffer_load_lds(rs_##voff, (PG8_LAS unsigned*)(lds + (bufoff) + ldsw + _i * 8192), 16, (int)(voff)[_i], so_, 0, 0); } while (0)
; #define PG8_LDA(dst, b, h) do { _Pragma("unroll") for (int m = 0; m < 4; ++m) _Pragma("unroll") for (int k = 0; k < 2; ++k) dst[m][k] = *(const PG8_LAS bf16x8*)(lds + PG8_SA(b, h) + aoff + m * 2048 + k * 1024); } while (0)
; #define PG8_MMA(ai, bj, At, Bt) do { __builtin_amdgcn_s_setprio(1); _Pragma("unroll") for (int m = 0; m < 4; ++m) _Pragma("unroll") for (int n = 0; n < 2; ++n) _Pragma("unroll") for (int k = 0; k < 2; ++k) \
;         acc[ai][bj][m][n] = __builtin_amdgcn_mfma_f32_16x16x32_bf16(Bt[n][k], At[m][k], acc[ai][bj][m][n], 0, 0, 0); __builtin_amdgcn_s_setprio(0); } while (0)
; #define PG8_WAIT_V(n) asm volatile("s_waitcnt vmcnt(" #n ")" ::: "memory")
; #define PG8_WAIT_L(n) asm volatile("s_waitcnt lgkmcnt(" #n ")" ::: "memory")
; #define PG8_BAR __builtin_amdgcn_s_barrier()
; #define PG8_SCHED __builtin_amdgcn_sched_barrier(0)
; template <class Epi, class Sched, bool ALIGN_EPI = false, bool SP2 = false>
; __device__ __forceinline__ void gemm_phase(PG8_LAS unsigned char* lds, const Gemm g, const Sched& S, const Epi& E, int tid_in) {
;     ...
;             PG8_WAIT_V(8); PG8_WAIT_L(0); PG8_BAR; PG8_MMA(0, 0, At, B0); PG8_MMA(0, 1, At, B1); PG8_BAR; PG8_SCHED;
;             PG8_LDA(At, 1, 1); PG8_STAGE(PG8_SB(1, 0), b3, voffB); PG8_STAGE(PG8_SB(1, 1), b3 + hstepB, voffB); PG8_STAGE(PG8_SA(1, 0), a3, voffA);
;             PG8_WAIT_V(8); PG8_WAIT_L(0); PG8_BAR; PG8_MMA(1, 0, At, B0); PG8_MMA(1, 1, At, B1); PG8_BAR; PG8_SCHED;
;     ...
;         if constexpr (ALIGN_EPI) { if (wr == 0) PG8_BAR; }
;         if constexpr (!Epi::AFTER_DRAIN) { E(acc, cur, wr, wc, fr, fq); S.done(cur); }
	v_mfma_f32_16x16x32_bf16 v[126:129], v[130:133], v[162:165], v[126:129]
	v_mfma_f32_16x16x32_bf16 v[122:125], v[138:141], v[162:165], v[122:125]
	v_mfma_f32_16x16x32_bf16 v[106:109], v[138:141], v[170:173], v[106:109]
	v_mfma_f32_16x16x32_bf16 v[110:113], v[130:133], v[170:173], v[110:113]
	v_mfma_f32_16x16x32_bf16 v[94:97], v[130:133], v[178:181], v[94:97]
	v_mfma_f32_16x16x32_bf16 v[90:93], v[138:141], v[178:181], v[90:93]
	v_mfma_f32_16x16x32_bf16 v[74:77], v[138:141], v[186:189], v[74:77]
	v_mfma_f32_16x16x32_bf16 v[78:81], v[130:133], v[186:189], v[78:81]
	v_mfma_f32_16x16x32_bf16 v[126:129], v[134:137], v[166:169], v[126:129]
	v_mfma_f32_16x16x32_bf16 v[122:125], v[142:145], v[166:169], v[122:125]
	v_mfma_f32_16x16x32_bf16 v[106:109], v[142:145], v[174:177], v[106:109]
	v_mfma_f32_16x16x32_bf16 v[110:113], v[134:137], v[174:177], v[110:113]
	v_mfma_f32_16x16x32_bf16 v[94:97], v[134:137], v[182:185], v[94:97]
	v_mfma_f32_16x16x32_bf16 v[90:93], v[142:145], v[182:185], v[90:93]
	v_mfma_f32_16x16x32_bf16 v[74:77], v[142:145], v[190:193], v[74:77]
	v_mfma_f32_16x16x32_bf16 v[78:81], v[134:137], v[190:193], v[78:81]
	v_mfma_f32_16x16x32_bf16 v[118:121], v[146:149], v[162:165], v[118:121]
	v_mfma_f32_16x16x32_bf16 v[114:117], v[154:157], v[162:165], v[114:117]
	v_mfma_f32_16x16x32_bf16 v[98:101], v[154:157], v[170:173], v[98:101]
	v_mfma_f32_16x16x32_bf16 v[102:105], v[146:149], v[170:173], v[102:105]
	v_mfma_f32_16x16x32_bf16 v[86:89], v[146:149], v[178:181], v[86:89]
	v_mfma_f32_16x16x32_bf16 v[82:85], v[154:157], v[178:181], v[82:85]
	v_mfma_f32_16x16x32_bf16 v[66:69], v[154:157], v[186:189], v[66:69]
	v_mfma_f32_16x16x32_bf16 v[70:73], v[146:149], v[186:189], v[70:73]
	v_mfma_f32_16x16x32_bf16 v[118:121], v[150:153], v[166:169], v[118:121]
	v_mfma_f32_16x16x32_bf16 v[114:117], v[158:161], v[166:169], v[114:117]
	v_mfma_f32_16x16x32_bf16 v[98:101], v[158:161], v[174:177], v[98:101]
	v_mfma_f32_16x16x32_bf16 v[102:105], v[150:153], v[174:177], v[102:105]
	v_mfma_f32_16x16x32_bf16 v[86:89], v[150:153], v[182:185], v[86:89]
	v_mfma_f32_16x16x32_bf16 v[82:85], v[158:161], v[182:185], v[82:85]
	v_mfma_f32_16x16x32_bf16 v[66:69], v[158:161], v[190:193], v[66:69]
	v_mfma_f32_16x16x32_bf16 v[70:73], v[150:153], v[190:193], v[70:73]
	s_barrier
	s_setprio 0
	s_mov_b32 m0, s75
	s_add_i32 s36, s12, 0x80
	buffer_load_dwordx4 v207, s[40:43], s36 offen lds
	s_mov_b32 m0, s76
	s_add_i32 s12, s12, 0x80080
	buffer_load_dwordx4 v224, s[40:43], s36 offen lds
	ds_read_b128 v[162:165], v238 offset:49152
	ds_read_b128 v[166:169], v238 offset:50176
	ds_read_b128 v[170:173], v238 offset:51200
	ds_read_b128 v[174:177], v238 offset:52224
	ds_read_b128 v[178:181], v238 offset:53248
	ds_read_b128 v[182:185], v238 offset:54272
	ds_read_b128 v[186:189], v238 offset:55296
	ds_read_b128 v[190:193], v238 offset:56320
	s_mov_b32 m0, s79
	s_addk_i32 s13, 0x80
	buffer_load_dwordx4 v207, s[40:43], s12 offen lds
	s_mov_b32 m0, s68
	s_nop 0
	buffer_load_dwordx4 v224, s[40:43], s12 offen lds
	s_mov_b32 m0, s77
	s_nop 0
	buffer_load_dwordx4 v195, s[4:7], s13 offen lds
	s_waitcnt vmcnt(7)
	s_waitcnt lgkmcnt(0)
	s_setprio 1
	s_barrier
	v_mfma_f32_16x16x32_bf16 v[62:65], v[130:133], v[162:165], v[62:65]
	v_mfma_f32_16x16x32_bf16 v[58:61], v[138:141], v[162:165], v[58:61]
	v_mfma_f32_16x16x32_bf16 v[42:45], v[138:141], v[170:173], v[42:45]
	v_mfma_f32_16x16x32_bf16 v[46:49], v[130:133], v[170:173], v[46:49]
	v_mfma_f32_16x16x32_bf16 v[30:33], v[130:133], v[178:181], v[30:33]
	v_mfma_f32_16x16x32_bf16 v[26:29], v[138:141], v[178:181], v[26:29]
	v_mfma_f32_16x16x32_bf16 v[10:13], v[138:141], v[186:189], v[10:13]
	v_mfma_f32_16x16x32_bf16 v[14:17], v[130:133], v[186:189], v[14:17]
	v_mfma_f32_16x16x32_bf16 v[62:65], v[134:137], v[166:169], v[62:65]
	v_mfma_f32_16x16x32_bf16 v[58:61], v[142:145], v[166:169], v[58:61]
	v_mfma_f32_16x16x32_bf16 v[42:45], v[142:145], v[174:177], v[42:45]
	v_mfma_f32_16x16x32_bf16 v[46:49], v[134:137], v[174:177], v[46:49]
	v_mfma_f32_16x16x32_bf16 v[30:33], v[134:137], v[182:185], v[30:33]
	v_mfma_f32_16x16x32_bf16 v[26:29], v[142:145], v[182:185], v[26:29]
	v_mfma_f32_16x16x32_bf16 v[10:13], v[142:145], v[190:193], v[10:13]
	v_mfma_f32_16x16x32_bf16 v[14:17], v[134:137], v[190:193], v[14:17]
	v_mfma_f32_16x16x32_bf16 v[54:57], v[146:149], v[162:165], v[54:57]
	v_mfma_f32_16x16x32_bf16 v[50:53], v[154:157], v[162:165], v[50:53]
	v_mfma_f32_16x16x32_bf16 v[34:37], v[154:157], v[170:173], v[34:37]
	v_mfma_f32_16x16x32_bf16 v[38:41], v[146:149], v[170:173], v[38:41]
	v_mfma_f32_16x16x32_bf16 v[22:25], v[146:149], v[178:181], v[22:25]
	v_mfma_f32_16x16x32_bf16 v[18:21], v[154:157], v[178:181], v[18:21]
	v_mfma_f32_16x16x32_bf16 v[2:5], v[154:157], v[186:189], v[2:5]
	v_mfma_f32_16x16x32_bf16 v[6:9], v[146:149], v[186:189], v[6:9]
	v_mfma_f32_16x16x32_bf16 v[54:57], v[150:153], v[166:169], v[54:57]
	v_mfma_f32_16x16x32_bf16 v[50:53], v[158:161], v[166:169], v[50:53]
	v_mfma_f32_16x16x32_bf16 v[34:37], v[158:161], v[174:177], v[34:37]
	v_mfma_f32_16x16x32_bf16 v[38:41], v[150:153], v[174:177], v[38:41]
	v_mfma_f32_16x16x32_bf16 v[22:25], v[150:153], v[182:185], v[22:25]
	v_mfma_f32_16x16x32_bf16 v[18:21], v[158:161], v[182:185], v[18:21]
	v_mfma_f32_16x16x32_bf16 v[2:5], v[158:161], v[190:193], v[2:5]
	v_mfma_f32_16x16x32_bf16 v[6:9], v[150:153], v[190:193], v[6:9]
	s_barrier
	s_setprio 0
	s_add_i32 s23, s23, 2
	s_add_u32 s20, s20, 0x100
	s_addc_u32 s21, s21, 0
	s_cmp_gt_u32 s23, 29
	s_mov_b64 s[12:13], s[16:17]
	s_cbranch_scc0 .LBB0_312
	s_and_b64 vcc, exec, s[48:49]
	s_cbranch_vccz .LBB0_315
	s_barrier

; #define PG8_STAGE(bufoff, gbase, voff) do { const int so_ = (int)(unsigned)((const char*)(gbase) - base_##voff); _Pragma("unroll") for (int _i = 0; _i < 2; ++_i) \
;         __builtin_amdgcn_raw_ptr_buffer_load_lds(rs_##voff, (PG8_LAS unsigned*)(lds + (bufoff) + ldsw + _i * 8192), 16, (int)(voff)[_i], so_, 0, 0); } while (0)
; #define PG8_LDA(dst, b, h) do { _Pragma("unroll") for (int m = 0; m < 4; ++m) _Pragma("unroll") for (int k = 0; k < 2; ++k) dst[m][k] = *(const PG8_LAS bf16x8*)(lds + PG8_SA(b, h) + aoff + m * 2048 + k * 1024); } while (0)
; #define PG8_LDB(dst, b, h) do { _Pragma("unroll") for (int n = 0; n < 2; ++n) _Pragma("unroll") for (int k = 0; k < 2; ++k) dst[n][k] = *(const PG8_LAS bf16x8*)(lds + PG8_SB(b, h) + boff + n * 2048 + k * 1024); } while (0)
; #define PG8_MMA(ai, bj, At, Bt) do { __builtin_amdgcn_s_setprio(1); _Pragma("unroll") for (int m = 0; m < 4; ++m) _Pragma("unroll") for (int n = 0; n < 2; ++n) _Pragma("unroll") for (int k = 0; k < 2; ++k) \
;         acc[ai][bj][m][n] = __builtin_amdgcn_mfma_f32_16x16x32_bf16(Bt[n][k], At[m][k], acc[ai][bj][m][n], 0, 0, 0); __builtin_amdgcn_s_setprio(0); } while (0)
; #define PG8_WAIT_V(n) asm volatile("s_waitcnt vmcnt(" #n ")" ::: "memory")
; #define PG8_WAIT_L(n) asm volatile("s_waitcnt lgkmcnt(" #n ")" ::: "memory")
; #define PG8_BAR __builtin_amdgcn_s_barrier()
; #define PG8_SCHED __builtin_amdgcn_sched_barrier(0)
; template <class Epi, class Sched, bool ALIGN_EPI = false, bool SP2 = false>
; __device__ __forceinline__ void gemm_phase(PG8_LAS unsigned char* lds, const Gemm g, const Sched& S, const Epi& E, int tid_in) {
;     ...
;             PG8_LDB(B0, 0, 0); PG8_LDB(B1, 0, 1); PG8_SCHED; PG8_LDA(At, 0, 0); PG8_STAGE(PG8_SA(1, 1), a1 + hstepA, voffA);
;             PG8_WAIT_V(8); PG8_WAIT_L(0); PG8_BAR; PG8_MMA(0, 0, At, B0); PG8_MMA(0, 1, At, B1); PG8_BAR; PG8_SCHED;
;             PG8_LDA(At, 0, 1); PG8_STAGE(PG8_SB(0, 0), b2, voffB); PG8_STAGE(PG8_SB(0, 1), b2 + hstepB, voffB); PG8_STAGE(PG8_SA(0, 0), a2, voffA);
;             PG8_WAIT_V(8); PG8_WAIT_L(0); PG8_BAR; PG8_MMA(1, 0, At, B0); PG8_MMA(1, 1, At, B1); PG8_BAR; PG8_SCHED;
.LBB0_1037:
	v_add_u32_e32 v0, 0x10000, v236
	ds_read_b128 v[132:135], v0
	ds_read_b128 v[136:139], v0 offset:1024
	ds_read_b128 v[140:143], v0 offset:2048
	ds_read_b128 v[144:147], v0 offset:3072
	v_add_u32_e32 v0, 0x14000, v236
	ds_read_b128 v[148:151], v0
	ds_read_b128 v[152:155], v0 offset:1024
	ds_read_b128 v[156:159], v0 offset:2048
	ds_read_b128 v[160:163], v0 offset:3072
	s_add_u32 s16, s12, 0x100
	s_addc_u32 s17, s13, 0
	s_sub_i32 s12, s12, s4
	s_add_i32 s12, s12, 0xc0080
	s_sub_i32 s39, s12, 0xc0000
	s_cmp_eq_u32 s38, 12
	s_cselect_b32 s13, s24, s16
	s_mov_b32 m0, s76
	ds_read_b128 v[164:167], v237
	ds_read_b128 v[168:171], v237 offset:1024
	ds_read_b128 v[172:175], v237 offset:2048
	ds_read_b128 v[176:179], v237 offset:3072
	ds_read_b128 v[180:183], v237 offset:4096
	ds_read_b128 v[184:187], v237 offset:5120
	ds_read_b128 v[188:191], v237 offset:6144
	ds_read_b128 v[192:195], v237 offset:7168
	s_mov_b32 m0, s73
	s_nop 0
	buffer_load_dwordx4 v222, s[4:7], s39 offen lds
	s_mov_b32 m0, s76
	s_nop 0
	buffer_load_dwordx4 v220, s[4:7], s12 offen lds
	s_mov_b32 m0, s77
	s_nop 0
	buffer_load_dwordx4 v222, s[4:7], s12 offen lds
	s_waitcnt vmcnt(8)
	s_waitcnt lgkmcnt(0)
	s_setprio 1
	s_barrier
	v_mfma_f32_16x16x32_bf16 v[128:131], v[132:135], v[164:167], v[128:131]
	v_mfma_f32_16x16x32_bf16 v[124:127], v[140:143], v[164:167], v[124:127]
	v_mfma_f32_16x16x32_bf16 v[116:119], v[140:143], v[172:175], v[116:119]
	v_mfma_f32_16x16x32_bf16 v[120:123], v[132:135], v[172:175], v[120:123]
	v_mfma_f32_16x16x32_bf16 v[112:115], v[132:135], v[180:183], v[112:115]
	v_mfma_f32_16x16x32_bf16 v[108:111], v[140:143], v[180:183], v[108:111]
	v_mfma_f32_16x16x32_bf16 v[100:103], v[140:143], v[188:191], v[100:103]
	v_mfma_f32_16x16x32_bf16 v[104:107], v[132:135], v[188:191], v[104:107]
	v_mfma_f32_16x16x32_bf16 v[128:131], v[136:139], v[168:171], v[128:131]
	v_mfma_f32_16x16x32_bf16 v[124:127], v[144:147], v[168:171], v[124:127]
	v_mfma_f32_16x16x32_bf16 v[116:119], v[144:147], v[176:179], v[116:119]
	v_mfma_f32_16x16x32_bf16 v[120:123], v[136:139], v[176:179], v[120:123]
	v_mfma_f32_16x16x32_bf16 v[112:115], v[136:139], v[184:187], v[112:115]
	v_mfma_f32_16x16x32_bf16 v[108:111], v[144:147], v[184:187], v[108:111]
	v_mfma_f32_16x16x32_bf16 v[100:103], v[144:147], v[192:195], v[100:103]
	v_mfma_f32_16x16x32_bf16 v[104:107], v[136:139], v[192:195], v[104:107]
	v_mfma_f32_16x16x32_bf16 v[96:99], v[148:151], v[164:167], v[96:99]
	v_mfma_f32_16x16x32_bf16 v[92:95], v[156:159], v[164:167], v[92:95]
	v_mfma_f32_16x16x32_bf16 v[84:87], v[156:159], v[172:175], v[84:87]
	v_mfma_f32_16x16x32_bf16 v[88:91], v[148:151], v[172:175], v[88:91]
	v_mfma_f32_16x16x32_bf16 v[80:83], v[148:151], v[180:183], v[80:83]
	v_mfma_f32_16x16x32_bf16 v[76:79], v[156:159], v[180:183], v[76:79]
	v_mfma_f32_16x16x32_bf16 v[68:71], v[156:159], v[188:191], v[68:71]
	v_mfma_f32_16x16x32_bf16 v[72:75], v[148:151], v[188:191], v[72:75]
	v_mfma_f32_16x16x32_bf16 v[96:99], v[152:155], v[168:171], v[96:99]
	v_mfma_f32_16x16x32_bf16 v[92:95], v[160:163], v[168:171], v[92:95]
	v_mfma_f32_16x16x32_bf16 v[84:87], v[160:163], v[176:179], v[84:87]
	v_mfma_f32_16x16x32_bf16 v[88:91], v[152:155], v[176:179], v[88:91]
	v_mfma_f32_16x16x32_bf16 v[80:83], v[152:155], v[184:187], v[80:83]
	v_mfma_f32_16x16x32_bf16 v[76:79], v[160:163], v[184:187], v[76:79]
	v_mfma_f32_16x16x32_bf16 v[68:71], v[160:163], v[192:195], v[68:71]
	v_mfma_f32_16x16x32_bf16 v[72:75], v[152:155], v[192:195], v[72:75]
	s_barrier
	s_setprio 0
	s_cselect_b32 s12, s18, s19
	s_mov_b32 m0, s26
	s_mov_b32 s46, s6
	s_mov_b32 s47, s7
	s_sub_i32 s12, s12, s44
	buffer_load_dwordx4 v221, s[44:47], s12 offen lds
	s_mov_b32 m0, s53
	s_add_i32 s39, s12, 0x40000
	buffer_load_dwordx4 v223, s[44:47], s12 offen lds
	ds_read_b128 v[164:167], v237 offset:16384
	ds_read_b128 v[168:171], v237 offset:17408
	ds_read_b128 v[172:175], v237 offset:18432
	ds_read_b128 v[176:179], v237 offset:19456
	ds_read_b128 v[180:183], v237 offset:20480
	ds_read_b128 v[184:187], v237 offset:21504
	ds_read_b128 v[188:191], v237 offset:22528
	ds_read_b128 v[192:195], v237 offset:23552
	s_mov_b32 m0, s60
	s_sub_i32 s13, s13, s4
	buffer_load_dwordx4 v221, s[44:47], s39 offen lds
	s_mov_b32 m0, s61
	s_nop 0
	buffer_load_dwordx4 v223, s[44:47], s39 offen lds
	s_mov_b32 m0, s21
	s_nop 0
	buffer_load_dwordx4 v220, s[4:7], s13 offen lds
	s_waitcnt vmcnt(7)
	s_waitcnt lgkmcnt(0)
	s_setprio 1
	s_barrier
	v_mfma_f32_16x16x32_bf16 v[64:67], v[132:135], v[164:167], v[64:67]
	v_mfma_f32_16x16x32_bf16 v[60:63], v[140:143], v[164:167], v[60:63]
	v_mfma_f32_16x16x32_bf16 v[52:55], v[140:143], v[172:175], v[52:55]
	v_mfma_f32_16x16x32_bf16 v[56:59], v[132:135], v[172:175], v[56:59]
	v_mfma_f32_16x16x32_bf16 v[48:51], v[132:135], v[180:183], v[48:51]
	v_mfma_f32_16x16x32_bf16 v[44:47], v[140:143], v[180:183], v[44:47]
	v_mfma_f32_16x16x32_bf16 v[36:39], v[140:143], v[188:191], v[36:39]
	v_mfma_f32_16x16x32_bf16 v[40:43], v[132:135], v[188:191], v[40:43]
	v_mfma_f32_16x16x32_bf16 v[64:67], v[136:139], v[168:171], v[64:67]
	v_mfma_f32_16x16x32_bf16 v[60:63], v[144:147], v[168:171], v[60:63]
	v_mfma_f32_16x16x32_bf16 v[52:55], v[144:147], v[176:179], v[52:55]
	v_mfma_f32_16x16x32_bf16 v[56:59], v[136:139], v[176:179], v[56:59]
	v_mfma_f32_16x16x32_bf16 v[48:51], v[136:139], v[184:187], v[48:51]
	v_mfma_f32_16x16x32_bf16 v[44:47], v[144:147], v[184:187], v[44:47]
	v_mfma_f32_16x16x32_bf16 v[36:39], v[144:147], v[192:195], v[36:39]
	v_mfma_f32_16x16x32_bf16 v[40:43], v[136:139], v[192:195], v[40:43]
	v_mfma_f32_16x16x32_bf16 v[32:35], v[148:151], v[164:167], v[32:35]
	v_mfma_f32_16x16x32_bf16 v[28:31], v[156:159], v[164:167], v[28:31]
	v_mfma_f32_16x16x32_bf16 v[20:23], v[156:159], v[172:175], v[20:23]
	v_mfma_f32_16x16x32_bf16 v[24:27], v[148:151], v[172:175], v[24:27]
	v_mfma_f32_16x16x32_bf16 v[16:19], v[148:151], v[180:183], v[16:19]
	v_mfma_f32_16x16x32_bf16 v[12:15], v[156:159], v[180:183], v[12:15]
	v_mfma_f32_16x16x32_bf16 v[2:5], v[156:159], v[188:191], v[4:7]
	v_mfma_f32_16x16x32_bf16 v[8:11], v[148:151], v[188:191], v[8:11]
	v_mfma_f32_16x16x32_bf16 v[32:35], v[152:155], v[168:171], v[32:35]
	v_mfma_f32_16x16x32_bf16 v[28:31], v[160:163], v[168:171], v[28:31]
	v_mfma_f32_16x16x32_bf16 v[20:23], v[160:163], v[176:179], v[20:23]
	v_mfma_f32_16x16x32_bf16 v[24:27], v[152:155], v[176:179], v[24:27]
	v_mfma_f32_16x16x32_bf16 v[16:19], v[152:155], v[184:187], v[16:19]
	v_mfma_f32_16x16x32_bf16 v[12:15], v[160:163], v[184:187], v[12:15]
	v_mfma_f32_16x16x32_bf16 v[2:5], v[160:163], v[192:195], v[2:5]
	v_mfma_f32_16x16x32_bf16 v[8:11], v[152:155], v[192:195], v[8:11]
	s_barrier
; #define PG8_STAGE(bufoff, gbase, voff) do { const int so_ = (int)(unsigned)((const char*)(gbase) - base_##voff); _Pragma("unroll") for (int _i = 0; _i < 2; ++_i) \
;         __builtin_amdgcn_raw_ptr_buffer_load_lds(rs_##voff, (PG8_LAS unsigned*)(lds + (bufoff) + ldsw + _i * 8192), 16, (int)(voff)[_i], so_, 0, 0); } while (0)
; #define PG8_LDA(dst, b, h) do { _Pragma("unroll") for (int m = 0; m < 4; ++m) _Pragma("unroll") for (int k = 0; k < 2; ++k) dst[m][k] = *(const PG8_LAS bf16x8*)(lds + PG8_SA(b, h) + aoff + m * 2048 + k * 1024); } while (0)
; #define PG8_LDB(dst, b, h) do { _Pragma("unroll") for (int n = 0; n < 2; ++n) _Pragma("unroll") for (int k = 0; k < 2; ++k) dst[n][k] = *(const PG8_LAS bf16x8*)(lds + PG8_SB(b, h) + boff + n * 2048 + k * 1024); } while (0)
; #define PG8_MMA(ai, bj, At, Bt) do { __builtin_amdgcn_s_setprio(1); _Pragma("unroll") for (int m = 0; m < 4; ++m) _Pragma("unroll") for (int n = 0; n < 2; ++n) _Pragma("unroll") for (int k = 0; k < 2; ++k) \
;         acc[ai][bj][m][n] = __builtin_amdgcn_mfma_f32_16x16x32_bf16(Bt[n][k], At[m][k], acc[ai][bj][m][n], 0, 0, 0); __builtin_amdgcn_s_setprio(0); } while (0)
; #define PG8_BAR __builtin_amdgcn_s_barrier()
; template <class Epi, class Sched, bool ALIGN_EPI = false, bool SP2 = false>
; __device__ __forceinline__ void gemm_phase(PG8_LAS unsigned char* lds, const Gemm g, const Sched& S, const Epi& E, int tid_in) {
;     ...
;             PG8_WAIT_V(8); PG8_WAIT_L(0); PG8_BAR; PG8_MMA(0, 0, At, B0); PG8_MMA(0, 1, At, B1); PG8_BAR; PG8_SCHED;
;             PG8_LDA(At, 0, 1); PG8_STAGE(PG8_SB(0, 0), b2, voffB); PG8_STAGE(PG8_SB(0, 1), b2 + hstepB, voffB); PG8_STAGE(PG8_SA(0, 0), a2, voffA);
;             PG8_WAIT_V(8); PG8_WAIT_L(0); PG8_BAR; PG8_MMA(1, 0, At, B0); PG8_MMA(1, 1, At, B1); PG8_BAR; PG8_SCHED;
;             PG8_LDB(B0, 1, 0); PG8_LDB(B1, 1, 1); PG8_SCHED; PG8_LDA(At, 1, 0); PG8_STAGE(PG8_SA(0, 1), a2 + hstepA, voffA);
;             PG8_WAIT_V(8); PG8_WAIT_L(0); PG8_BAR; PG8_MMA(0, 0, At, B0); PG8_MMA(0, 1, At, B1); PG8_BAR; PG8_SCHED;
;             PG8_LDA(At, 1, 1); PG8_STAGE(PG8_SB(1, 0), b3, voffB); PG8_STAGE(PG8_SB(1, 1), b3 + hstepB, voffB); PG8_STAGE(PG8_SA(1, 0), a3, voffA);
;             PG8_WAIT_V(8); PG8_WAIT_L(0); PG8_BAR; PG8_MMA(1, 0, At, B0); PG8_MMA(1, 1, At, B1); PG8_BAR; PG8_SCHED;
;     ...
;         if constexpr (ALIGN_EPI) { if (wr == 0) PG8_BAR; }
	s_setprio 0
	v_add_u32_e32 v0, 0x18000, v236
	ds_read_b128 v[132:135], v0
	ds_read_b128 v[136:139], v0 offset:1024
	ds_read_b128 v[140:143], v0 offset:2048
	ds_read_b128 v[144:147], v0 offset:3072
	v_add_u32_e32 v0, 0x1c000, v236
	ds_read_b128 v[148:151], v0
	ds_read_b128 v[152:155], v0 offset:1024
	ds_read_b128 v[156:159], v0 offset:2048
	ds_read_b128 v[160:163], v0 offset:3072
	s_add_i32 s39, s13, 0xc0000
	s_mov_b32 m0, s63
	ds_read_b128 v[164:167], v237 offset:32768
	ds_read_b128 v[168:171], v237 offset:33792
	ds_read_b128 v[172:175], v237 offset:34816
	ds_read_b128 v[176:179], v237 offset:35840
	ds_read_b128 v[180:183], v237 offset:36864
	ds_read_b128 v[184:187], v237 offset:37888
	ds_read_b128 v[188:191], v237 offset:38912
	ds_read_b128 v[192:195], v237 offset:39936
	s_mov_b32 m0, s62
	s_nop 0
	buffer_load_dwordx4 v222, s[4:7], s13 offen lds
	s_mov_b32 m0, s63
	s_nop 0
	buffer_load_dwordx4 v220, s[4:7], s39 offen lds
	s_mov_b32 m0, s66
	s_nop 0
	buffer_load_dwordx4 v222, s[4:7], s39 offen lds
	s_waitcnt vmcnt(8)
	s_waitcnt lgkmcnt(0)
	s_setprio 1
	s_barrier
	v_mfma_f32_16x16x32_bf16 v[128:131], v[132:135], v[164:167], v[128:131]
	v_mfma_f32_16x16x32_bf16 v[124:127], v[140:143], v[164:167], v[124:127]
	v_mfma_f32_16x16x32_bf16 v[116:119], v[140:143], v[172:175], v[116:119]
	v_mfma_f32_16x16x32_bf16 v[120:123], v[132:135], v[172:175], v[120:123]
	v_mfma_f32_16x16x32_bf16 v[112:115], v[132:135], v[180:183], v[112:115]
	v_mfma_f32_16x16x32_bf16 v[108:111], v[140:143], v[180:183], v[108:111]
	v_mfma_f32_16x16x32_bf16 v[100:103], v[140:143], v[188:191], v[100:103]
	v_mfma_f32_16x16x32_bf16 v[104:107], v[132:135], v[188:191], v[104:107]
	v_mfma_f32_16x16x32_bf16 v[128:131], v[136:139], v[168:171], v[128:131]
	v_mfma_f32_16x16x32_bf16 v[124:127], v[144:147], v[168:171], v[124:127]
	v_mfma_f32_16x16x32_bf16 v[116:119], v[144:147], v[176:179], v[116:119]
	v_mfma_f32_16x16x32_bf16 v[120:123], v[136:139], v[176:179], v[120:123]
	v_mfma_f32_16x16x32_bf16 v[112:115], v[136:139], v[184:187], v[112:115]
	v_mfma_f32_16x16x32_bf16 v[108:111], v[144:147], v[184:187], v[108:111]
	v_mfma_f32_16x16x32_bf16 v[100:103], v[144:147], v[192:195], v[100:103]
	v_mfma_f32_16x16x32_bf16 v[104:107], v[136:139], v[192:195], v[104:107]
	v_mfma_f32_16x16x32_bf16 v[96:99], v[148:151], v[164:167], v[96:99]
	v_mfma_f32_16x16x32_bf16 v[92:95], v[156:159], v[164:167], v[92:95]
	v_mfma_f32_16x16x32_bf16 v[84:87], v[156:159], v[172:175], v[84:87]
	v_mfma_f32_16x16x32_bf16 v[88:91], v[148:151], v[172:175], v[88:91]
	v_mfma_f32_16x16x32_bf16 v[80:83], v[148:151], v[180:183], v[80:83]
	v_mfma_f32_16x16x32_bf16 v[76:79], v[156:159], v[180:183], v[76:79]
	v_mfma_f32_16x16x32_bf16 v[68:71], v[156:159], v[188:191], v[68:71]
	v_mfma_f32_16x16x32_bf16 v[72:75], v[148:151], v[188:191], v[72:75]
	v_mfma_f32_16x16x32_bf16 v[96:99], v[152:155], v[168:171], v[96:99]
	v_mfma_f32_16x16x32_bf16 v[92:95], v[160:163], v[168:171], v[92:95]
	v_mfma_f32_16x16x32_bf16 v[84:87], v[160:163], v[176:179], v[84:87]
	v_mfma_f32_16x16x32_bf16 v[88:91], v[152:155], v[176:179], v[88:91]
	v_mfma_f32_16x16x32_bf16 v[80:83], v[152:155], v[184:187], v[80:83]
	v_mfma_f32_16x16x32_bf16 v[76:79], v[160:163], v[184:187], v[76:79]
	v_mfma_f32_16x16x32_bf16 v[68:71], v[160:163], v[192:195], v[68:71]
	v_mfma_f32_16x16x32_bf16 v[72:75], v[152:155], v[192:195], v[72:75]
	s_barrier
	s_setprio 0
	s_mov_b32 m0, s69
	s_add_i32 s39, s12, 0x80
	buffer_load_dwordx4 v221, s[44:47], s39 offen lds
	s_mov_b32 m0, s71
	s_add_i32 s12, s12, 0x40080
	buffer_load_dwordx4 v223, s[44:47], s39 offen lds
	ds_read_b128 v[164:167], v237 offset:49152
	ds_read_b128 v[168:171], v237 offset:50176
	ds_read_b128 v[172:175], v237 offset:51200
	ds_read_b128 v[176:179], v237 offset:52224
	ds_read_b128 v[180:183], v237 offset:53248
	ds_read_b128 v[184:187], v237 offset:54272
	ds_read_b128 v[188:191], v237 offset:55296
	ds_read_b128 v[192:195], v237 offset:56320
	s_mov_b32 m0, s74
	s_addk_i32 s13, 0x80
	buffer_load_dwordx4 v221, s[44:47], s12 offen lds
	s_mov_b32 m0, s75
	s_nop 0
	buffer_load_dwordx4 v223, s[44:47], s12 offen lds
	s_mov_b32 m0, s72
	s_nop 0
	buffer_load_dwordx4 v220, s[4:7], s13 offen lds
	s_waitcnt vmcnt(7)
	s_waitcnt lgkmcnt(0)
	s_setprio 1
	s_barrier
	v_mfma_f32_16x16x32_bf16 v[64:67], v[132:135], v[164:167], v[64:67]
	v_mfma_f32_16x16x32_bf16 v[60:63], v[140:143], v[164:167], v[60:63]
	v_mfma_f32_16x16x32_bf16 v[52:55], v[140:143], v[172:175], v[52:55]
	v_mfma_f32_16x16x32_bf16 v[56:59], v[132:135], v[172:175], v[56:59]
	v_mfma_f32_16x16x32_bf16 v[48:51], v[132:135], v[180:183], v[48:51]
	v_mfma_f32_16x16x32_bf16 v[44:47], v[140:143], v[180:183], v[44:47]
	v_mfma_f32_16x16x32_bf16 v[36:39], v[140:143], v[188:191], v[36:39]
	v_mfma_f32_16x16x32_bf16 v[40:43], v[132:135], v[188:191], v[40:43]
	v_mfma_f32_16x16x32_bf16 v[64:67], v[136:139], v[168:171], v[64:67]
	v_mfma_f32_16x16x32_bf16 v[60:63], v[144:147], v[168:171], v[60:63]
	v_mfma_f32_16x16x32_bf16 v[52:55], v[144:147], v[176:179], v[52:55]
	v_mfma_f32_16x16x32_bf16 v[56:59], v[136:139], v[176:179], v[56:59]
	v_mfma_f32_16x16x32_bf16 v[48:51], v[136:139], v[184:187], v[48:51]
	v_mfma_f32_16x16x32_bf16 v[44:47], v[144:147], v[184:187], v[44:47]
	v_mfma_f32_16x16x32_bf16 v[36:39], v[144:147], v[192:195], v[36:39]
	v_mfma_f32_16x16x32_bf16 v[40:43], v[136:139], v[192:195], v[40:43]
	v_mfma_f32_16x16x32_bf16 v[32:35], v[148:151], v[164:167], v[32:35]
	v_mfma_f32_16x16x32_bf16 v[28:31], v[156:159], v[164:167], v[28:31]
	v_mfma_f32_16x16x32_bf16 v[20:23], v[156:159], v[172:175], v[20:23]
	v_mfma_f32_16x16x32_bf16 v[24:27], v[148:151], v[172:175], v[24:27]
	v_mfma_f32_16x16x32_bf16 v[16:19], v[148:151], v[180:183], v[16:19]
	v_mfma_f32_16x16x32_bf16 v[12:15], v[156:159], v[180:183], v[12:15]
	v_mfma_f32_16x16x32_bf16 v[2:5], v[156:159], v[188:191], v[2:5]
	v_mfma_f32_16x16x32_bf16 v[6:9], v[148:151], v[188:191], v[8:11]
	v_mfma_f32_16x16x32_bf16 v[32:35], v[152:155], v[168:171], v[32:35]
	v_mfma_f32_16x16x32_bf16 v[28:31], v[160:163], v[168:171], v[28:31]
	v_mfma_f32_16x16x32_bf16 v[20:23], v[160:163], v[176:179], v[20:23]
	v_mfma_f32_16x16x32_bf16 v[24:27], v[152:155], v[176:179], v[24:27]
	v_mfma_f32_16x16x32_bf16 v[16:19], v[152:155], v[184:187], v[16:19]
	v_mfma_f32_16x16x32_bf16 v[12:15], v[160:163], v[184:187], v[12:15]
	v_mfma_f32_16x16x32_bf16 v[8:11], v[152:155], v[192:195], v[6:9]
	v_mfma_f32_16x16x32_bf16 v[4:7], v[160:163], v[192:195], v[2:5]
	s_barrier
	s_setprio 0
	s_add_i32 s38, s38, 2
	s_add_u32 s19, s19, 0x100
	s_addc_u32 s23, s23, 0
	s_cmp_gt_u32 s38, 13
	s_mov_b64 s[12:13], s[16:17]
	s_cbranch_scc0 .LBB0_1037
	s_and_b64 vcc, exec, s[14:15]
	s_cbranch_vccz .LBB0_1040
	s_barrier

; #define PG8_STAGE(bufoff, gbase, voff) do { const int so_ = (int)(unsigned)((const char*)(gbase) - base_##voff); _Pragma("unroll") for (int _i = 0; _i < 2; ++_i) \
;         __builtin_amdgcn_raw_ptr_buffer_load_lds(rs_##voff, (PG8_LAS unsigned*)(lds + (bufoff) + ldsw + _i * 8192), 16, (int)(voff)[_i], so_, 0, 0); } while (0)
; #define PG8_LDA(dst, b, h) do { _Pragma("unroll") for (int m = 0; m < 4; ++m) _Pragma("unroll") for (int k = 0; k < 2; ++k) dst[m][k] = *(const PG8_LAS bf16x8*)(lds + PG8_SA(b, h) + aoff + m * 2048 + k * 1024); } while (0)
; #define PG8_LDB(dst, b, h) do { _Pragma("unroll") for (int n = 0; n < 2; ++n) _Pragma("unroll") for (int k = 0; k < 2; ++k) dst[n][k] = *(const PG8_LAS bf16x8*)(lds + PG8_SB(b, h) + boff + n * 2048 + k * 1024); } while (0)
; #define PG8_MMA(ai, bj, At, Bt) do { __builtin_amdgcn_s_setprio(1); _Pragma("unroll") for (int m = 0; m < 4; ++m) _Pragma("unroll") for (int n = 0; n < 2; ++n) _Pragma("unroll") for (int k = 0; k < 2; ++k) \
;         acc[ai][bj][m][n] = __builtin_amdgcn_mfma_f32_16x16x32_bf16(Bt[n][k], At[m][k], acc[ai][bj][m][n], 0, 0, 0); __builtin_amdgcn_s_setprio(0); } while (0)
; #define PG8_WAIT_V(n) asm volatile("s_waitcnt vmcnt(" #n ")" ::: "memory")
; #define PG8_WAIT_L(n) asm volatile("s_waitcnt lgkmcnt(" #n ")" ::: "memory")
; #define PG8_BAR __builtin_amdgcn_s_barrier()
; #define PG8_SCHED __builtin_amdgcn_sched_barrier(0)
; template <class Epi, class Sched, bool ALIGN_EPI = false, bool SP2 = false>
; __device__ __forceinline__ void gemm_phase(PG8_LAS unsigned char* lds, const Gemm g, const Sched& S, const Epi& E, int tid_in) {
;     ...
;             PG8_LDB(B0, 0, 0); PG8_LDB(B1, 0, 1); PG8_SCHED; PG8_LDA(At, 0, 0); PG8_STAGE(PG8_SA(1, 1), a1 + hstepA, voffA);
;             PG8_WAIT_V(8); PG8_WAIT_L(0); PG8_BAR; PG8_MMA(0, 0, At, B0); PG8_MMA(0, 1, At, B1); PG8_BAR; PG8_SCHED;
;             PG8_LDA(At, 0, 1); PG8_STAGE(PG8_SB(0, 0), b2, voffB); PG8_STAGE(PG8_SB(0, 1), b2 + hstepB, voffB); PG8_STAGE(PG8_SA(0, 0), a2, voffA);
;             PG8_WAIT_V(8); PG8_WAIT_L(0); PG8_BAR; PG8_MMA(1, 0, At, B0); PG8_MMA(1, 1, At, B1); PG8_BAR; PG8_SCHED;
.LBB0_1265:
	v_add_u32_e32 v133, 0x10000, v131
	ds_read_b128 v[134:137], v133
	ds_read_b128 v[138:141], v133 offset:1024
	ds_read_b128 v[142:145], v133 offset:2048
	ds_read_b128 v[146:149], v133 offset:3072
	v_add_u32_e32 v133, 0x14000, v131
	ds_read_b128 v[150:153], v133
	ds_read_b128 v[154:157], v133 offset:1024
	ds_read_b128 v[158:161], v133 offset:2048
	ds_read_b128 v[166:169], v133 offset:3072
	s_add_i32 s42, s18, s44
	s_add_i32 s21, s14, s44
	s_add_i32 s79, s12, s44
	s_addk_i32 s42, 0xff80
	s_sub_i32 vcc_lo, s42, 0x80000
	s_cmp_eq_u32 s19, 28
	s_cselect_b32 s21, s15, s21
	s_mov_b32 m0, s75
	ds_read_b128 v[170:173], v132
	ds_read_b128 v[174:177], v132 offset:1024
	ds_read_b128 v[178:181], v132 offset:2048
	ds_read_b128 v[182:185], v132 offset:3072
	ds_read_b128 v[186:189], v132 offset:4096
	ds_read_b128 v[190:193], v132 offset:5120
	ds_read_b128 v[200:203], v132 offset:6144
	ds_read_b128 v[206:209], v132 offset:7168
	s_mov_b32 m0, s72
	s_nop 0
	buffer_load_dwordx4 v130, s[4:7], vcc_lo offen lds
	s_mov_b32 m0, s75
	s_nop 0
	buffer_load_dwordx4 v0, s[4:7], s42 offen lds
	s_mov_b32 m0, s76
	s_nop 0
	buffer_load_dwordx4 v130, s[4:7], s42 offen lds
	s_waitcnt vmcnt(8)
	s_waitcnt lgkmcnt(0)
	s_setprio 1
	s_barrier
	v_mfma_f32_16x16x32_bf16 v[34:37], v[134:137], v[170:173], v[34:37]
	v_mfma_f32_16x16x32_bf16 v[18:21], v[142:145], v[170:173], v[18:21]
	v_mfma_f32_16x16x32_bf16 v[78:81], v[142:145], v[178:181], v[78:81]
	v_mfma_f32_16x16x32_bf16 v[86:89], v[134:137], v[178:181], v[86:89]
	v_mfma_f32_16x16x32_bf16 v[106:109], v[134:137], v[186:189], v[106:109]
	v_mfma_f32_16x16x32_bf16 v[102:105], v[142:145], v[186:189], v[102:105]
	v_mfma_f32_16x16x32_bf16 v[122:125], v[142:145], v[200:203], v[122:125]
	v_mfma_f32_16x16x32_bf16 v[126:129], v[134:137], v[200:203], v[126:129]
	v_mfma_f32_16x16x32_bf16 v[34:37], v[138:141], v[174:177], v[34:37]
	v_mfma_f32_16x16x32_bf16 v[18:21], v[146:149], v[174:177], v[18:21]
	v_mfma_f32_16x16x32_bf16 v[78:81], v[146:149], v[182:185], v[78:81]
	v_mfma_f32_16x16x32_bf16 v[86:89], v[138:141], v[182:185], v[86:89]
	v_mfma_f32_16x16x32_bf16 v[106:109], v[138:141], v[190:193], v[106:109]
	v_mfma_f32_16x16x32_bf16 v[102:105], v[146:149], v[190:193], v[102:105]
	v_mfma_f32_16x16x32_bf16 v[122:125], v[146:149], v[206:209], v[122:125]
	v_mfma_f32_16x16x32_bf16 v[126:129], v[138:141], v[206:209], v[126:129]
	v_mfma_f32_16x16x32_bf16 v[14:17], v[150:153], v[170:173], v[14:17]
	v_mfma_f32_16x16x32_bf16 v[38:41], v[158:161], v[170:173], v[38:41]
	v_mfma_f32_16x16x32_bf16 v[90:93], v[158:161], v[178:181], v[90:93]
	v_mfma_f32_16x16x32_bf16 v[74:77], v[150:153], v[178:181], v[74:77]
	v_mfma_f32_16x16x32_bf16 v[98:101], v[150:153], v[186:189], v[98:101]
	v_mfma_f32_16x16x32_bf16 v[110:113], v[158:161], v[186:189], v[110:113]
	v_mfma_f32_16x16x32_bf16 v[114:117], v[158:161], v[200:203], v[114:117]
	v_mfma_f32_16x16x32_bf16 v[118:121], v[150:153], v[200:203], v[118:121]
	v_mfma_f32_16x16x32_bf16 v[14:17], v[154:157], v[174:177], v[14:17]
	v_mfma_f32_16x16x32_bf16 v[38:41], v[166:169], v[174:177], v[38:41]
	v_mfma_f32_16x16x32_bf16 v[90:93], v[166:169], v[182:185], v[90:93]
	v_mfma_f32_16x16x32_bf16 v[74:77], v[154:157], v[182:185], v[74:77]
	v_mfma_f32_16x16x32_bf16 v[98:101], v[154:157], v[190:193], v[98:101]
	v_mfma_f32_16x16x32_bf16 v[110:113], v[166:169], v[190:193], v[110:113]
	v_mfma_f32_16x16x32_bf16 v[114:117], v[166:169], v[206:209], v[114:117]
	v_mfma_f32_16x16x32_bf16 v[118:121], v[154:157], v[206:209], v[118:121]
	s_barrier
	s_setprio 0
	s_cselect_b32 s79, s17, s79
	s_mov_b32 m0, s49
	s_mov_b32 s42, s6
	s_mov_b32 s43, s7
	s_sub_i32 s79, s79, s40
	buffer_load_dwordx4 v0, s[40:43], s79 offen lds
	s_mov_b32 m0, s60
	s_add_i32 vcc_lo, s79, 0x80000
	buffer_load_dwordx4 v130, s[40:43], s79 offen lds
	ds_read_b128 v[170:173], v132 offset:16384
	ds_read_b128 v[174:177], v132 offset:17408
	ds_read_b128 v[178:181], v132 offset:18432
	ds_read_b128 v[182:185], v132 offset:19456
	ds_read_b128 v[186:189], v132 offset:20480
	ds_read_b128 v[190:193], v132 offset:21504
	ds_read_b128 v[200:203], v132 offset:22528
	ds_read_b128 v[206:209], v132 offset:23552
	s_mov_b32 m0, s61
	s_sub_i32 s21, s21, s4
	buffer_load_dwordx4 v0, s[40:43], vcc_lo offen lds
	s_mov_b32 m0, s62
	s_nop 0
	buffer_load_dwordx4 v130, s[40:43], vcc_lo offen lds
	s_mov_b32 m0, s35
	s_nop 0
	buffer_load_dwordx4 v0, s[4:7], s21 offen lds
	s_waitcnt vmcnt(7)
	s_waitcnt lgkmcnt(0)
	s_setprio 1
	s_barrier
	v_mfma_f32_16x16x32_bf16 v[50:53], v[134:137], v[170:173], v[50:53]
	v_mfma_f32_16x16x32_bf16 v[30:33], v[142:145], v[170:173], v[30:33]
	v_mfma_f32_16x16x32_bf16 v[58:61], v[142:145], v[178:181], v[58:61]
	v_mfma_f32_16x16x32_bf16 v[62:65], v[134:137], v[178:181], v[62:65]
	v_mfma_f32_16x16x32_bf16 v[94:97], v[134:137], v[186:189], v[94:97]
	v_mfma_f32_16x16x32_bf16 v[82:85], v[142:145], v[186:189], v[82:85]
	v_mfma_f32_16x16x32_bf16 v[26:29], v[142:145], v[200:203], v[26:29]
	v_mfma_f32_16x16x32_bf16 v[46:49], v[134:137], v[200:203], v[46:49]
	v_mfma_f32_16x16x32_bf16 v[50:53], v[138:141], v[174:177], v[50:53]
	v_mfma_f32_16x16x32_bf16 v[30:33], v[146:149], v[174:177], v[30:33]
	v_mfma_f32_16x16x32_bf16 v[58:61], v[146:149], v[182:185], v[58:61]
	v_mfma_f32_16x16x32_bf16 v[62:65], v[138:141], v[182:185], v[62:65]
	v_mfma_f32_16x16x32_bf16 v[94:97], v[138:141], v[190:193], v[94:97]
	v_mfma_f32_16x16x32_bf16 v[82:85], v[146:149], v[190:193], v[82:85]
	v_mfma_f32_16x16x32_bf16 v[26:29], v[146:149], v[206:209], v[26:29]
	v_mfma_f32_16x16x32_bf16 v[46:49], v[138:141], v[206:209], v[46:49]
	v_mfma_f32_16x16x32_bf16 v[22:25], v[150:153], v[170:173], v[22:25]
	v_mfma_f32_16x16x32_bf16 v[10:13], v[158:161], v[170:173], v[10:13]
	v_mfma_f32_16x16x32_bf16 v[66:69], v[158:161], v[178:181], v[66:69]
	v_mfma_f32_16x16x32_bf16 v[54:57], v[150:153], v[178:181], v[54:57]
	v_mfma_f32_16x16x32_bf16 v[70:73], v[150:153], v[186:189], v[70:73]
	v_mfma_f32_16x16x32_bf16 v[42:45], v[158:161], v[186:189], v[42:45]
	v_mfma_f32_16x16x32_bf16 v[2:5], v[158:161], v[200:203], v[2:5]
	v_mfma_f32_16x16x32_bf16 v[6:9], v[150:153], v[200:203], v[6:9]
	v_mfma_f32_16x16x32_bf16 v[22:25], v[154:157], v[174:177], v[22:25]
	v_mfma_f32_16x16x32_bf16 v[10:13], v[166:169], v[174:177], v[10:13]
	v_mfma_f32_16x16x32_bf16 v[66:69], v[166:169], v[182:185], v[66:69]
	v_mfma_f32_16x16x32_bf16 v[54:57], v[154:157], v[182:185], v[54:57]
	v_mfma_f32_16x16x32_bf16 v[70:73], v[154:157], v[190:193], v[70:73]
	v_mfma_f32_16x16x32_bf16 v[42:45], v[166:169], v[190:193], v[42:45]
	v_mfma_f32_16x16x32_bf16 v[2:5], v[166:169], v[206:209], v[2:5]
	v_mfma_f32_16x16x32_bf16 v[6:9], v[154:157], v[206:209], v[6:9]
	s_barrier
; #define PG8_STAGE(bufoff, gbase, voff) do { const int so_ = (int)(unsigned)((const char*)(gbase) - base_##voff); _Pragma("unroll") for (int _i = 0; _i < 2; ++_i) \
;         __builtin_amdgcn_raw_ptr_buffer_load_lds(rs_##voff, (PG8_LAS unsigned*)(lds + (bufoff) + ldsw + _i * 8192), 16, (int)(voff)[_i], so_, 0, 0); } while (0)
; #define PG8_LDA(dst, b, h) do { _Pragma("unroll") for (int m = 0; m < 4; ++m) _Pragma("unroll") for (int k = 0; k < 2; ++k) dst[m][k] = *(const PG8_LAS bf16x8*)(lds + PG8_SA(b, h) + aoff + m * 2048 + k * 1024); } while (0)
; #define PG8_LDB(dst, b, h) do { _Pragma("unroll") for (int n = 0; n < 2; ++n) _Pragma("unroll") for (int k = 0; k < 2; ++k) dst[n][k] = *(const PG8_LAS bf16x8*)(lds + PG8_SB(b, h) + boff + n * 2048 + k * 1024); } while (0)
; #define PG8_MMA(ai, bj, At, Bt) do { __builtin_amdgcn_s_setprio(1); _Pragma("unroll") for (int m = 0; m < 4; ++m) _Pragma("unroll") for (int n = 0; n < 2; ++n) _Pragma("unroll") for (int k = 0; k < 2; ++k) \
;         acc[ai][bj][m][n] = __builtin_amdgcn_mfma_f32_16x16x32_bf16(Bt[n][k], At[m][k], acc[ai][bj][m][n], 0, 0, 0); __builtin_amdgcn_s_setprio(0); } while (0)
; #define PG8_WAIT_V(n) asm volatile("s_waitcnt vmcnt(" #n ")" ::: "memory")
; #define PG8_WAIT_L(n) asm volatile("s_waitcnt lgkmcnt(" #n ")" ::: "memory")
; #define PG8_BAR __builtin_amdgcn_s_barrier()
; #define PG8_SCHED __builtin_amdgcn_sched_barrier(0)
; template <class Epi, class Sched, bool ALIGN_EPI = false, bool SP2 = false>
; __device__ __forceinline__ void gemm_phase(PG8_LAS unsigned char* lds, const Gemm g, const Sched& S, const Epi& E, int tid_in) {
;     ...
;             PG8_LDB(B0, 1, 0); PG8_LDB(B1, 1, 1); PG8_SCHED; PG8_LDA(At, 1, 0); PG8_STAGE(PG8_SA(0, 1), a2 + hstepA, voffA);
;             PG8_WAIT_V(8); PG8_WAIT_L(0); PG8_BAR; PG8_MMA(0, 0, At, B0); PG8_MMA(0, 1, At, B1); PG8_BAR; PG8_SCHED;
;             PG8_LDA(At, 1, 1); PG8_STAGE(PG8_SB(1, 0), b3, voffB); PG8_STAGE(PG8_SB(1, 1), b3 + hstepB, voffB); PG8_STAGE(PG8_SA(1, 0), a3, voffA);
;             PG8_WAIT_V(8); PG8_WAIT_L(0); PG8_BAR; PG8_MMA(1, 0, At, B0); PG8_MMA(1, 1, At, B1); PG8_BAR; PG8_SCHED;
	s_setprio 0
	v_add_u32_e32 v133, 0x18000, v131
	ds_read_b128 v[134:137], v133
	ds_read_b128 v[138:141], v133 offset:1024
	ds_read_b128 v[142:145], v133 offset:2048
	ds_read_b128 v[146:149], v133 offset:3072
	v_add_u32_e32 v133, 0x1c000, v131
	ds_read_b128 v[150:153], v133
	ds_read_b128 v[154:157], v133 offset:1024
	ds_read_b128 v[158:161], v133 offset:2048
	ds_read_b128 v[166:169], v133 offset:3072
	s_add_i32 vcc_lo, s21, 0x80000
	s_mov_b32 m0, s66
	ds_read_b128 v[170:173], v132 offset:32768
	ds_read_b128 v[174:177], v132 offset:33792
	ds_read_b128 v[178:181], v132 offset:34816
	ds_read_b128 v[182:185], v132 offset:35840
	ds_read_b128 v[186:189], v132 offset:36864
	ds_read_b128 v[190:193], v132 offset:37888
	ds_read_b128 v[200:203], v132 offset:38912
	ds_read_b128 v[206:209], v132 offset:39936
	s_mov_b32 m0, s63
	s_nop 0
	buffer_load_dwordx4 v130, s[4:7], s21 offen lds
	s_mov_b32 m0, s66
	s_nop 0
	buffer_load_dwordx4 v0, s[4:7], vcc_lo offen lds
	s_mov_b32 m0, s67
	s_nop 0
	buffer_load_dwordx4 v130, s[4:7], vcc_lo offen lds
	s_waitcnt vmcnt(8)
	s_waitcnt lgkmcnt(0)
	s_setprio 1
	s_barrier
	v_mfma_f32_16x16x32_bf16 v[34:37], v[134:137], v[170:173], v[34:37]
	v_mfma_f32_16x16x32_bf16 v[18:21], v[142:145], v[170:173], v[18:21]
	v_mfma_f32_16x16x32_bf16 v[78:81], v[142:145], v[178:181], v[78:81]
	v_mfma_f32_16x16x32_bf16 v[86:89], v[134:137], v[178:181], v[86:89]
	v_mfma_f32_16x16x32_bf16 v[106:109], v[134:137], v[186:189], v[106:109]
	v_mfma_f32_16x16x32_bf16 v[102:105], v[142:145], v[186:189], v[102:105]
	v_mfma_f32_16x16x32_bf16 v[122:125], v[142:145], v[200:203], v[122:125]
	v_mfma_f32_16x16x32_bf16 v[126:129], v[134:137], v[200:203], v[126:129]
	v_mfma_f32_16x16x32_bf16 v[34:37], v[138:141], v[174:177], v[34:37]
	v_mfma_f32_16x16x32_bf16 v[18:21], v[146:149], v[174:177], v[18:21]
	v_mfma_f32_16x16x32_bf16 v[78:81], v[146:149], v[182:185], v[78:81]
	v_mfma_f32_16x16x32_bf16 v[86:89], v[138:141], v[182:185], v[86:89]
	v_mfma_f32_16x16x32_bf16 v[106:109], v[138:141], v[190:193], v[106:109]
	v_mfma_f32_16x16x32_bf16 v[102:105], v[146:149], v[190:193], v[102:105]
	v_mfma_f32_16x16x32_bf16 v[122:125], v[146:149], v[206:209], v[122:125]
	v_mfma_f32_16x16x32_bf16 v[126:129], v[138:141], v[206:209], v[126:129]
	v_mfma_f32_16x16x32_bf16 v[14:17], v[150:153], v[170:173], v[14:17]
	v_mfma_f32_16x16x32_bf16 v[38:41], v[158:161], v[170:173], v[38:41]
	v_mfma_f32_16x16x32_bf16 v[90:93], v[158:161], v[178:181], v[90:93]
	v_mfma_f32_16x16x32_bf16 v[74:77], v[150:153], v[178:181], v[74:77]
	v_mfma_f32_16x16x32_bf16 v[98:101], v[150:153], v[186:189], v[98:101]
	v_mfma_f32_16x16x32_bf16 v[110:113], v[158:161], v[186:189], v[110:113]
	v_mfma_f32_16x16x32_bf16 v[114:117], v[158:161], v[200:203], v[114:117]
	v_mfma_f32_16x16x32_bf16 v[118:121], v[150:153], v[200:203], v[118:121]
	v_mfma_f32_16x16x32_bf16 v[14:17], v[154:157], v[174:177], v[14:17]
	v_mfma_f32_16x16x32_bf16 v[38:41], v[166:169], v[174:177], v[38:41]
	v_mfma_f32_16x16x32_bf16 v[90:93], v[166:169], v[182:185], v[90:93]
	v_mfma_f32_16x16x32_bf16 v[74:77], v[154:157], v[182:185], v[74:77]
	v_mfma_f32_16x16x32_bf16 v[98:101], v[154:157], v[190:193], v[98:101]
	v_mfma_f32_16x16x32_bf16 v[110:113], v[166:169], v[190:193], v[110:113]
	v_mfma_f32_16x16x32_bf16 v[114:117], v[166:169], v[206:209], v[114:117]
	v_mfma_f32_16x16x32_bf16 v[118:121], v[154:157], v[206:209], v[118:121]
	s_barrier
	s_setprio 0
	s_mov_b32 m0, s68
	s_add_i32 vcc_lo, s79, 0x80
	buffer_load_dwordx4 v0, s[40:43], vcc_lo offen lds
	s_mov_b32 m0, s69
	s_add_i32 s79, s79, 0x80080
	buffer_load_dwordx4 v130, s[40:43], vcc_lo offen lds
	ds_read_b128 v[170:173], v132 offset:49152
	ds_read_b128 v[174:177], v132 offset:50176
	ds_read_b128 v[178:181], v132 offset:51200
	ds_read_b128 v[182:185], v132 offset:52224
	ds_read_b128 v[186:189], v132 offset:53248
	ds_read_b128 v[190:193], v132 offset:54272
	ds_read_b128 v[200:203], v132 offset:55296
	ds_read_b128 v[206:209], v132 offset:56320
	s_mov_b32 m0, s73
	s_addk_i32 s21, 0x80
	buffer_load_dwordx4 v0, s[40:43], s79 offen lds
	s_mov_b32 m0, s74
	s_nop 0
	buffer_load_dwordx4 v130, s[40:43], s79 offen lds
	s_mov_b32 m0, s71
	s_nop 0
	buffer_load_dwordx4 v0, s[4:7], s21 offen lds
	s_waitcnt vmcnt(7)
	s_waitcnt lgkmcnt(0)
	s_setprio 1
	s_barrier
;     static __device__ __forceinline__ bool last_of_chain(const Unit& u) { return (u.pn >> 3) == 2; }
; #define PG8_STAGE(bufoff, gbase, voff) do { const int so_ = (int)(unsigned)((const char*)(gbase) - base_##voff); _Pragma("unroll") for (int _i = 0; _i < 2; ++_i) \
;         __builtin_amdgcn_raw_ptr_buffer_load_lds(rs_##voff, (PG8_LAS unsigned*)(lds + (bufoff) + ldsw + _i * 8192), 16, (int)(voff)[_i], so_, 0, 0); } while (0)
; #define PG8_LDA(dst, b, h) do { _Pragma("unroll") for (int m = 0; m < 4; ++m) _Pragma("unroll") for (int k = 0; k < 2; ++k) dst[m][k] = *(const PG8_LAS bf16x8*)(lds + PG8_SA(b, h) + aoff + m * 2048 + k * 1024); } while (0)
; #define PG8_MMA(ai, bj, At, Bt) do { __builtin_amdgcn_s_setprio(1); _Pragma("unroll") for (int m = 0; m < 4; ++m) _Pragma("unroll") for (int n = 0; n < 2; ++n) _Pragma("unroll") for (int k = 0; k < 2; ++k) \
;         acc[ai][bj][m][n] = __builtin_amdgcn_mfma_f32_16x16x32_bf16(Bt[n][k], At[m][k], acc[ai][bj][m][n], 0, 0, 0); __builtin_amdgcn_s_setprio(0); } while (0)
; #define PG8_WAIT_V(n) asm volatile("s_waitcnt vmcnt(" #n ")" ::: "memory")
; #define PG8_WAIT_L(n) asm volatile("s_waitcnt lgkmcnt(" #n ")" ::: "memory")
; #define PG8_BAR __builtin_amdgcn_s_barrier()
; #define PG8_SCHED __builtin_amdgcn_sched_barrier(0)
; template <class Epi, class Sched, bool ALIGN_EPI = false, bool SP2 = false>
; __device__ __forceinline__ void gemm_phase(PG8_LAS unsigned char* lds, const Gemm g, const Sched& S, const Epi& E, int tid_in) {
;     ...
;             PG8_WAIT_V(8); PG8_WAIT_L(0); PG8_BAR; PG8_MMA(0, 0, At, B0); PG8_MMA(0, 1, At, B1); PG8_BAR; PG8_SCHED;
;             PG8_LDA(At, 1, 1); PG8_STAGE(PG8_SB(1, 0), b3, voffB); PG8_STAGE(PG8_SB(1, 1), b3 + hstepB, voffB); PG8_STAGE(PG8_SA(1, 0), a3, voffA);
;             PG8_WAIT_V(8); PG8_WAIT_L(0); PG8_BAR; PG8_MMA(1, 0, At, B0); PG8_MMA(1, 1, At, B1); PG8_BAR; PG8_SCHED;
;     ...
;         bool zero_acc = true; if constexpr (Epi::CHAIN) zero_acc = Epi::last_of_chain(cur);
;         if (zero_acc) {
; #pragma unroll
;         for (int a = 0; a < 2; ++a)
; #pragma unroll
;             for (int b = 0; b < 2; ++b)
; #pragma unroll
;                 for (int m = 0; m < 4; ++m)
; #pragma unroll
;                     for (int n = 0; n < 2; ++n) acc[a][b][m][n] = (f32x4){0.f, 0.f, 0.f, 0.f};
;         }
;         cur = nxt; cA = nA; cB = nB; ++ui;
	v_mfma_f32_16x16x32_bf16 v[50:53], v[134:137], v[170:173], v[50:53]
	v_mfma_f32_16x16x32_bf16 v[30:33], v[142:145], v[170:173], v[30:33]
	v_mfma_f32_16x16x32_bf16 v[58:61], v[142:145], v[178:181], v[58:61]
	v_mfma_f32_16x16x32_bf16 v[62:65], v[134:137], v[178:181], v[62:65]
	v_mfma_f32_16x16x32_bf16 v[94:97], v[134:137], v[186:189], v[94:97]
	v_mfma_f32_16x16x32_bf16 v[82:85], v[142:145], v[186:189], v[82:85]
	v_mfma_f32_16x16x32_bf16 v[26:29], v[142:145], v[200:203], v[26:29]
	v_mfma_f32_16x16x32_bf16 v[46:49], v[134:137], v[200:203], v[46:49]
	v_mfma_f32_16x16x32_bf16 v[50:53], v[138:141], v[174:177], v[50:53]
	v_mfma_f32_16x16x32_bf16 v[30:33], v[146:149], v[174:177], v[30:33]
	v_mfma_f32_16x16x32_bf16 v[58:61], v[146:149], v[182:185], v[58:61]
	v_mfma_f32_16x16x32_bf16 v[62:65], v[138:141], v[182:185], v[62:65]
	v_mfma_f32_16x16x32_bf16 v[94:97], v[138:141], v[190:193], v[94:97]
	v_mfma_f32_16x16x32_bf16 v[82:85], v[146:149], v[190:193], v[82:85]
	v_mfma_f32_16x16x32_bf16 v[26:29], v[146:149], v[206:209], v[26:29]
	v_mfma_f32_16x16x32_bf16 v[46:49], v[138:141], v[206:209], v[46:49]
	v_mfma_f32_16x16x32_bf16 v[22:25], v[150:153], v[170:173], v[22:25]
	v_mfma_f32_16x16x32_bf16 v[10:13], v[158:161], v[170:173], v[10:13]
	v_mfma_f32_16x16x32_bf16 v[66:69], v[158:161], v[178:181], v[66:69]
	v_mfma_f32_16x16x32_bf16 v[54:57], v[150:153], v[178:181], v[54:57]
	v_mfma_f32_16x16x32_bf16 v[70:73], v[150:153], v[186:189], v[70:73]
	v_mfma_f32_16x16x32_bf16 v[42:45], v[158:161], v[186:189], v[42:45]
	v_mfma_f32_16x16x32_bf16 v[2:5], v[158:161], v[200:203], v[2:5]
	v_mfma_f32_16x16x32_bf16 v[6:9], v[150:153], v[200:203], v[6:9]
	v_mfma_f32_16x16x32_bf16 v[22:25], v[154:157], v[174:177], v[22:25]
	v_mfma_f32_16x16x32_bf16 v[10:13], v[166:169], v[174:177], v[10:13]
	v_mfma_f32_16x16x32_bf16 v[66:69], v[166:169], v[182:185], v[66:69]
	v_mfma_f32_16x16x32_bf16 v[54:57], v[154:157], v[182:185], v[54:57]
	v_mfma_f32_16x16x32_bf16 v[70:73], v[154:157], v[190:193], v[70:73]
	v_mfma_f32_16x16x32_bf16 v[42:45], v[166:169], v[190:193], v[42:45]
	v_mfma_f32_16x16x32_bf16 v[2:5], v[166:169], v[206:209], v[2:5]
	v_mfma_f32_16x16x32_bf16 v[6:9], v[154:157], v[206:209], v[6:9]
	s_barrier
	s_setprio 0
	s_add_i32 s19, s19, 2
	s_add_u32 s44, s44, 0x100
	s_addc_u32 s45, s45, 0
	s_cmp_gt_u32 s19, 29
	s_cbranch_scc0 .LBB0_1265
	s_andn2_b64 vcc, exec, s[38:39]
	s_cbranch_vccnz .LBB0_1257
	v_mov_b32_e32 v2, 0
	s_mov_b64 s[12:13], s[24:25]
	s_mov_b32 s10, s16
	s_mov_b32 s48, s20
	s_mov_b64 s[14:15], s[22:23]
	s_mov_b32 s13, s78
	v_mov_b32_e32 v3, v2
	v_mov_b32_e32 v4, v2
	v_mov_b32_e32 v5, v2
	v_mov_b32_e32 v6, v2
	v_mov_b32_e32 v7, v2
	v_mov_b32_e32 v8, v2
	v_mov_b32_e32 v9, v2
	v_mov_b32_e32 v42, v2
	v_mov_b32_e32 v43, v2
	v_mov_b32_e32 v44, v2
	v_mov_b32_e32 v45, v2
	v_mov_b32_e32 v70, v2
	v_mov_b32_e32 v71, v2
	v_mov_b32_e32 v72, v2
	v_mov_b32_e32 v73, v2
	v_mov_b32_e32 v66, v2
	v_mov_b32_e32 v67, v2
	v_mov_b32_e32 v68, v2
	v_mov_b32_e32 v69, v2
	v_mov_b32_e32 v54, v2
	v_mov_b32_e32 v55, v2
	v_mov_b32_e32 v56, v2
	v_mov_b32_e32 v57, v2
	v_mov_b32_e32 v10, v2
	v_mov_b32_e32 v11, v2
	v_mov_b32_e32 v12, v2
	v_mov_b32_e32 v13, v2
	v_mov_b32_e32 v22, v2
	v_mov_b32_e32 v23, v2
	v_mov_b32_e32 v24, v2
	v_mov_b32_e32 v25, v2
	v_mov_b32_e32 v26, v2
	v_mov_b32_e32 v27, v2
	v_mov_b32_e32 v28, v2
	v_mov_b32_e32 v29, v2
	v_mov_b32_e32 v46, v2
	v_mov_b32_e32 v47, v2
	v_mov_b32_e32 v48, v2
	v_mov_b32_e32 v49, v2
	v_mov_b32_e32 v82, v2
	v_mov_b32_e32 v83, v2
	v_mov_b32_e32 v84, v2
	v_mov_b32_e32 v85, v2
	v_mov_b32_e32 v94, v2
	v_mov_b32_e32 v95, v2
	v_mov_b32_e32 v96, v2
	v_mov_b32_e32 v97, v2
	v_mov_b32_e32 v58, v2
	v_mov_b32_e32 v59, v2
	v_mov_b32_e32 v60, v2
	v_mov_b32_e32 v61, v2
	v_mov_b32_e32 v62, v2
	v_mov_b32_e32 v63, v2
	v_mov_b32_e32 v64, v2
	v_mov_b32_e32 v65, v2
	v_mov_b32_e32 v30, v2
	v_mov_b32_e32 v31, v2
	v_mov_b32_e32 v32, v2
	v_mov_b32_e32 v33, v2
	v_mov_b32_e32 v50, v2
	v_mov_b32_e32 v51, v2
	v_mov_b32_e32 v52, v2
	v_mov_b32_e32 v53, v2
	v_mov_b32_e32 v114, v2
	v_mov_b32_e32 v115, v2
	v_mov_b32_e32 v116, v2
	v_mov_b32_e32 v117, v2
	v_mov_b32_e32 v118, v2
	v_mov_b32_e32 v119, v2
	v_mov_b32_e32 v120, v2
	v_mov_b32_e32 v121, v2
	v_mov_b32_e32 v110, v2
	v_mov_b32_e32 v111, v2
	v_mov_b32_e32 v112, v2
	v_mov_b32_e32 v113, v2
	v_mov_b32_e32 v98, v2
	v_mov_b32_e32 v99, v2
	v_mov_b32_e32 v100, v2
	v_mov_b32_e32 v101, v2
	v_mov_b32_e32 v90, v2
	v_mov_b32_e32 v91, v2
	v_mov_b32_e32 v92, v2
	v_mov_b32_e32 v93, v2
	v_mov_b32_e32 v74, v2
	v_mov_b32_e32 v75, v2
	v_mov_b32_e32 v76, v2
	v_mov_b32_e32 v77, v2
	v_mov_b32_e32 v38, v2
	v_mov_b32_e32 v39, v2
	v_mov_b32_e32 v40, v2
	v_mov_b32_e32 v41, v2
	v_mov_b32_e32 v14, v2
	v_mov_b32_e32 v15, v2
	v_mov_b32_e32 v16, v2
	v_mov_b32_e32 v17, v2
	v_mov_b32_e32 v122, v2
	v_mov_b32_e32 v123, v2
	v_mov_b32_e32 v124, v2
	v_mov_b32_e32 v125, v2
	v_mov_b32_e32 v126, v2
	v_mov_b32_e32 v127, v2
	v_mov_b32_e32 v128, v2
	v_mov_b32_e32 v129, v2
	v_mov_b32_e32 v102, v2
	v_mov_b32_e32 v103, v2
	v_mov_b32_e32 v104, v2
	v_mov_b32_e32 v105, v2
	v_mov_b32_e32 v106, v2
	v_mov_b32_e32 v107, v2
	v_mov_b32_e32 v108, v2
	v_mov_b32_e32 v109, v2
	v_mov_b32_e32 v78, v2
	v_mov_b32_e32 v79, v2
	v_mov_b32_e32 v80, v2
	v_mov_b32_e32 v81, v2
	v_mov_b32_e32 v86, v2
	v_mov_b32_e32 v87, v2
	v_mov_b32_e32 v88, v2
	v_mov_b32_e32 v89, v2
	v_mov_b32_e32 v18, v2
	v_mov_b32_e32 v19, v2
	v_mov_b32_e32 v20, v2
	v_mov_b32_e32 v21, v2
	v_mov_b32_e32 v34, v2
	v_mov_b32_e32 v35, v2
	v_mov_b32_e32 v36, v2
	v_mov_b32_e32 v37, v2
	s_branch .LBB0_1257

;     __host__ __device__ bool next(int i, Unit& u) const { const int t = i / 3, b = i - 3 * t; Unit v; if (!StaticOrder::next(t, v)) return false; u.pm = v.pm; u.pn = 8 * b + v.pn; return true; }
; #define PG8_STAGE(bufoff, gbase, voff) do { const int so_ = (int)(unsigned)((const char*)(gbase) - base_##voff); _Pragma("unroll") for (int _i = 0; _i < 2; ++_i) \
;         __builtin_amdgcn_raw_ptr_buffer_load_lds(rs_##voff, (PG8_LAS unsigned*)(lds + (bufoff) + ldsw + _i * 8192), 16, (int)(voff)[_i], so_, 0, 0); } while (0)
; #define PG8_LDA(dst, b, h) do { _Pragma("unroll") for (int m = 0; m < 4; ++m) _Pragma("unroll") for (int k = 0; k < 2; ++k) dst[m][k] = *(const PG8_LAS bf16x8*)(lds + PG8_SA(b, h) + aoff + m * 2048 + k * 1024); } while (0)
; #define PG8_WAIT_V(n) asm volatile("s_waitcnt vmcnt(" #n ")" ::: "memory")
; #define PG8_WAIT_L(n) asm volatile("s_waitcnt lgkmcnt(" #n ")" ::: "memory")
; #define PG8_BAR __builtin_amdgcn_s_barrier()
; template <class Epi, class Sched, bool ALIGN_EPI = false, bool SP2 = false>
; __device__ __forceinline__ void gemm_phase(PG8_LAS unsigned char* lds, const Gemm g, const Sched& S, const Epi& E, int tid_in) {
;     ...
;         const bool has_next = S.next(ui + 1, nxt);
;         const char* nA = has_next ? (const char*)g.A + (size_t)nxt.pm * tstepA + (g.grp ? (size_t)(nxt.pn / g.grp) * g.agrp : (size_t)0) : cA; const char* nB = has_next ? (const char*)g.Bt + (size_t)nxt.pn * tstepB : cB;
;         for (int t = 0; t < nt; t += 2) {
;             const bool last = (t == nt - 2);
;             const char* a1 = cA + (size_t)(t + 1) * kstep;
;             const char* a2 = last ? nA : cA + (size_t)(t + 2) * kstep; const char* b2 = last ? nB : cB + (size_t)(t + 2) * kstep;
;             const char* a3 = a2 + kstep; const char* b3 = b2 + kstep;
;             if (last && has_next) S.a_ready(nxt);
;             if constexpr (SP2) {
;             PG8_LDB(B0, 0, 0); PG8_LDB(B1, 0, 1); PG8_SCHED; PG8_LDA(At, 0, 0); PG8_STAGE(PG8_SA(1, 1), a1 + hstepA, voffA);
;             PG8_WAIT_V(8); PG8_WAIT_L(0); PG8_BAR; PG8_MMA(0, 0, At, B0); PG8_MMA(0, 1, At, B1); PG8_BAR; PG8_SCHED;
;             PG8_LDA(At, 0, 1); PG8_STAGE(PG8_SB(0, 0), b2, voffB); PG8_STAGE(PG8_SB(0, 1), b2 + hstepB, voffB); PG8_STAGE(PG8_SA(0, 0), a2, voffA);
;             PG8_WAIT_V(8); PG8_WAIT_L(0); PG8_BAR; PG8_MMA(1, 0, At, B0); PG8_MMA(1, 1, At, B1); PG8_BAR; PG8_SCHED;
.LBB0_1513:
	s_ashr_i32 s21, s20, 31
	s_lshl_b64 s[18:19], s[20:21], 20
	s_add_u32 s22, s4, s18
	s_addc_u32 s23, s9, s19
	s_and_b64 s[18:19], s[36:37], exec
	s_cselect_b32 s18, s22, s16
	s_ashr_i32 s15, s14, 31
	s_lshl_b64 s[24:25], s[14:15], 20
	s_add_u32 s24, s40, s24
	s_addc_u32 s25, s26, s25
	s_and_b64 s[42:43], s[36:37], exec
	s_cselect_b32 s15, s24, s38
	s_add_u32 s19, s38, 0x100
	v_mov_b32_e32 v2, 0
	s_addc_u32 s21, s39, 0
	s_mov_b32 s73, -2
	v_add_u32_e32 v141, 0x10000, v139
	ds_read_b128 v[130:133], v141
	ds_read_b128 v[142:145], v141 offset:1024
	ds_read_b128 v[146:149], v141 offset:2048
	ds_read_b128 v[150:153], v141 offset:3072
	v_add_u32_e32 v141, 0x14000, v139
	ds_read_b128 v[154:157], v141
	ds_read_b128 v[158:161], v141 offset:1024
	ds_read_b128 v[162:165], v141 offset:2048
	ds_read_b128 v[166:169], v141 offset:3072
	s_add_u32 s38, s16, 0x100
	s_addc_u32 s39, s17, 0
	s_sub_i32 s16, s16, s4
	s_add_i32 s16, s16, 0x80080
	s_sub_i32 s74, s16, 0x80000
	s_cmp_eq_u32 s73, 28
	s_cselect_b32 s17, s18, s38
	s_mov_b32 m0, s67
	ds_read_b128 v[170:173], v140
	ds_read_b128 v[174:177], v140 offset:1024
	ds_read_b128 v[178:181], v140 offset:2048
	ds_read_b128 v[182:185], v140 offset:3072
	ds_read_b128 v[186:189], v140 offset:4096
	ds_read_b128 v[190:193], v140 offset:5120
	ds_read_b128 v[200:203], v140 offset:6144
	ds_read_b128 v[206:209], v140 offset:7168
	s_mov_b32 m0, s62
	s_nop 0
	buffer_load_dwordx4 v135, s[4:7], s74 offen lds
	s_mov_b32 m0, s67
	s_nop 0
	buffer_load_dwordx4 v0, s[4:7], s16 offen lds
	s_mov_b32 m0, s68
	s_nop 0
	buffer_load_dwordx4 v135, s[4:7], s16 offen lds
	s_waitcnt vmcnt(8)
	s_waitcnt lgkmcnt(0)
	s_setprio 1
	s_barrier
	v_mfma_f32_16x16x32_bf16 v[126:129], v[130:133], v[170:173], 0
	v_mfma_f32_16x16x32_bf16 v[122:125], v[146:149], v[170:173], 0
	v_mfma_f32_16x16x32_bf16 v[106:109], v[146:149], v[178:181], 0
	v_mfma_f32_16x16x32_bf16 v[110:113], v[130:133], v[178:181], 0
	v_mfma_f32_16x16x32_bf16 v[94:97], v[130:133], v[186:189], 0
	v_mfma_f32_16x16x32_bf16 v[90:93], v[146:149], v[186:189], 0
	v_mfma_f32_16x16x32_bf16 v[74:77], v[146:149], v[200:203], 0
	v_mfma_f32_16x16x32_bf16 v[78:81], v[130:133], v[200:203], 0
	v_mfma_f32_16x16x32_bf16 v[126:129], v[142:145], v[174:177], v[126:129]
	v_mfma_f32_16x16x32_bf16 v[122:125], v[150:153], v[174:177], v[122:125]
	v_mfma_f32_16x16x32_bf16 v[106:109], v[150:153], v[182:185], v[106:109]
	v_mfma_f32_16x16x32_bf16 v[110:113], v[142:145], v[182:185], v[110:113]
	v_mfma_f32_16x16x32_bf16 v[94:97], v[142:145], v[190:193], v[94:97]
	v_mfma_f32_16x16x32_bf16 v[90:93], v[150:153], v[190:193], v[90:93]
	v_mfma_f32_16x16x32_bf16 v[74:77], v[150:153], v[206:209], v[74:77]
	v_mfma_f32_16x16x32_bf16 v[78:81], v[142:145], v[206:209], v[78:81]
	v_mfma_f32_16x16x32_bf16 v[118:121], v[154:157], v[170:173], 0
	v_mfma_f32_16x16x32_bf16 v[114:117], v[162:165], v[170:173], 0
	v_mfma_f32_16x16x32_bf16 v[98:101], v[162:165], v[178:181], 0
	v_mfma_f32_16x16x32_bf16 v[102:105], v[154:157], v[178:181], 0
	v_mfma_f32_16x16x32_bf16 v[86:89], v[154:157], v[186:189], 0
	v_mfma_f32_16x16x32_bf16 v[82:85], v[162:165], v[186:189], 0
	v_mfma_f32_16x16x32_bf16 v[66:69], v[162:165], v[200:203], 0
	v_mfma_f32_16x16x32_bf16 v[70:73], v[154:157], v[200:203], 0
	v_mfma_f32_16x16x32_bf16 v[118:121], v[158:161], v[174:177], v[118:121]
	v_mfma_f32_16x16x32_bf16 v[114:117], v[166:169], v[174:177], v[114:117]
	v_mfma_f32_16x16x32_bf16 v[98:101], v[166:169], v[182:185], v[98:101]
	v_mfma_f32_16x16x32_bf16 v[102:105], v[158:161], v[182:185], v[102:105]
	v_mfma_f32_16x16x32_bf16 v[86:89], v[158:161], v[190:193], v[86:89]
	v_mfma_f32_16x16x32_bf16 v[82:85], v[166:169], v[190:193], v[82:85]
	v_mfma_f32_16x16x32_bf16 v[66:69], v[166:169], v[206:209], v[66:69]
	v_mfma_f32_16x16x32_bf16 v[70:73], v[158:161], v[206:209], v[70:73]
	s_barrier
	s_setprio 0
	s_cselect_b32 s16, s15, s19
	s_mov_b32 m0, s35
	s_mov_b32 s42, s6
	s_mov_b32 s43, s7
	s_sub_i32 s16, s16, s40
	buffer_load_dwordx4 v134, s[40:43], s16 offen lds
	s_mov_b32 m0, s44
	s_add_i32 s74, s16, 0x80000
	buffer_load_dwordx4 v136, s[40:43], s16 offen lds
	ds_read_b128 v[170:173], v140 offset:16384
	ds_read_b128 v[174:177], v140 offset:17408
	ds_read_b128 v[178:181], v140 offset:18432
	ds_read_b128 v[182:185], v140 offset:19456
	ds_read_b128 v[186:189], v140 offset:20480
	ds_read_b128 v[190:193], v140 offset:21504
	ds_read_b128 v[200:203], v140 offset:22528
	ds_read_b128 v[206:209], v140 offset:23552
	s_mov_b32 m0, s45
	s_sub_i32 s17, s17, s4
	buffer_load_dwordx4 v134, s[40:43], s74 offen lds
	s_mov_b32 m0, s46
	s_nop 0
	buffer_load_dwordx4 v136, s[40:43], s74 offen lds
	s_mov_b32 m0, s34
	s_nop 0
	buffer_load_dwordx4 v0, s[4:7], s17 offen lds
	s_waitcnt vmcnt(7)
	s_waitcnt lgkmcnt(0)
	s_setprio 1
	s_barrier
; #define PG8_STAGE(bufoff, gbase, voff) do { const int so_ = (int)(unsigned)((const char*)(gbase) - base_##voff); _Pragma("unroll") for (int _i = 0; _i < 2; ++_i) \
;         __builtin_amdgcn_raw_ptr_buffer_load_lds(rs_##voff, (PG8_LAS unsigned*)(lds + (bufoff) + ldsw + _i * 8192), 16, (int)(voff)[_i], so_, 0, 0); } while (0)
; #define PG8_LDA(dst, b, h) do { _Pragma("unroll") for (int m = 0; m < 4; ++m) _Pragma("unroll") for (int k = 0; k < 2; ++k) dst[m][k] = *(const PG8_LAS bf16x8*)(lds + PG8_SA(b, h) + aoff + m * 2048 + k * 1024); } while (0)
; #define PG8_LDB(dst, b, h) do { _Pragma("unroll") for (int n = 0; n < 2; ++n) _Pragma("unroll") for (int k = 0; k < 2; ++k) dst[n][k] = *(const PG8_LAS bf16x8*)(lds + PG8_SB(b, h) + boff + n * 2048 + k * 1024); } while (0)
; #define PG8_MMA(ai, bj, At, Bt) do { __builtin_amdgcn_s_setprio(1); _Pragma("unroll") for (int m = 0; m < 4; ++m) _Pragma("unroll") for (int n = 0; n < 2; ++n) _Pragma("unroll") for (int k = 0; k < 2; ++k) \
;         acc[ai][bj][m][n] = __builtin_amdgcn_mfma_f32_16x16x32_bf16(Bt[n][k], At[m][k], acc[ai][bj][m][n], 0, 0, 0); __builtin_amdgcn_s_setprio(0); } while (0)
; #define PG8_WAIT_V(n) asm volatile("s_waitcnt vmcnt(" #n ")" ::: "memory")
; #define PG8_WAIT_L(n) asm volatile("s_waitcnt lgkmcnt(" #n ")" ::: "memory")
; #define PG8_BAR __builtin_amdgcn_s_barrier()
; #define PG8_SCHED __builtin_amdgcn_sched_barrier(0)
; template <class Epi, class Sched, bool ALIGN_EPI = false, bool SP2 = false>
; __device__ __forceinline__ void gemm_phase(PG8_LAS unsigned char* lds, const Gemm g, const Sched& S, const Epi& E, int tid_in) {
;     ...
;             PG8_LDA(At, 0, 1); PG8_STAGE(PG8_SB(0, 0), b2, voffB); PG8_STAGE(PG8_SB(0, 1), b2 + hstepB, voffB); PG8_STAGE(PG8_SA(0, 0), a2, voffA);
;             PG8_WAIT_V(8); PG8_WAIT_L(0); PG8_BAR; PG8_MMA(1, 0, At, B0); PG8_MMA(1, 1, At, B1); PG8_BAR; PG8_SCHED;
;             PG8_LDB(B0, 1, 0); PG8_LDB(B1, 1, 1); PG8_SCHED; PG8_LDA(At, 1, 0); PG8_STAGE(PG8_SA(0, 1), a2 + hstepA, voffA);
;             PG8_WAIT_V(8); PG8_WAIT_L(0); PG8_BAR; PG8_MMA(0, 0, At, B0); PG8_MMA(0, 1, At, B1); PG8_BAR; PG8_SCHED;
	v_mfma_f32_16x16x32_bf16 v[62:65], v[130:133], v[170:173], 0
	v_mfma_f32_16x16x32_bf16 v[58:61], v[146:149], v[170:173], 0
	v_mfma_f32_16x16x32_bf16 v[42:45], v[146:149], v[178:181], 0
	v_mfma_f32_16x16x32_bf16 v[46:49], v[130:133], v[178:181], 0
	v_mfma_f32_16x16x32_bf16 v[30:33], v[130:133], v[186:189], 0
	v_mfma_f32_16x16x32_bf16 v[26:29], v[146:149], v[186:189], 0
	v_mfma_f32_16x16x32_bf16 v[10:13], v[146:149], v[200:203], 0
	v_mfma_f32_16x16x32_bf16 v[14:17], v[130:133], v[200:203], 0
	v_mfma_f32_16x16x32_bf16 v[62:65], v[142:145], v[174:177], v[62:65]
	v_mfma_f32_16x16x32_bf16 v[58:61], v[150:153], v[174:177], v[58:61]
	v_mfma_f32_16x16x32_bf16 v[42:45], v[150:153], v[182:185], v[42:45]
	v_mfma_f32_16x16x32_bf16 v[46:49], v[142:145], v[182:185], v[46:49]
	v_mfma_f32_16x16x32_bf16 v[30:33], v[142:145], v[190:193], v[30:33]
	v_mfma_f32_16x16x32_bf16 v[26:29], v[150:153], v[190:193], v[26:29]
	v_mfma_f32_16x16x32_bf16 v[10:13], v[150:153], v[206:209], v[10:13]
	v_mfma_f32_16x16x32_bf16 v[14:17], v[142:145], v[206:209], v[14:17]
	v_mfma_f32_16x16x32_bf16 v[54:57], v[154:157], v[170:173], 0
	v_mfma_f32_16x16x32_bf16 v[50:53], v[162:165], v[170:173], 0
	v_mfma_f32_16x16x32_bf16 v[34:37], v[162:165], v[178:181], 0
	v_mfma_f32_16x16x32_bf16 v[38:41], v[154:157], v[178:181], 0
	v_mfma_f32_16x16x32_bf16 v[22:25], v[154:157], v[186:189], 0
	v_mfma_f32_16x16x32_bf16 v[18:21], v[162:165], v[186:189], 0
	v_mfma_f32_16x16x32_bf16 v[2:5], v[162:165], v[200:203], 0
	v_mfma_f32_16x16x32_bf16 v[6:9], v[154:157], v[200:203], 0
	v_mfma_f32_16x16x32_bf16 v[54:57], v[158:161], v[174:177], v[54:57]
	v_mfma_f32_16x16x32_bf16 v[50:53], v[166:169], v[174:177], v[50:53]
	v_mfma_f32_16x16x32_bf16 v[34:37], v[166:169], v[182:185], v[34:37]
	v_mfma_f32_16x16x32_bf16 v[38:41], v[158:161], v[182:185], v[38:41]
	v_mfma_f32_16x16x32_bf16 v[22:25], v[158:161], v[190:193], v[22:25]
	v_mfma_f32_16x16x32_bf16 v[18:21], v[166:169], v[190:193], v[18:21]
	v_mfma_f32_16x16x32_bf16 v[2:5], v[166:169], v[206:209], v[2:5]
	v_mfma_f32_16x16x32_bf16 v[6:9], v[158:161], v[206:209], v[6:9]
	s_barrier
	s_setprio 0
	v_add_u32_e32 v141, 0x18000, v139
	ds_read_b128 v[130:133], v141
	ds_read_b128 v[142:145], v141 offset:1024
	ds_read_b128 v[146:149], v141 offset:2048
	ds_read_b128 v[150:153], v141 offset:3072
	v_add_u32_e32 v141, 0x1c000, v139
	ds_read_b128 v[154:157], v141
	ds_read_b128 v[158:161], v141 offset:1024
	ds_read_b128 v[162:165], v141 offset:2048
	ds_read_b128 v[166:169], v141 offset:3072
	s_add_i32 s74, s17, 0x80000
	s_mov_b32 m0, s48
	ds_read_b128 v[170:173], v140 offset:32768
	ds_read_b128 v[174:177], v140 offset:33792
	ds_read_b128 v[178:181], v140 offset:34816
	ds_read_b128 v[182:185], v140 offset:35840
	ds_read_b128 v[186:189], v140 offset:36864
	ds_read_b128 v[190:193], v140 offset:37888
	ds_read_b128 v[200:203], v140 offset:38912
	ds_read_b128 v[206:209], v140 offset:39936
	s_mov_b32 m0, s47
	s_nop 0
	buffer_load_dwordx4 v135, s[4:7], s17 offen lds
	s_mov_b32 m0, s48
	s_nop 0
	buffer_load_dwordx4 v0, s[4:7], s74 offen lds
	s_mov_b32 m0, s49
	s_nop 0
	buffer_load_dwordx4 v135, s[4:7], s74 offen lds
	s_waitcnt vmcnt(8)
	s_waitcnt lgkmcnt(0)
	s_setprio 1
	s_barrier
	v_mfma_f32_16x16x32_bf16 v[126:129], v[130:133], v[170:173], v[126:129]
	v_mfma_f32_16x16x32_bf16 v[122:125], v[146:149], v[170:173], v[122:125]
	v_mfma_f32_16x16x32_bf16 v[106:109], v[146:149], v[178:181], v[106:109]
	v_mfma_f32_16x16x32_bf16 v[110:113], v[130:133], v[178:181], v[110:113]
	v_mfma_f32_16x16x32_bf16 v[94:97], v[130:133], v[186:189], v[94:97]
	v_mfma_f32_16x16x32_bf16 v[90:93], v[146:149], v[186:189], v[90:93]
	v_mfma_f32_16x16x32_bf16 v[74:77], v[146:149], v[200:203], v[74:77]
	v_mfma_f32_16x16x32_bf16 v[78:81], v[130:133], v[200:203], v[78:81]
	v_mfma_f32_16x16x32_bf16 v[126:129], v[142:145], v[174:177], v[126:129]
	v_mfma_f32_16x16x32_bf16 v[122:125], v[150:153], v[174:177], v[122:125]
	v_mfma_f32_16x16x32_bf16 v[106:109], v[150:153], v[182:185], v[106:109]
	v_mfma_f32_16x16x32_bf16 v[110:113], v[142:145], v[182:185], v[110:113]
	v_mfma_f32_16x16x32_bf16 v[94:97], v[142:145], v[190:193], v[94:97]
	v_mfma_f32_16x16x32_bf16 v[90:93], v[150:153], v[190:193], v[90:93]
	v_mfma_f32_16x16x32_bf16 v[74:77], v[150:153], v[206:209], v[74:77]
	v_mfma_f32_16x16x32_bf16 v[78:81], v[142:145], v[206:209], v[78:81]
	v_mfma_f32_16x16x32_bf16 v[118:121], v[154:157], v[170:173], v[118:121]
	v_mfma_f32_16x16x32_bf16 v[114:117], v[162:165], v[170:173], v[114:117]
	v_mfma_f32_16x16x32_bf16 v[98:101], v[162:165], v[178:181], v[98:101]
	v_mfma_f32_16x16x32_bf16 v[102:105], v[154:157], v[178:181], v[102:105]
	v_mfma_f32_16x16x32_bf16 v[86:89], v[154:157], v[186:189], v[86:89]
	v_mfma_f32_16x16x32_bf16 v[82:85], v[162:165], v[186:189], v[82:85]
	v_mfma_f32_16x16x32_bf16 v[66:69], v[162:165], v[200:203], v[66:69]
	v_mfma_f32_16x16x32_bf16 v[70:73], v[154:157], v[200:203], v[70:73]
	v_mfma_f32_16x16x32_bf16 v[118:121], v[158:161], v[174:177], v[118:121]
	v_mfma_f32_16x16x32_bf16 v[114:117], v[166:169], v[174:177], v[114:117]
	v_mfma_f32_16x16x32_bf16 v[98:101], v[166:169], v[182:185], v[98:101]
	v_mfma_f32_16x16x32_bf16 v[102:105], v[158:161], v[182:185], v[102:105]
	v_mfma_f32_16x16x32_bf16 v[86:89], v[158:161], v[190:193], v[86:89]
	v_mfma_f32_16x16x32_bf16 v[82:85], v[166:169], v[190:193], v[82:85]
	v_mfma_f32_16x16x32_bf16 v[66:69], v[166:169], v[206:209], v[66:69]
	v_mfma_f32_16x16x32_bf16 v[70:73], v[158:161], v[206:209], v[70:73]
	s_barrier
; #define PG8_STAGE(bufoff, gbase, voff) do { const int so_ = (int)(unsigned)((const char*)(gbase) - base_##voff); _Pragma("unroll") for (int _i = 0; _i < 2; ++_i) \
;         __builtin_amdgcn_raw_ptr_buffer_load_lds(rs_##voff, (PG8_LAS unsigned*)(lds + (bufoff) + ldsw + _i * 8192), 16, (int)(voff)[_i], so_, 0, 0); } while (0)
; #define PG8_LDA(dst, b, h) do { _Pragma("unroll") for (int m = 0; m < 4; ++m) _Pragma("unroll") for (int k = 0; k < 2; ++k) dst[m][k] = *(const PG8_LAS bf16x8*)(lds + PG8_SA(b, h) + aoff + m * 2048 + k * 1024); } while (0)
; #define PG8_LDB(dst, b, h) do { _Pragma("unroll") for (int n = 0; n < 2; ++n) _Pragma("unroll") for (int k = 0; k < 2; ++k) dst[n][k] = *(const PG8_LAS bf16x8*)(lds + PG8_SB(b, h) + boff + n * 2048 + k * 1024); } while (0)
; #define PG8_MMA(ai, bj, At, Bt) do { __builtin_amdgcn_s_setprio(1); _Pragma("unroll") for (int m = 0; m < 4; ++m) _Pragma("unroll") for (int n = 0; n < 2; ++n) _Pragma("unroll") for (int k = 0; k < 2; ++k) \
;         acc[ai][bj][m][n] = __builtin_amdgcn_mfma_f32_16x16x32_bf16(Bt[n][k], At[m][k], acc[ai][bj][m][n], 0, 0, 0); __builtin_amdgcn_s_setprio(0); } while (0)
; template <class Epi, class Sched, bool ALIGN_EPI = false, bool SP2 = false>
; __device__ __forceinline__ void gemm_phase(PG8_LAS unsigned char* lds, const Gemm g, const Sched& S, const Epi& E, int tid_in) {
;     ...
;             PG8_LDB(B0, 0, 0); PG8_LDB(B1, 0, 1); PG8_SCHED; PG8_LDA(At, 0, 0); PG8_STAGE(PG8_SA(1, 1), a1 + hstepA, voffA);
;             PG8_WAIT_V(8); PG8_WAIT_L(0); PG8_BAR; PG8_MMA(0, 0, At, B0); PG8_MMA(0, 1, At, B1); PG8_BAR; PG8_SCHED;
;             PG8_LDA(At, 0, 1); PG8_STAGE(PG8_SB(0, 0), b2, voffB); PG8_STAGE(PG8_SB(0, 1), b2 + hstepB, voffB); PG8_STAGE(PG8_SA(0, 0), a2, voffA);
;             PG8_WAIT_V(8); PG8_WAIT_L(0); PG8_BAR; PG8_MMA(1, 0, At, B0); PG8_MMA(1, 1, At, B1); PG8_BAR; PG8_SCHED;
;             PG8_LDB(B0, 1, 0); PG8_LDB(B1, 1, 1); PG8_SCHED; PG8_LDA(At, 1, 0); PG8_STAGE(PG8_SA(0, 1), a2 + hstepA, voffA);
;             PG8_WAIT_V(8); PG8_WAIT_L(0); PG8_BAR; PG8_MMA(0, 0, At, B0); PG8_MMA(0, 1, At, B1); PG8_BAR; PG8_SCHED;
;             PG8_LDA(At, 1, 1); PG8_STAGE(PG8_SB(1, 0), b3, voffB); PG8_STAGE(PG8_SB(1, 1), b3 + hstepB, voffB); PG8_STAGE(PG8_SA(1, 0), a3, voffA);
;             PG8_WAIT_V(8); PG8_WAIT_L(0); PG8_BAR; PG8_MMA(1, 0, At, B0); PG8_MMA(1, 1, At, B1); PG8_BAR; PG8_SCHED;
	s_setprio 0
	s_mov_b32 m0, s53
	s_add_i32 s74, s16, 0x80
	buffer_load_dwordx4 v134, s[40:43], s74 offen lds
	s_mov_b32 m0, s60
	s_add_i32 s16, s16, 0x80080
	buffer_load_dwordx4 v136, s[40:43], s74 offen lds
	ds_read_b128 v[170:173], v140 offset:49152
	ds_read_b128 v[174:177], v140 offset:50176
	ds_read_b128 v[178:181], v140 offset:51200
	ds_read_b128 v[182:185], v140 offset:52224
	ds_read_b128 v[186:189], v140 offset:53248
	ds_read_b128 v[190:193], v140 offset:54272
	ds_read_b128 v[200:203], v140 offset:55296
	ds_read_b128 v[206:209], v140 offset:56320
	s_mov_b32 m0, s63
	s_addk_i32 s17, 0x80
	buffer_load_dwordx4 v134, s[40:43], s16 offen lds
	s_mov_b32 m0, s66
	s_nop 0
	buffer_load_dwordx4 v136, s[40:43], s16 offen lds
	s_mov_b32 m0, s61
	s_nop 0
	buffer_load_dwordx4 v0, s[4:7], s17 offen lds
	s_waitcnt vmcnt(7)
	s_waitcnt lgkmcnt(0)
	s_setprio 1
	s_barrier
	v_mfma_f32_16x16x32_bf16 v[62:65], v[130:133], v[170:173], v[62:65]
	v_mfma_f32_16x16x32_bf16 v[58:61], v[146:149], v[170:173], v[58:61]
	v_mfma_f32_16x16x32_bf16 v[42:45], v[146:149], v[178:181], v[42:45]
	v_mfma_f32_16x16x32_bf16 v[46:49], v[130:133], v[178:181], v[46:49]
	v_mfma_f32_16x16x32_bf16 v[30:33], v[130:133], v[186:189], v[30:33]
	v_mfma_f32_16x16x32_bf16 v[26:29], v[146:149], v[186:189], v[26:29]
	v_mfma_f32_16x16x32_bf16 v[10:13], v[146:149], v[200:203], v[10:13]
	v_mfma_f32_16x16x32_bf16 v[14:17], v[130:133], v[200:203], v[14:17]
	v_mfma_f32_16x16x32_bf16 v[62:65], v[142:145], v[174:177], v[62:65]
	v_mfma_f32_16x16x32_bf16 v[58:61], v[150:153], v[174:177], v[58:61]
	v_mfma_f32_16x16x32_bf16 v[42:45], v[150:153], v[182:185], v[42:45]
	v_mfma_f32_16x16x32_bf16 v[46:49], v[142:145], v[182:185], v[46:49]
	v_mfma_f32_16x16x32_bf16 v[30:33], v[142:145], v[190:193], v[30:33]
	v_mfma_f32_16x16x32_bf16 v[26:29], v[150:153], v[190:193], v[26:29]
	v_mfma_f32_16x16x32_bf16 v[10:13], v[150:153], v[206:209], v[10:13]
	v_mfma_f32_16x16x32_bf16 v[14:17], v[142:145], v[206:209], v[14:17]
	v_mfma_f32_16x16x32_bf16 v[54:57], v[154:157], v[170:173], v[54:57]
	v_mfma_f32_16x16x32_bf16 v[50:53], v[162:165], v[170:173], v[50:53]
	v_mfma_f32_16x16x32_bf16 v[34:37], v[162:165], v[178:181], v[34:37]
	v_mfma_f32_16x16x32_bf16 v[38:41], v[154:157], v[178:181], v[38:41]
	v_mfma_f32_16x16x32_bf16 v[22:25], v[154:157], v[186:189], v[22:25]
	v_mfma_f32_16x16x32_bf16 v[18:21], v[162:165], v[186:189], v[18:21]
	v_mfma_f32_16x16x32_bf16 v[2:5], v[162:165], v[200:203], v[2:5]
	v_mfma_f32_16x16x32_bf16 v[6:9], v[154:157], v[200:203], v[6:9]
	v_mfma_f32_16x16x32_bf16 v[54:57], v[158:161], v[174:177], v[54:57]
	v_mfma_f32_16x16x32_bf16 v[50:53], v[166:169], v[174:177], v[50:53]
	v_mfma_f32_16x16x32_bf16 v[34:37], v[166:169], v[182:185], v[34:37]
	v_mfma_f32_16x16x32_bf16 v[38:41], v[158:161], v[182:185], v[38:41]
	v_mfma_f32_16x16x32_bf16 v[22:25], v[158:161], v[190:193], v[22:25]
	v_mfma_f32_16x16x32_bf16 v[18:21], v[166:169], v[190:193], v[18:21]
	v_mfma_f32_16x16x32_bf16 v[2:5], v[166:169], v[206:209], v[2:5]
	v_mfma_f32_16x16x32_bf16 v[6:9], v[158:161], v[206:209], v[6:9]
	s_barrier
	s_setprio 0
	s_add_i32 s73, s73, 2
	s_add_u32 s19, s19, 0x100
	s_addc_u32 s21, s21, 0
	s_cmp_gt_u32 s73, 29
	s_mov_b64 s[16:17], s[38:39]
.LBB0_1514:
	v_add_u32_e32 v141, 0x10000, v139
	ds_read_b128 v[130:133], v141
	ds_read_b128 v[142:145], v141 offset:1024
	ds_read_b128 v[146:149], v141 offset:2048
	ds_read_b128 v[150:153], v141 offset:3072
	v_add_u32_e32 v141, 0x14000, v139
	ds_read_b128 v[154:157], v141
	ds_read_b128 v[158:161], v141 offset:1024
	ds_read_b128 v[162:165], v141 offset:2048
	ds_read_b128 v[166:169], v141 offset:3072
	s_add_u32 s38, s16, 0x100
	s_addc_u32 s39, s17, 0
	s_sub_i32 s16, s16, s4
	s_add_i32 s16, s16, 0x80080
	s_sub_i32 s74, s16, 0x80000
	s_cmp_eq_u32 s73, 28
	s_cselect_b32 s17, s18, s38
	s_mov_b32 m0, s67
	ds_read_b128 v[170:173], v140
	ds_read_b128 v[174:177], v140 offset:1024
	ds_read_b128 v[178:181], v140 offset:2048
	ds_read_b128 v[182:185], v140 offset:3072
	ds_read_b128 v[186:189], v140 offset:4096
	ds_read_b128 v[190:193], v140 offset:5120
	ds_read_b128 v[200:203], v140 offset:6144
	ds_read_b128 v[206:209], v140 offset:7168
	s_mov_b32 m0, s62
	s_nop 0
	buffer_load_dwordx4 v135, s[4:7], s74 offen lds
	s_mov_b32 m0, s67
	s_nop 0
	buffer_load_dwordx4 v0, s[4:7], s16 offen lds
	s_mov_b32 m0, s68
	s_nop 0
	buffer_load_dwordx4 v135, s[4:7], s16 offen lds
	s_waitcnt vmcnt(8)
	s_waitcnt lgkmcnt(0)
	s_setprio 1
	s_barrier
	v_mfma_f32_16x16x32_bf16 v[126:129], v[130:133], v[170:173], v[126:129]
	v_mfma_f32_16x16x32_bf16 v[122:125], v[146:149], v[170:173], v[122:125]
	v_mfma_f32_16x16x32_bf16 v[106:109], v[146:149], v[178:181], v[106:109]
	v_mfma_f32_16x16x32_bf16 v[110:113], v[130:133], v[178:181], v[110:113]
	v_mfma_f32_16x16x32_bf16 v[94:97], v[130:133], v[186:189], v[94:97]
	v_mfma_f32_16x16x32_bf16 v[90:93], v[146:149], v[186:189], v[90:93]
	v_mfma_f32_16x16x32_bf16 v[74:77], v[146:149], v[200:203], v[74:77]
	v_mfma_f32_16x16x32_bf16 v[78:81], v[130:133], v[200:203], v[78:81]
	v_mfma_f32_16x16x32_bf16 v[126:129], v[142:145], v[174:177], v[126:129]
	v_mfma_f32_16x16x32_bf16 v[122:125], v[150:153], v[174:177], v[122:125]
	v_mfma_f32_16x16x32_bf16 v[106:109], v[150:153], v[182:185], v[106:109]
	v_mfma_f32_16x16x32_bf16 v[110:113], v[142:145], v[182:185], v[110:113]
	v_mfma_f32_16x16x32_bf16 v[94:97], v[142:145], v[190:193], v[94:97]
	v_mfma_f32_16x16x32_bf16 v[90:93], v[150:153], v[190:193], v[90:93]
	v_mfma_f32_16x16x32_bf16 v[74:77], v[150:153], v[206:209], v[74:77]
	v_mfma_f32_16x16x32_bf16 v[78:81], v[142:145], v[206:209], v[78:81]
	v_mfma_f32_16x16x32_bf16 v[118:121], v[154:157], v[170:173], v[118:121]
	v_mfma_f32_16x16x32_bf16 v[114:117], v[162:165], v[170:173], v[114:117]
	v_mfma_f32_16x16x32_bf16 v[98:101], v[162:165], v[178:181], v[98:101]
	v_mfma_f32_16x16x32_bf16 v[102:105], v[154:157], v[178:181], v[102:105]
	v_mfma_f32_16x16x32_bf16 v[86:89], v[154:157], v[186:189], v[86:89]
	v_mfma_f32_16x16x32_bf16 v[82:85], v[162:165], v[186:189], v[82:85]
	v_mfma_f32_16x16x32_bf16 v[66:69], v[162:165], v[200:203], v[66:69]
	v_mfma_f32_16x16x32_bf16 v[70:73], v[154:157], v[200:203], v[70:73]
	v_mfma_f32_16x16x32_bf16 v[118:121], v[158:161], v[174:177], v[118:121]
	v_mfma_f32_16x16x32_bf16 v[114:117], v[166:169], v[174:177], v[114:117]
	v_mfma_f32_16x16x32_bf16 v[98:101], v[166:169], v[182:185], v[98:101]
	v_mfma_f32_16x16x32_bf16 v[102:105], v[158:161], v[182:185], v[102:105]
	v_mfma_f32_16x16x32_bf16 v[86:89], v[158:161], v[190:193], v[86:89]
	v_mfma_f32_16x16x32_bf16 v[82:85], v[166:169], v[190:193], v[82:85]
	v_mfma_f32_16x16x32_bf16 v[66:69], v[166:169], v[206:209], v[66:69]
	v_mfma_f32_16x16x32_bf16 v[70:73], v[158:161], v[206:209], v[70:73]
	s_barrier
; #define PG8_STAGE(bufoff, gbase, voff) do { const int so_ = (int)(unsigned)((const char*)(gbase) - base_##voff); _Pragma("unroll") for (int _i = 0; _i < 2; ++_i) \
;         __builtin_amdgcn_raw_ptr_buffer_load_lds(rs_##voff, (PG8_LAS unsigned*)(lds + (bufoff) + ldsw + _i * 8192), 16, (int)(voff)[_i], so_, 0, 0); } while (0)
; #define PG8_LDA(dst, b, h) do { _Pragma("unroll") for (int m = 0; m < 4; ++m) _Pragma("unroll") for (int k = 0; k < 2; ++k) dst[m][k] = *(const PG8_LAS bf16x8*)(lds + PG8_SA(b, h) + aoff + m * 2048 + k * 1024); } while (0)
; #define PG8_LDB(dst, b, h) do { _Pragma("unroll") for (int n = 0; n < 2; ++n) _Pragma("unroll") for (int k = 0; k < 2; ++k) dst[n][k] = *(const PG8_LAS bf16x8*)(lds + PG8_SB(b, h) + boff + n * 2048 + k * 1024); } while (0)
; #define PG8_MMA(ai, bj, At, Bt) do { __builtin_amdgcn_s_setprio(1); _Pragma("unroll") for (int m = 0; m < 4; ++m) _Pragma("unroll") for (int n = 0; n < 2; ++n) _Pragma("unroll") for (int k = 0; k < 2; ++k) \
;         acc[ai][bj][m][n] = __builtin_amdgcn_mfma_f32_16x16x32_bf16(Bt[n][k], At[m][k], acc[ai][bj][m][n], 0, 0, 0); __builtin_amdgcn_s_setprio(0); } while (0)
; #define PG8_WAIT_V(n) asm volatile("s_waitcnt vmcnt(" #n ")" ::: "memory")
; #define PG8_WAIT_L(n) asm volatile("s_waitcnt lgkmcnt(" #n ")" ::: "memory")
; #define PG8_BAR __builtin_amdgcn_s_barrier()
; #define PG8_SCHED __builtin_amdgcn_sched_barrier(0)
; template <class Epi, class Sched, bool ALIGN_EPI = false, bool SP2 = false>
; __device__ __forceinline__ void gemm_phase(PG8_LAS unsigned char* lds, const Gemm g, const Sched& S, const Epi& E, int tid_in) {
;     ...
;             PG8_WAIT_V(8); PG8_WAIT_L(0); PG8_BAR; PG8_MMA(0, 0, At, B0); PG8_MMA(0, 1, At, B1); PG8_BAR; PG8_SCHED;
;             PG8_LDA(At, 0, 1); PG8_STAGE(PG8_SB(0, 0), b2, voffB); PG8_STAGE(PG8_SB(0, 1), b2 + hstepB, voffB); PG8_STAGE(PG8_SA(0, 0), a2, voffA);
;             PG8_WAIT_V(8); PG8_WAIT_L(0); PG8_BAR; PG8_MMA(1, 0, At, B0); PG8_MMA(1, 1, At, B1); PG8_BAR; PG8_SCHED;
;             PG8_LDB(B0, 1, 0); PG8_LDB(B1, 1, 1); PG8_SCHED; PG8_LDA(At, 1, 0); PG8_STAGE(PG8_SA(0, 1), a2 + hstepA, voffA);
;             PG8_WAIT_V(8); PG8_WAIT_L(0); PG8_BAR; PG8_MMA(0, 0, At, B0); PG8_MMA(0, 1, At, B1); PG8_BAR; PG8_SCHED;
	s_setprio 0
	s_cselect_b32 s16, s15, s19
	s_mov_b32 m0, s35
	s_mov_b32 s42, s6
	s_mov_b32 s43, s7
	s_sub_i32 s16, s16, s40
	buffer_load_dwordx4 v134, s[40:43], s16 offen lds
	s_mov_b32 m0, s44
	s_add_i32 s74, s16, 0x80000
	buffer_load_dwordx4 v136, s[40:43], s16 offen lds
	ds_read_b128 v[170:173], v140 offset:16384
	ds_read_b128 v[174:177], v140 offset:17408
	ds_read_b128 v[178:181], v140 offset:18432
	ds_read_b128 v[182:185], v140 offset:19456
	ds_read_b128 v[186:189], v140 offset:20480
	ds_read_b128 v[190:193], v140 offset:21504
	ds_read_b128 v[200:203], v140 offset:22528
	ds_read_b128 v[206:209], v140 offset:23552
	s_mov_b32 m0, s45
	s_sub_i32 s17, s17, s4
	buffer_load_dwordx4 v134, s[40:43], s74 offen lds
	s_mov_b32 m0, s46
	s_nop 0
	buffer_load_dwordx4 v136, s[40:43], s74 offen lds
	s_mov_b32 m0, s34
	s_nop 0
	buffer_load_dwordx4 v0, s[4:7], s17 offen lds
	s_waitcnt vmcnt(7)
	s_waitcnt lgkmcnt(0)
	s_setprio 1
	s_barrier
	v_mfma_f32_16x16x32_bf16 v[62:65], v[130:133], v[170:173], v[62:65]
	v_mfma_f32_16x16x32_bf16 v[58:61], v[146:149], v[170:173], v[58:61]
	v_mfma_f32_16x16x32_bf16 v[42:45], v[146:149], v[178:181], v[42:45]
	v_mfma_f32_16x16x32_bf16 v[46:49], v[130:133], v[178:181], v[46:49]
	v_mfma_f32_16x16x32_bf16 v[30:33], v[130:133], v[186:189], v[30:33]
	v_mfma_f32_16x16x32_bf16 v[26:29], v[146:149], v[186:189], v[26:29]
	v_mfma_f32_16x16x32_bf16 v[10:13], v[146:149], v[200:203], v[10:13]
	v_mfma_f32_16x16x32_bf16 v[14:17], v[130:133], v[200:203], v[14:17]
	v_mfma_f32_16x16x32_bf16 v[62:65], v[142:145], v[174:177], v[62:65]
	v_mfma_f32_16x16x32_bf16 v[58:61], v[150:153], v[174:177], v[58:61]
	v_mfma_f32_16x16x32_bf16 v[42:45], v[150:153], v[182:185], v[42:45]
	v_mfma_f32_16x16x32_bf16 v[46:49], v[142:145], v[182:185], v[46:49]
	v_mfma_f32_16x16x32_bf16 v[30:33], v[142:145], v[190:193], v[30:33]
	v_mfma_f32_16x16x32_bf16 v[26:29], v[150:153], v[190:193], v[26:29]
	v_mfma_f32_16x16x32_bf16 v[10:13], v[150:153], v[206:209], v[10:13]
	v_mfma_f32_16x16x32_bf16 v[14:17], v[142:145], v[206:209], v[14:17]
	v_mfma_f32_16x16x32_bf16 v[54:57], v[154:157], v[170:173], v[54:57]
	v_mfma_f32_16x16x32_bf16 v[50:53], v[162:165], v[170:173], v[50:53]
	v_mfma_f32_16x16x32_bf16 v[34:37], v[162:165], v[178:181], v[34:37]
	v_mfma_f32_16x16x32_bf16 v[38:41], v[154:157], v[178:181], v[38:41]
	v_mfma_f32_16x16x32_bf16 v[22:25], v[154:157], v[186:189], v[22:25]
	v_mfma_f32_16x16x32_bf16 v[18:21], v[162:165], v[186:189], v[18:21]
	v_mfma_f32_16x16x32_bf16 v[2:5], v[162:165], v[200:203], v[2:5]
	v_mfma_f32_16x16x32_bf16 v[6:9], v[154:157], v[200:203], v[6:9]
	v_mfma_f32_16x16x32_bf16 v[54:57], v[158:161], v[174:177], v[54:57]
	v_mfma_f32_16x16x32_bf16 v[50:53], v[166:169], v[174:177], v[50:53]
	v_mfma_f32_16x16x32_bf16 v[34:37], v[166:169], v[182:185], v[34:37]
	v_mfma_f32_16x16x32_bf16 v[38:41], v[158:161], v[182:185], v[38:41]
	v_mfma_f32_16x16x32_bf16 v[22:25], v[158:161], v[190:193], v[22:25]
	v_mfma_f32_16x16x32_bf16 v[18:21], v[166:169], v[190:193], v[18:21]
	v_mfma_f32_16x16x32_bf16 v[2:5], v[166:169], v[206:209], v[2:5]
	v_mfma_f32_16x16x32_bf16 v[6:9], v[158:161], v[206:209], v[6:9]
	s_barrier
	s_setprio 0
	v_add_u32_e32 v141, 0x18000, v139
	ds_read_b128 v[130:133], v141
	ds_read_b128 v[142:145], v141 offset:1024
	ds_read_b128 v[146:149], v141 offset:2048
	ds_read_b128 v[150:153], v141 offset:3072
	v_add_u32_e32 v141, 0x1c000, v139
	ds_read_b128 v[154:157], v141
	ds_read_b128 v[158:161], v141 offset:1024
	ds_read_b128 v[162:165], v141 offset:2048
	ds_read_b128 v[166:169], v141 offset:3072
	s_add_i32 s74, s17, 0x80000
	s_mov_b32 m0, s48
	ds_read_b128 v[170:173], v140 offset:32768
	ds_read_b128 v[174:177], v140 offset:33792
	ds_read_b128 v[178:181], v140 offset:34816
	ds_read_b128 v[182:185], v140 offset:35840
	ds_read_b128 v[186:189], v140 offset:36864
	ds_read_b128 v[190:193], v140 offset:37888
	ds_read_b128 v[200:203], v140 offset:38912
	ds_read_b128 v[206:209], v140 offset:39936
	s_mov_b32 m0, s47
	s_nop 0
	buffer_load_dwordx4 v135, s[4:7], s17 offen lds
	s_mov_b32 m0, s48
	s_nop 0
	buffer_load_dwordx4 v0, s[4:7], s74 offen lds
	s_mov_b32 m0, s49
	s_nop 0
	buffer_load_dwordx4 v135, s[4:7], s74 offen lds
	s_waitcnt vmcnt(8)
	s_waitcnt lgkmcnt(0)
	s_setprio 1
	s_barrier
; #define PG8_STAGE(bufoff, gbase, voff) do { const int so_ = (int)(unsigned)((const char*)(gbase) - base_##voff); _Pragma("unroll") for (int _i = 0; _i < 2; ++_i) \
;         __builtin_amdgcn_raw_ptr_buffer_load_lds(rs_##voff, (PG8_LAS unsigned*)(lds + (bufoff) + ldsw + _i * 8192), 16, (int)(voff)[_i], so_, 0, 0); } while (0)
; #define PG8_LDA(dst, b, h) do { _Pragma("unroll") for (int m = 0; m < 4; ++m) _Pragma("unroll") for (int k = 0; k < 2; ++k) dst[m][k] = *(const PG8_LAS bf16x8*)(lds + PG8_SA(b, h) + aoff + m * 2048 + k * 1024); } while (0)
; #define PG8_MMA(ai, bj, At, Bt) do { __builtin_amdgcn_s_setprio(1); _Pragma("unroll") for (int m = 0; m < 4; ++m) _Pragma("unroll") for (int n = 0; n < 2; ++n) _Pragma("unroll") for (int k = 0; k < 2; ++k) \
;         acc[ai][bj][m][n] = __builtin_amdgcn_mfma_f32_16x16x32_bf16(Bt[n][k], At[m][k], acc[ai][bj][m][n], 0, 0, 0); __builtin_amdgcn_s_setprio(0); } while (0)
; #define PG8_WAIT_V(n) asm volatile("s_waitcnt vmcnt(" #n ")" ::: "memory")
; #define PG8_WAIT_L(n) asm volatile("s_waitcnt lgkmcnt(" #n ")" ::: "memory")
; #define PG8_BAR __builtin_amdgcn_s_barrier()
; #define PG8_SCHED __builtin_amdgcn_sched_barrier(0)
; template <class Epi, class Sched, bool ALIGN_EPI = false, bool SP2 = false>
; __device__ __forceinline__ void gemm_phase(PG8_LAS unsigned char* lds, const Gemm g, const Sched& S, const Epi& E, int tid_in) {
;     ...
;             PG8_WAIT_V(8); PG8_WAIT_L(0); PG8_BAR; PG8_MMA(0, 0, At, B0); PG8_MMA(0, 1, At, B1); PG8_BAR; PG8_SCHED;
;             PG8_LDA(At, 1, 1); PG8_STAGE(PG8_SB(1, 0), b3, voffB); PG8_STAGE(PG8_SB(1, 1), b3 + hstepB, voffB); PG8_STAGE(PG8_SA(1, 0), a3, voffA);
;             PG8_WAIT_V(8); PG8_WAIT_L(0); PG8_BAR; PG8_MMA(1, 0, At, B0); PG8_MMA(1, 1, At, B1); PG8_BAR; PG8_SCHED;
;     ...
;         if constexpr (ALIGN_EPI) { if (wr == 0) PG8_BAR; }
	v_mfma_f32_16x16x32_bf16 v[126:129], v[130:133], v[170:173], v[126:129]
	v_mfma_f32_16x16x32_bf16 v[122:125], v[146:149], v[170:173], v[122:125]
	v_mfma_f32_16x16x32_bf16 v[106:109], v[146:149], v[178:181], v[106:109]
	v_mfma_f32_16x16x32_bf16 v[110:113], v[130:133], v[178:181], v[110:113]
	v_mfma_f32_16x16x32_bf16 v[94:97], v[130:133], v[186:189], v[94:97]
	v_mfma_f32_16x16x32_bf16 v[90:93], v[146:149], v[186:189], v[90:93]
	v_mfma_f32_16x16x32_bf16 v[74:77], v[146:149], v[200:203], v[74:77]
	v_mfma_f32_16x16x32_bf16 v[78:81], v[130:133], v[200:203], v[78:81]
	v_mfma_f32_16x16x32_bf16 v[126:129], v[142:145], v[174:177], v[126:129]
	v_mfma_f32_16x16x32_bf16 v[122:125], v[150:153], v[174:177], v[122:125]
	v_mfma_f32_16x16x32_bf16 v[106:109], v[150:153], v[182:185], v[106:109]
	v_mfma_f32_16x16x32_bf16 v[110:113], v[142:145], v[182:185], v[110:113]
	v_mfma_f32_16x16x32_bf16 v[94:97], v[142:145], v[190:193], v[94:97]
	v_mfma_f32_16x16x32_bf16 v[90:93], v[150:153], v[190:193], v[90:93]
	v_mfma_f32_16x16x32_bf16 v[74:77], v[150:153], v[206:209], v[74:77]
	v_mfma_f32_16x16x32_bf16 v[78:81], v[142:145], v[206:209], v[78:81]
	v_mfma_f32_16x16x32_bf16 v[118:121], v[154:157], v[170:173], v[118:121]
	v_mfma_f32_16x16x32_bf16 v[114:117], v[162:165], v[170:173], v[114:117]
	v_mfma_f32_16x16x32_bf16 v[98:101], v[162:165], v[178:181], v[98:101]
	v_mfma_f32_16x16x32_bf16 v[102:105], v[154:157], v[178:181], v[102:105]
	v_mfma_f32_16x16x32_bf16 v[86:89], v[154:157], v[186:189], v[86:89]
	v_mfma_f32_16x16x32_bf16 v[82:85], v[162:165], v[186:189], v[82:85]
	v_mfma_f32_16x16x32_bf16 v[66:69], v[162:165], v[200:203], v[66:69]
	v_mfma_f32_16x16x32_bf16 v[70:73], v[154:157], v[200:203], v[70:73]
	v_mfma_f32_16x16x32_bf16 v[118:121], v[158:161], v[174:177], v[118:121]
	v_mfma_f32_16x16x32_bf16 v[114:117], v[166:169], v[174:177], v[114:117]
	v_mfma_f32_16x16x32_bf16 v[98:101], v[166:169], v[182:185], v[98:101]
	v_mfma_f32_16x16x32_bf16 v[102:105], v[158:161], v[182:185], v[102:105]
	v_mfma_f32_16x16x32_bf16 v[86:89], v[158:161], v[190:193], v[86:89]
	v_mfma_f32_16x16x32_bf16 v[82:85], v[166:169], v[190:193], v[82:85]
	v_mfma_f32_16x16x32_bf16 v[66:69], v[166:169], v[206:209], v[66:69]
	v_mfma_f32_16x16x32_bf16 v[70:73], v[158:161], v[206:209], v[70:73]
	s_barrier
	s_setprio 0
	s_mov_b32 m0, s53
	s_add_i32 s74, s16, 0x80
	buffer_load_dwordx4 v134, s[40:43], s74 offen lds
	s_mov_b32 m0, s60
	s_add_i32 s16, s16, 0x80080
	buffer_load_dwordx4 v136, s[40:43], s74 offen lds
	ds_read_b128 v[170:173], v140 offset:49152
	ds_read_b128 v[174:177], v140 offset:50176
	ds_read_b128 v[178:181], v140 offset:51200
	ds_read_b128 v[182:185], v140 offset:52224
	ds_read_b128 v[186:189], v140 offset:53248
	ds_read_b128 v[190:193], v140 offset:54272
	ds_read_b128 v[200:203], v140 offset:55296
	ds_read_b128 v[206:209], v140 offset:56320
	s_mov_b32 m0, s63
	s_addk_i32 s17, 0x80
	buffer_load_dwordx4 v134, s[40:43], s16 offen lds
	s_mov_b32 m0, s66
	s_nop 0
	buffer_load_dwordx4 v136, s[40:43], s16 offen lds
	s_mov_b32 m0, s61
	s_nop 0
	buffer_load_dwordx4 v0, s[4:7], s17 offen lds
	s_waitcnt vmcnt(7)
	s_waitcnt lgkmcnt(0)
	s_setprio 1
	s_barrier
	v_mfma_f32_16x16x32_bf16 v[62:65], v[130:133], v[170:173], v[62:65]
	v_mfma_f32_16x16x32_bf16 v[58:61], v[146:149], v[170:173], v[58:61]
	v_mfma_f32_16x16x32_bf16 v[42:45], v[146:149], v[178:181], v[42:45]
	v_mfma_f32_16x16x32_bf16 v[46:49], v[130:133], v[178:181], v[46:49]
	v_mfma_f32_16x16x32_bf16 v[30:33], v[130:133], v[186:189], v[30:33]
	v_mfma_f32_16x16x32_bf16 v[26:29], v[146:149], v[186:189], v[26:29]
	v_mfma_f32_16x16x32_bf16 v[10:13], v[146:149], v[200:203], v[10:13]
	v_mfma_f32_16x16x32_bf16 v[14:17], v[130:133], v[200:203], v[14:17]
	v_mfma_f32_16x16x32_bf16 v[62:65], v[142:145], v[174:177], v[62:65]
	v_mfma_f32_16x16x32_bf16 v[58:61], v[150:153], v[174:177], v[58:61]
	v_mfma_f32_16x16x32_bf16 v[42:45], v[150:153], v[182:185], v[42:45]
	v_mfma_f32_16x16x32_bf16 v[46:49], v[142:145], v[182:185], v[46:49]
	v_mfma_f32_16x16x32_bf16 v[30:33], v[142:145], v[190:193], v[30:33]
	v_mfma_f32_16x16x32_bf16 v[26:29], v[150:153], v[190:193], v[26:29]
	v_mfma_f32_16x16x32_bf16 v[10:13], v[150:153], v[206:209], v[10:13]
	v_mfma_f32_16x16x32_bf16 v[14:17], v[142:145], v[206:209], v[14:17]
	v_mfma_f32_16x16x32_bf16 v[54:57], v[154:157], v[170:173], v[54:57]
	v_mfma_f32_16x16x32_bf16 v[50:53], v[162:165], v[170:173], v[50:53]
	v_mfma_f32_16x16x32_bf16 v[34:37], v[162:165], v[178:181], v[34:37]
	v_mfma_f32_16x16x32_bf16 v[38:41], v[154:157], v[178:181], v[38:41]
	v_mfma_f32_16x16x32_bf16 v[22:25], v[154:157], v[186:189], v[22:25]
	v_mfma_f32_16x16x32_bf16 v[18:21], v[162:165], v[186:189], v[18:21]
	v_mfma_f32_16x16x32_bf16 v[2:5], v[162:165], v[200:203], v[2:5]
	v_mfma_f32_16x16x32_bf16 v[6:9], v[154:157], v[200:203], v[6:9]
	v_mfma_f32_16x16x32_bf16 v[54:57], v[158:161], v[174:177], v[54:57]
	v_mfma_f32_16x16x32_bf16 v[50:53], v[166:169], v[174:177], v[50:53]
	v_mfma_f32_16x16x32_bf16 v[34:37], v[166:169], v[182:185], v[34:37]
	v_mfma_f32_16x16x32_bf16 v[38:41], v[158:161], v[182:185], v[38:41]
	v_mfma_f32_16x16x32_bf16 v[22:25], v[158:161], v[190:193], v[22:25]
	v_mfma_f32_16x16x32_bf16 v[18:21], v[166:169], v[190:193], v[18:21]
	v_mfma_f32_16x16x32_bf16 v[2:5], v[166:169], v[206:209], v[2:5]
	v_mfma_f32_16x16x32_bf16 v[6:9], v[158:161], v[206:209], v[6:9]
	s_barrier
	s_setprio 0
	s_add_i32 s73, s73, 2
	s_add_u32 s19, s19, 0x100
	s_addc_u32 s21, s21, 0
	s_cmp_gt_u32 s73, 29
	s_mov_b64 s[16:17], s[38:39]
	s_cbranch_scc0 .LBB0_1514
	s_and_b64 vcc, exec, s[12:13]
	s_cbranch_vccz .LBB0_1517
	s_barrier

; #define PG8_STAGE(bufoff, gbase, voff) do { const int so_ = (int)(unsigned)((const char*)(gbase) - base_##voff); _Pragma("unroll") for (int _i = 0; _i < 2; ++_i) \
;         __builtin_amdgcn_raw_ptr_buffer_load_lds(rs_##voff, (PG8_LAS unsigned*)(lds + (bufoff) + ldsw + _i * 8192), 16, (int)(voff)[_i], so_, 0, 0); } while (0)
; #define PG8_LDA(dst, b, h) do { _Pragma("unroll") for (int m = 0; m < 4; ++m) _Pragma("unroll") for (int k = 0; k < 2; ++k) dst[m][k] = *(const PG8_LAS bf16x8*)(lds + PG8_SA(b, h) + aoff + m * 2048 + k * 1024); } while (0)
; #define PG8_LDB(dst, b, h) do { _Pragma("unroll") for (int n = 0; n < 2; ++n) _Pragma("unroll") for (int k = 0; k < 2; ++k) dst[n][k] = *(const PG8_LAS bf16x8*)(lds + PG8_SB(b, h) + boff + n * 2048 + k * 1024); } while (0)
; #define PG8_MMA(ai, bj, At, Bt) do { __builtin_amdgcn_s_setprio(1); _Pragma("unroll") for (int m = 0; m < 4; ++m) _Pragma("unroll") for (int n = 0; n < 2; ++n) _Pragma("unroll") for (int k = 0; k < 2; ++k) \
;         acc[ai][bj][m][n] = __builtin_amdgcn_mfma_f32_16x16x32_bf16(Bt[n][k], At[m][k], acc[ai][bj][m][n], 0, 0, 0); __builtin_amdgcn_s_setprio(0); } while (0)
; #define PG8_WAIT_V(n) asm volatile("s_waitcnt vmcnt(" #n ")" ::: "memory")
; #define PG8_WAIT_L(n) asm volatile("s_waitcnt lgkmcnt(" #n ")" ::: "memory")
; #define PG8_BAR __builtin_amdgcn_s_barrier()
; #define PG8_SCHED __builtin_amdgcn_sched_barrier(0)
; template <class Epi, class Sched, bool ALIGN_EPI = false, bool SP2 = false>
; __device__ __forceinline__ void gemm_phase(PG8_LAS unsigned char* lds, const Gemm g, const Sched& S, const Epi& E, int tid_in) {
;     ...
;             PG8_LDB(B0, 0, 0); PG8_LDB(B1, 0, 1); PG8_SCHED; PG8_LDA(At, 0, 0); PG8_STAGE(PG8_SA(1, 1), a1 + hstepA, voffA);
;             PG8_WAIT_V(8); PG8_WAIT_L(0); PG8_BAR; PG8_MMA(0, 0, At, B0); PG8_MMA(0, 1, At, B1); PG8_BAR; PG8_SCHED;
;             PG8_LDA(At, 0, 1); PG8_STAGE(PG8_SB(0, 0), b2, voffB); PG8_STAGE(PG8_SB(0, 1), b2 + hstepB, voffB); PG8_STAGE(PG8_SA(0, 0), a2, voffA);
;             PG8_WAIT_V(8); PG8_WAIT_L(0); PG8_BAR; PG8_MMA(1, 0, At, B0); PG8_MMA(1, 1, At, B1); PG8_BAR; PG8_SCHED;
.LBB0_1584:
	v_add_u32_e32 v133, 0x10000, v131
	ds_read_b128 v[134:137], v133
	ds_read_b128 v[138:141], v133 offset:1024
	ds_read_b128 v[142:145], v133 offset:2048
	ds_read_b128 v[146:149], v133 offset:3072
	v_add_u32_e32 v133, 0x14000, v131
	ds_read_b128 v[150:153], v133
	ds_read_b128 v[154:157], v133 offset:1024
	ds_read_b128 v[158:161], v133 offset:2048
	ds_read_b128 v[166:169], v133 offset:3072
	s_add_i32 s43, s38, s22
	s_add_i32 s42, s14, s22
	s_add_i32 s76, s12, s22
	s_addk_i32 s43, 0xff80
	s_sub_i32 s78, s43, 0x160000
	s_cmpk_eq_i32 s39, 0x54
	s_cselect_b32 s77, s16, s42
	s_mov_b32 m0, s68
	ds_read_b128 v[170:173], v132
	ds_read_b128 v[174:177], v132 offset:1024
	ds_read_b128 v[178:181], v132 offset:2048
	ds_read_b128 v[182:185], v132 offset:3072
	ds_read_b128 v[186:189], v132 offset:4096
	ds_read_b128 v[190:193], v132 offset:5120
	ds_read_b128 v[200:203], v132 offset:6144
	ds_read_b128 v[206:209], v132 offset:7168
	s_mov_b32 m0, s63
	s_nop 0
	buffer_load_dwordx4 v130, s[4:7], s78 offen lds
	s_mov_b32 m0, s68
	s_nop 0
	buffer_load_dwordx4 v0, s[4:7], s43 offen lds
	s_mov_b32 m0, s69
	s_nop 0
	buffer_load_dwordx4 v130, s[4:7], s43 offen lds
	s_waitcnt vmcnt(8)
	s_waitcnt lgkmcnt(0)
	s_setprio 1
	s_barrier
	v_mfma_f32_16x16x32_bf16 v[22:25], v[134:137], v[170:173], v[22:25]
	v_mfma_f32_16x16x32_bf16 v[14:17], v[142:145], v[170:173], v[14:17]
	v_mfma_f32_16x16x32_bf16 v[54:57], v[142:145], v[178:181], v[54:57]
	v_mfma_f32_16x16x32_bf16 v[74:77], v[134:137], v[178:181], v[74:77]
	v_mfma_f32_16x16x32_bf16 v[106:109], v[134:137], v[186:189], v[106:109]
	v_mfma_f32_16x16x32_bf16 v[102:105], v[142:145], v[186:189], v[102:105]
	v_mfma_f32_16x16x32_bf16 v[118:121], v[142:145], v[200:203], v[118:121]
	v_mfma_f32_16x16x32_bf16 v[122:125], v[134:137], v[200:203], v[122:125]
	v_mfma_f32_16x16x32_bf16 v[22:25], v[138:141], v[174:177], v[22:25]
	v_mfma_f32_16x16x32_bf16 v[14:17], v[146:149], v[174:177], v[14:17]
	v_mfma_f32_16x16x32_bf16 v[54:57], v[146:149], v[182:185], v[54:57]
	v_mfma_f32_16x16x32_bf16 v[74:77], v[138:141], v[182:185], v[74:77]
	v_mfma_f32_16x16x32_bf16 v[106:109], v[138:141], v[190:193], v[106:109]
	v_mfma_f32_16x16x32_bf16 v[102:105], v[146:149], v[190:193], v[102:105]
	v_mfma_f32_16x16x32_bf16 v[118:121], v[146:149], v[206:209], v[118:121]
	v_mfma_f32_16x16x32_bf16 v[122:125], v[138:141], v[206:209], v[122:125]
	v_mfma_f32_16x16x32_bf16 v[6:9], v[150:153], v[170:173], v[6:9]
	v_mfma_f32_16x16x32_bf16 v[18:21], v[158:161], v[170:173], v[18:21]
	v_mfma_f32_16x16x32_bf16 v[78:81], v[158:161], v[178:181], v[78:81]
	v_mfma_f32_16x16x32_bf16 v[50:53], v[150:153], v[178:181], v[50:53]
	v_mfma_f32_16x16x32_bf16 v[98:101], v[150:153], v[186:189], v[98:101]
	v_mfma_f32_16x16x32_bf16 v[110:113], v[158:161], v[186:189], v[110:113]
	v_mfma_f32_16x16x32_bf16 v[126:129], v[158:161], v[200:203], v[126:129]
	v_mfma_f32_16x16x32_bf16 v[114:117], v[150:153], v[200:203], v[114:117]
	v_mfma_f32_16x16x32_bf16 v[6:9], v[154:157], v[174:177], v[6:9]
	v_mfma_f32_16x16x32_bf16 v[18:21], v[166:169], v[174:177], v[18:21]
	v_mfma_f32_16x16x32_bf16 v[78:81], v[166:169], v[182:185], v[78:81]
	v_mfma_f32_16x16x32_bf16 v[50:53], v[154:157], v[182:185], v[50:53]
	v_mfma_f32_16x16x32_bf16 v[98:101], v[154:157], v[190:193], v[98:101]
	v_mfma_f32_16x16x32_bf16 v[110:113], v[166:169], v[190:193], v[110:113]
	v_mfma_f32_16x16x32_bf16 v[126:129], v[166:169], v[206:209], v[126:129]
	v_mfma_f32_16x16x32_bf16 v[114:117], v[154:157], v[206:209], v[114:117]
	s_barrier
	s_setprio 0
	s_cselect_b32 s76, s20, s76
	s_mov_b32 m0, s26
	s_mov_b32 s42, s6
	s_mov_b32 s43, s7
	s_sub_i32 s76, s76, s40
	buffer_load_dwordx4 v0, s[40:43], s76 offen lds
	s_mov_b32 m0, s44
	s_add_i32 s78, s76, 0x160000
	buffer_load_dwordx4 v130, s[40:43], s76 offen lds
	ds_read_b128 v[170:173], v132 offset:16384
	ds_read_b128 v[174:177], v132 offset:17408
	ds_read_b128 v[178:181], v132 offset:18432
	ds_read_b128 v[182:185], v132 offset:19456
	ds_read_b128 v[186:189], v132 offset:20480
	ds_read_b128 v[190:193], v132 offset:21504
	ds_read_b128 v[200:203], v132 offset:22528
	ds_read_b128 v[206:209], v132 offset:23552
	s_mov_b32 m0, s45
	s_sub_i32 s77, s77, s4
	buffer_load_dwordx4 v0, s[40:43], s78 offen lds
	s_mov_b32 m0, s46
	s_nop 0
	buffer_load_dwordx4 v130, s[40:43], s78 offen lds
	s_mov_b32 m0, s19
	s_nop 0
	buffer_load_dwordx4 v0, s[4:7], s77 offen lds
	s_waitcnt vmcnt(7)
	s_waitcnt lgkmcnt(0)
	s_setprio 1
	s_barrier
	v_mfma_f32_16x16x32_bf16 v[62:65], v[134:137], v[170:173], v[62:65]
	v_mfma_f32_16x16x32_bf16 v[46:49], v[142:145], v[170:173], v[46:49]
	v_mfma_f32_16x16x32_bf16 v[70:73], v[142:145], v[178:181], v[70:73]
	v_mfma_f32_16x16x32_bf16 v[82:85], v[134:137], v[178:181], v[82:85]
	v_mfma_f32_16x16x32_bf16 v[94:97], v[134:137], v[186:189], v[94:97]
	v_mfma_f32_16x16x32_bf16 v[90:93], v[142:145], v[186:189], v[90:93]
	v_mfma_f32_16x16x32_bf16 v[26:29], v[142:145], v[200:203], v[26:29]
	v_mfma_f32_16x16x32_bf16 v[38:41], v[134:137], v[200:203], v[38:41]
	v_mfma_f32_16x16x32_bf16 v[62:65], v[138:141], v[174:177], v[62:65]
	v_mfma_f32_16x16x32_bf16 v[46:49], v[146:149], v[174:177], v[46:49]
	v_mfma_f32_16x16x32_bf16 v[70:73], v[146:149], v[182:185], v[70:73]
	v_mfma_f32_16x16x32_bf16 v[82:85], v[138:141], v[182:185], v[82:85]
	v_mfma_f32_16x16x32_bf16 v[94:97], v[138:141], v[190:193], v[94:97]
	v_mfma_f32_16x16x32_bf16 v[90:93], v[146:149], v[190:193], v[90:93]
	v_mfma_f32_16x16x32_bf16 v[26:29], v[146:149], v[206:209], v[26:29]
	v_mfma_f32_16x16x32_bf16 v[38:41], v[138:141], v[206:209], v[38:41]
	v_mfma_f32_16x16x32_bf16 v[42:45], v[150:153], v[170:173], v[42:45]
	v_mfma_f32_16x16x32_bf16 v[30:33], v[158:161], v[170:173], v[30:33]
	v_mfma_f32_16x16x32_bf16 v[86:89], v[158:161], v[178:181], v[86:89]
	v_mfma_f32_16x16x32_bf16 v[66:69], v[150:153], v[178:181], v[66:69]
	v_mfma_f32_16x16x32_bf16 v[58:61], v[150:153], v[186:189], v[58:61]
	v_mfma_f32_16x16x32_bf16 v[34:37], v[158:161], v[186:189], v[34:37]
	v_mfma_f32_16x16x32_bf16 v[2:5], v[158:161], v[200:203], v[2:5]
	v_mfma_f32_16x16x32_bf16 v[10:13], v[150:153], v[200:203], v[10:13]
	v_mfma_f32_16x16x32_bf16 v[42:45], v[154:157], v[174:177], v[42:45]
	v_mfma_f32_16x16x32_bf16 v[30:33], v[166:169], v[174:177], v[30:33]
	v_mfma_f32_16x16x32_bf16 v[86:89], v[166:169], v[182:185], v[86:89]
	v_mfma_f32_16x16x32_bf16 v[66:69], v[154:157], v[182:185], v[66:69]
	v_mfma_f32_16x16x32_bf16 v[58:61], v[154:157], v[190:193], v[58:61]
	v_mfma_f32_16x16x32_bf16 v[34:37], v[166:169], v[190:193], v[34:37]
	v_mfma_f32_16x16x32_bf16 v[2:5], v[166:169], v[206:209], v[2:5]
	v_mfma_f32_16x16x32_bf16 v[10:13], v[154:157], v[206:209], v[10:13]
	s_barrier
; #define PG8_STAGE(bufoff, gbase, voff) do { const int so_ = (int)(unsigned)((const char*)(gbase) - base_##voff); _Pragma("unroll") for (int _i = 0; _i < 2; ++_i) \
;         __builtin_amdgcn_raw_ptr_buffer_load_lds(rs_##voff, (PG8_LAS unsigned*)(lds + (bufoff) + ldsw + _i * 8192), 16, (int)(voff)[_i], so_, 0, 0); } while (0)
; #define PG8_LDA(dst, b, h) do { _Pragma("unroll") for (int m = 0; m < 4; ++m) _Pragma("unroll") for (int k = 0; k < 2; ++k) dst[m][k] = *(const PG8_LAS bf16x8*)(lds + PG8_SA(b, h) + aoff + m * 2048 + k * 1024); } while (0)
; #define PG8_LDB(dst, b, h) do { _Pragma("unroll") for (int n = 0; n < 2; ++n) _Pragma("unroll") for (int k = 0; k < 2; ++k) dst[n][k] = *(const PG8_LAS bf16x8*)(lds + PG8_SB(b, h) + boff + n * 2048 + k * 1024); } while (0)
; #define PG8_MMA(ai, bj, At, Bt) do { __builtin_amdgcn_s_setprio(1); _Pragma("unroll") for (int m = 0; m < 4; ++m) _Pragma("unroll") for (int n = 0; n < 2; ++n) _Pragma("unroll") for (int k = 0; k < 2; ++k) \
;         acc[ai][bj][m][n] = __builtin_amdgcn_mfma_f32_16x16x32_bf16(Bt[n][k], At[m][k], acc[ai][bj][m][n], 0, 0, 0); __builtin_amdgcn_s_setprio(0); } while (0)
; #define PG8_WAIT_V(n) asm volatile("s_waitcnt vmcnt(" #n ")" ::: "memory")
; #define PG8_WAIT_L(n) asm volatile("s_waitcnt lgkmcnt(" #n ")" ::: "memory")
; #define PG8_BAR __builtin_amdgcn_s_barrier()
; #define PG8_SCHED __builtin_amdgcn_sched_barrier(0)
; template <class Epi, class Sched, bool ALIGN_EPI = false, bool SP2 = false>
; __device__ __forceinline__ void gemm_phase(PG8_LAS unsigned char* lds, const Gemm g, const Sched& S, const Epi& E, int tid_in) {
;     ...
;             PG8_LDB(B0, 1, 0); PG8_LDB(B1, 1, 1); PG8_SCHED; PG8_LDA(At, 1, 0); PG8_STAGE(PG8_SA(0, 1), a2 + hstepA, voffA);
;             PG8_WAIT_V(8); PG8_WAIT_L(0); PG8_BAR; PG8_MMA(0, 0, At, B0); PG8_MMA(0, 1, At, B1); PG8_BAR; PG8_SCHED;
;             PG8_LDA(At, 1, 1); PG8_STAGE(PG8_SB(1, 0), b3, voffB); PG8_STAGE(PG8_SB(1, 1), b3 + hstepB, voffB); PG8_STAGE(PG8_SA(1, 0), a3, voffA);
;             PG8_WAIT_V(8); PG8_WAIT_L(0); PG8_BAR; PG8_MMA(1, 0, At, B0); PG8_MMA(1, 1, At, B1); PG8_BAR; PG8_SCHED;
	s_setprio 0
	v_add_u32_e32 v133, 0x18000, v131
	ds_read_b128 v[134:137], v133
	ds_read_b128 v[138:141], v133 offset:1024
	ds_read_b128 v[142:145], v133 offset:2048
	ds_read_b128 v[146:149], v133 offset:3072
	v_add_u32_e32 v133, 0x1c000, v131
	ds_read_b128 v[150:153], v133
	ds_read_b128 v[154:157], v133 offset:1024
	ds_read_b128 v[158:161], v133 offset:2048
	ds_read_b128 v[166:169], v133 offset:3072
	s_add_i32 s78, s77, 0x160000
	s_mov_b32 m0, s48
	ds_read_b128 v[170:173], v132 offset:32768
	ds_read_b128 v[174:177], v132 offset:33792
	ds_read_b128 v[178:181], v132 offset:34816
	ds_read_b128 v[182:185], v132 offset:35840
	ds_read_b128 v[186:189], v132 offset:36864
	ds_read_b128 v[190:193], v132 offset:37888
	ds_read_b128 v[200:203], v132 offset:38912
	ds_read_b128 v[206:209], v132 offset:39936
	s_mov_b32 m0, s47
	s_nop 0
	buffer_load_dwordx4 v130, s[4:7], s77 offen lds
	s_mov_b32 m0, s48
	s_nop 0
	buffer_load_dwordx4 v0, s[4:7], s78 offen lds
	s_mov_b32 m0, s49
	s_nop 0
	buffer_load_dwordx4 v130, s[4:7], s78 offen lds
	s_waitcnt vmcnt(8)
	s_waitcnt lgkmcnt(0)
	s_setprio 1
	s_barrier
	v_mfma_f32_16x16x32_bf16 v[22:25], v[134:137], v[170:173], v[22:25]
	v_mfma_f32_16x16x32_bf16 v[14:17], v[142:145], v[170:173], v[14:17]
	v_mfma_f32_16x16x32_bf16 v[54:57], v[142:145], v[178:181], v[54:57]
	v_mfma_f32_16x16x32_bf16 v[74:77], v[134:137], v[178:181], v[74:77]
	v_mfma_f32_16x16x32_bf16 v[106:109], v[134:137], v[186:189], v[106:109]
	v_mfma_f32_16x16x32_bf16 v[102:105], v[142:145], v[186:189], v[102:105]
	v_mfma_f32_16x16x32_bf16 v[118:121], v[142:145], v[200:203], v[118:121]
	v_mfma_f32_16x16x32_bf16 v[122:125], v[134:137], v[200:203], v[122:125]
	v_mfma_f32_16x16x32_bf16 v[22:25], v[138:141], v[174:177], v[22:25]
	v_mfma_f32_16x16x32_bf16 v[14:17], v[146:149], v[174:177], v[14:17]
	v_mfma_f32_16x16x32_bf16 v[54:57], v[146:149], v[182:185], v[54:57]
	v_mfma_f32_16x16x32_bf16 v[74:77], v[138:141], v[182:185], v[74:77]
	v_mfma_f32_16x16x32_bf16 v[106:109], v[138:141], v[190:193], v[106:109]
	v_mfma_f32_16x16x32_bf16 v[102:105], v[146:149], v[190:193], v[102:105]
	v_mfma_f32_16x16x32_bf16 v[118:121], v[146:149], v[206:209], v[118:121]
	v_mfma_f32_16x16x32_bf16 v[122:125], v[138:141], v[206:209], v[122:125]
	v_mfma_f32_16x16x32_bf16 v[6:9], v[150:153], v[170:173], v[6:9]
	v_mfma_f32_16x16x32_bf16 v[18:21], v[158:161], v[170:173], v[18:21]
	v_mfma_f32_16x16x32_bf16 v[78:81], v[158:161], v[178:181], v[78:81]
	v_mfma_f32_16x16x32_bf16 v[50:53], v[150:153], v[178:181], v[50:53]
	v_mfma_f32_16x16x32_bf16 v[98:101], v[150:153], v[186:189], v[98:101]
	v_mfma_f32_16x16x32_bf16 v[110:113], v[158:161], v[186:189], v[110:113]
	v_mfma_f32_16x16x32_bf16 v[126:129], v[158:161], v[200:203], v[126:129]
	v_mfma_f32_16x16x32_bf16 v[114:117], v[150:153], v[200:203], v[114:117]
	v_mfma_f32_16x16x32_bf16 v[6:9], v[154:157], v[174:177], v[6:9]
	v_mfma_f32_16x16x32_bf16 v[18:21], v[166:169], v[174:177], v[18:21]
	v_mfma_f32_16x16x32_bf16 v[78:81], v[166:169], v[182:185], v[78:81]
	v_mfma_f32_16x16x32_bf16 v[50:53], v[154:157], v[182:185], v[50:53]
	v_mfma_f32_16x16x32_bf16 v[98:101], v[154:157], v[190:193], v[98:101]
	v_mfma_f32_16x16x32_bf16 v[110:113], v[166:169], v[190:193], v[110:113]
	v_mfma_f32_16x16x32_bf16 v[126:129], v[166:169], v[206:209], v[126:129]
	v_mfma_f32_16x16x32_bf16 v[114:117], v[154:157], v[206:209], v[114:117]
	s_barrier
	s_setprio 0
	s_mov_b32 m0, s60
	s_add_i32 s78, s76, 0x80
	buffer_load_dwordx4 v0, s[40:43], s78 offen lds
	s_mov_b32 m0, s61
	s_add_i32 s76, s76, 0x160080
	buffer_load_dwordx4 v130, s[40:43], s78 offen lds
	ds_read_b128 v[170:173], v132 offset:49152
	ds_read_b128 v[174:177], v132 offset:50176
	ds_read_b128 v[178:181], v132 offset:51200
	ds_read_b128 v[182:185], v132 offset:52224
	ds_read_b128 v[186:189], v132 offset:53248
	ds_read_b128 v[190:193], v132 offset:54272
	ds_read_b128 v[200:203], v132 offset:55296
	ds_read_b128 v[206:209], v132 offset:56320
	s_mov_b32 m0, s66
	s_addk_i32 s77, 0x80
	buffer_load_dwordx4 v0, s[40:43], s76 offen lds
	s_mov_b32 m0, s67
	s_nop 0
	buffer_load_dwordx4 v130, s[40:43], s76 offen lds
	s_mov_b32 m0, s62
	s_nop 0
	buffer_load_dwordx4 v0, s[4:7], s77 offen lds
	s_waitcnt vmcnt(7)
	s_waitcnt lgkmcnt(0)
	s_setprio 1
	s_barrier
;     static __device__ __forceinline__ bool last_of_chain(const Unit& u) { return (u.pn >> 3) == 2; }
; #define PG8_STAGE(bufoff, gbase, voff) do { const int so_ = (int)(unsigned)((const char*)(gbase) - base_##voff); _Pragma("unroll") for (int _i = 0; _i < 2; ++_i) \
;         __builtin_amdgcn_raw_ptr_buffer_load_lds(rs_##voff, (PG8_LAS unsigned*)(lds + (bufoff) + ldsw + _i * 8192), 16, (int)(voff)[_i], so_, 0, 0); } while (0)
; #define PG8_LDA(dst, b, h) do { _Pragma("unroll") for (int m = 0; m < 4; ++m) _Pragma("unroll") for (int k = 0; k < 2; ++k) dst[m][k] = *(const PG8_LAS bf16x8*)(lds + PG8_SA(b, h) + aoff + m * 2048 + k * 1024); } while (0)
; #define PG8_MMA(ai, bj, At, Bt) do { __builtin_amdgcn_s_setprio(1); _Pragma("unroll") for (int m = 0; m < 4; ++m) _Pragma("unroll") for (int n = 0; n < 2; ++n) _Pragma("unroll") for (int k = 0; k < 2; ++k) \
;         acc[ai][bj][m][n] = __builtin_amdgcn_mfma_f32_16x16x32_bf16(Bt[n][k], At[m][k], acc[ai][bj][m][n], 0, 0, 0); __builtin_amdgcn_s_setprio(0); } while (0)
; #define PG8_WAIT_V(n) asm volatile("s_waitcnt vmcnt(" #n ")" ::: "memory")
; #define PG8_WAIT_L(n) asm volatile("s_waitcnt lgkmcnt(" #n ")" ::: "memory")
; #define PG8_BAR __builtin_amdgcn_s_barrier()
; #define PG8_SCHED __builtin_amdgcn_sched_barrier(0)
; template <class Epi, class Sched, bool ALIGN_EPI = false, bool SP2 = false>
; __device__ __forceinline__ void gemm_phase(PG8_LAS unsigned char* lds, const Gemm g, const Sched& S, const Epi& E, int tid_in) {
;     ...
;             PG8_WAIT_V(8); PG8_WAIT_L(0); PG8_BAR; PG8_MMA(0, 0, At, B0); PG8_MMA(0, 1, At, B1); PG8_BAR; PG8_SCHED;
;             PG8_LDA(At, 1, 1); PG8_STAGE(PG8_SB(1, 0), b3, voffB); PG8_STAGE(PG8_SB(1, 1), b3 + hstepB, voffB); PG8_STAGE(PG8_SA(1, 0), a3, voffA);
;             PG8_WAIT_V(8); PG8_WAIT_L(0); PG8_BAR; PG8_MMA(1, 0, At, B0); PG8_MMA(1, 1, At, B1); PG8_BAR; PG8_SCHED;
;     ...
;         bool zero_acc = true; if constexpr (Epi::CHAIN) zero_acc = Epi::last_of_chain(cur);
;         if (zero_acc) {
; #pragma unroll
;         for (int a = 0; a < 2; ++a)
; #pragma unroll
;             for (int b = 0; b < 2; ++b)
; #pragma unroll
;                 for (int m = 0; m < 4; ++m)
; #pragma unroll
;                     for (int n = 0; n < 2; ++n) acc[a][b][m][n] = (f32x4){0.f, 0.f, 0.f, 0.f};
;         }
;         cur = nxt; cA = nA; cB = nB; ++ui;
	v_mfma_f32_16x16x32_bf16 v[62:65], v[134:137], v[170:173], v[62:65]
	v_mfma_f32_16x16x32_bf16 v[46:49], v[142:145], v[170:173], v[46:49]
	v_mfma_f32_16x16x32_bf16 v[70:73], v[142:145], v[178:181], v[70:73]
	v_mfma_f32_16x16x32_bf16 v[82:85], v[134:137], v[178:181], v[82:85]
	v_mfma_f32_16x16x32_bf16 v[94:97], v[134:137], v[186:189], v[94:97]
	v_mfma_f32_16x16x32_bf16 v[90:93], v[142:145], v[186:189], v[90:93]
	v_mfma_f32_16x16x32_bf16 v[26:29], v[142:145], v[200:203], v[26:29]
	v_mfma_f32_16x16x32_bf16 v[38:41], v[134:137], v[200:203], v[38:41]
	v_mfma_f32_16x16x32_bf16 v[62:65], v[138:141], v[174:177], v[62:65]
	v_mfma_f32_16x16x32_bf16 v[46:49], v[146:149], v[174:177], v[46:49]
	v_mfma_f32_16x16x32_bf16 v[70:73], v[146:149], v[182:185], v[70:73]
	v_mfma_f32_16x16x32_bf16 v[82:85], v[138:141], v[182:185], v[82:85]
	v_mfma_f32_16x16x32_bf16 v[94:97], v[138:141], v[190:193], v[94:97]
	v_mfma_f32_16x16x32_bf16 v[90:93], v[146:149], v[190:193], v[90:93]
	v_mfma_f32_16x16x32_bf16 v[26:29], v[146:149], v[206:209], v[26:29]
	v_mfma_f32_16x16x32_bf16 v[38:41], v[138:141], v[206:209], v[38:41]
	v_mfma_f32_16x16x32_bf16 v[42:45], v[150:153], v[170:173], v[42:45]
	v_mfma_f32_16x16x32_bf16 v[30:33], v[158:161], v[170:173], v[30:33]
	v_mfma_f32_16x16x32_bf16 v[86:89], v[158:161], v[178:181], v[86:89]
	v_mfma_f32_16x16x32_bf16 v[66:69], v[150:153], v[178:181], v[66:69]
	v_mfma_f32_16x16x32_bf16 v[58:61], v[150:153], v[186:189], v[58:61]
	v_mfma_f32_16x16x32_bf16 v[34:37], v[158:161], v[186:189], v[34:37]
	v_mfma_f32_16x16x32_bf16 v[2:5], v[158:161], v[200:203], v[2:5]
	v_mfma_f32_16x16x32_bf16 v[10:13], v[150:153], v[200:203], v[10:13]
	v_mfma_f32_16x16x32_bf16 v[42:45], v[154:157], v[174:177], v[42:45]
	v_mfma_f32_16x16x32_bf16 v[30:33], v[166:169], v[174:177], v[30:33]
	v_mfma_f32_16x16x32_bf16 v[86:89], v[166:169], v[182:185], v[86:89]
	v_mfma_f32_16x16x32_bf16 v[66:69], v[154:157], v[182:185], v[66:69]
	v_mfma_f32_16x16x32_bf16 v[58:61], v[154:157], v[190:193], v[58:61]
	v_mfma_f32_16x16x32_bf16 v[34:37], v[166:169], v[190:193], v[34:37]
	v_mfma_f32_16x16x32_bf16 v[2:5], v[166:169], v[206:209], v[2:5]
	v_mfma_f32_16x16x32_bf16 v[10:13], v[154:157], v[206:209], v[10:13]
	s_barrier
	s_setprio 0
	s_add_i32 s39, s39, 2
	s_add_u32 s22, s22, 0x100
	s_addc_u32 s23, s23, 0
	s_cmpk_gt_u32 s39, 0x55
	s_cbranch_scc0 .LBB0_1584
	s_and_b64 vcc, exec, s[36:37]
	s_cbranch_vccnz .LBB0_1572
	v_mov_b32_e32 v2, 0
	s_mov_b32 s10, s73
	s_mov_b32 s25, s74
	s_mov_b64 s[12:13], s[20:21]
	s_mov_b64 s[14:15], s[16:17]
	s_mov_b32 s72, s75
	v_mov_b32_e32 v3, v2
	v_mov_b32_e32 v4, v2
	v_mov_b32_e32 v5, v2
	v_mov_b32_e32 v10, v2
	v_mov_b32_e32 v11, v2
	v_mov_b32_e32 v12, v2
	v_mov_b32_e32 v13, v2
	v_mov_b32_e32 v34, v2
	v_mov_b32_e32 v35, v2
	v_mov_b32_e32 v36, v2
	v_mov_b32_e32 v37, v2
	v_mov_b32_e32 v58, v2
	v_mov_b32_e32 v59, v2
	v_mov_b32_e32 v60, v2
	v_mov_b32_e32 v61, v2
	v_mov_b32_e32 v86, v2
	v_mov_b32_e32 v87, v2
	v_mov_b32_e32 v88, v2
	v_mov_b32_e32 v89, v2
	v_mov_b32_e32 v66, v2
	v_mov_b32_e32 v67, v2
	v_mov_b32_e32 v68, v2
	v_mov_b32_e32 v69, v2
	v_mov_b32_e32 v30, v2
	v_mov_b32_e32 v31, v2
	v_mov_b32_e32 v32, v2
	v_mov_b32_e32 v33, v2
	v_mov_b32_e32 v42, v2
	v_mov_b32_e32 v43, v2
	v_mov_b32_e32 v44, v2
	v_mov_b32_e32 v45, v2
	v_mov_b32_e32 v26, v2
	v_mov_b32_e32 v27, v2
	v_mov_b32_e32 v28, v2
	v_mov_b32_e32 v29, v2
	v_mov_b32_e32 v38, v2
	v_mov_b32_e32 v39, v2
	v_mov_b32_e32 v40, v2
	v_mov_b32_e32 v41, v2
	v_mov_b32_e32 v90, v2
	v_mov_b32_e32 v91, v2
	v_mov_b32_e32 v92, v2
	v_mov_b32_e32 v93, v2
	v_mov_b32_e32 v94, v2
	v_mov_b32_e32 v95, v2
	v_mov_b32_e32 v96, v2
	v_mov_b32_e32 v97, v2
	v_mov_b32_e32 v70, v2
	v_mov_b32_e32 v71, v2
	v_mov_b32_e32 v72, v2
	v_mov_b32_e32 v73, v2
	v_mov_b32_e32 v82, v2
	v_mov_b32_e32 v83, v2
	v_mov_b32_e32 v84, v2
	v_mov_b32_e32 v85, v2
	v_mov_b32_e32 v46, v2
	v_mov_b32_e32 v47, v2
	v_mov_b32_e32 v48, v2
	v_mov_b32_e32 v49, v2
	v_mov_b32_e32 v62, v2
	v_mov_b32_e32 v63, v2
	v_mov_b32_e32 v64, v2
	v_mov_b32_e32 v65, v2
	v_mov_b32_e32 v126, v2
	v_mov_b32_e32 v127, v2
	v_mov_b32_e32 v128, v2
	v_mov_b32_e32 v129, v2
	v_mov_b32_e32 v114, v2
	v_mov_b32_e32 v115, v2
	v_mov_b32_e32 v116, v2
	v_mov_b32_e32 v117, v2
	v_mov_b32_e32 v110, v2
	v_mov_b32_e32 v111, v2
	v_mov_b32_e32 v112, v2
	v_mov_b32_e32 v113, v2
	v_mov_b32_e32 v98, v2
	v_mov_b32_e32 v99, v2
	v_mov_b32_e32 v100, v2
	v_mov_b32_e32 v101, v2
	v_mov_b32_e32 v78, v2
	v_mov_b32_e32 v79, v2
	v_mov_b32_e32 v80, v2
	v_mov_b32_e32 v81, v2
	v_mov_b32_e32 v50, v2
	v_mov_b32_e32 v51, v2
	v_mov_b32_e32 v52, v2
	v_mov_b32_e32 v53, v2
	v_mov_b32_e32 v18, v2
	v_mov_b32_e32 v19, v2
	v_mov_b32_e32 v20, v2
	v_mov_b32_e32 v21, v2
	v_mov_b32_e32 v6, v2
	v_mov_b32_e32 v7, v2
	v_mov_b32_e32 v8, v2
	v_mov_b32_e32 v9, v2
	v_mov_b32_e32 v118, v2
	v_mov_b32_e32 v119, v2
	v_mov_b32_e32 v120, v2
	v_mov_b32_e32 v121, v2
	v_mov_b32_e32 v122, v2
	v_mov_b32_e32 v123, v2
	v_mov_b32_e32 v124, v2
	v_mov_b32_e32 v125, v2
	v_mov_b32_e32 v102, v2
	v_mov_b32_e32 v103, v2
	v_mov_b32_e32 v104, v2
	v_mov_b32_e32 v105, v2
	v_mov_b32_e32 v106, v2
	v_mov_b32_e32 v107, v2
	v_mov_b32_e32 v108, v2
	v_mov_b32_e32 v109, v2
	v_mov_b32_e32 v54, v2
	v_mov_b32_e32 v55, v2
	v_mov_b32_e32 v56, v2
	v_mov_b32_e32 v57, v2
	v_mov_b32_e32 v74, v2
	v_mov_b32_e32 v75, v2
	v_mov_b32_e32 v76, v2
	v_mov_b32_e32 v77, v2
	v_mov_b32_e32 v14, v2
	v_mov_b32_e32 v15, v2
	v_mov_b32_e32 v16, v2
	v_mov_b32_e32 v17, v2
	v_mov_b32_e32 v22, v2
	v_mov_b32_e32 v23, v2
	v_mov_b32_e32 v24, v2
	v_mov_b32_e32 v25, v2
	s_branch .LBB0_1572
